# gMLP phase rewritten by hand: params + masked W tile built once, next-unit prefetch with counted waits, double-buffered VT (1 barrier per unit)
# speedup vs baseline: 1.0148x; 1.0148x over previous
; template <int KB, bool SK>
; __device__ __forceinline__ void qkt(f32x16& p0, f32x16& p1, const char* K_lds, int r32, int hi, const bf16x8* qr, bool act) {
;     if (SK && !act) { const float NEG = -__builtin_inff();
; #pragma unroll
;         for (int r = 0; r < 16; ++r) { p0[r] = NEG; p1[r] = NEG; } return; }
;     p0 = f32x16{}; p1 = f32x16{};
;     const char* kb[4];
; #pragma unroll
;     for (int dd = 0; dd < 4; ++dd) kb[dd] = K_lds + KB * SHM_K + KSWZ(r32, (dd * 16 + hi * 8) * 2);
; #pragma unroll
;     for (int d0 = 0; d0 < 8; ++d0) { const char* a = kb[d0 & 3] + (d0 >> 2) * 128;
;         bf16x8 b0 = *reinterpret_cast<const bf16x8*>(a);
;         bf16x8 b1 = *reinterpret_cast<const bf16x8*>(a + 32 * 256);
;         p0 = __builtin_amdgcn_mfma_f32_32x32x16_bf16(b0, qr[d0], p0, 0, 0, 0);
;         p1 = __builtin_amdgcn_mfma_f32_32x32x16_bf16(b1, qr[d0], p1, 0, 0, 0); }
; }
.LBB0_239:
	s_add_i32 s10, s60, 64
	s_cmp_gt_i32 s10, s55
	s_cselect_b64 s[8:9], -1, 0
	s_add_i32 s11, s60, 0x7f
	s_cmp_lt_i32 s11, s56
	s_cselect_b64 s[38:39], -1, 0
	s_or_b64 s[8:9], s[8:9], s[38:39]
	s_and_b64 vcc, exec, s[8:9]
	s_cbranch_vccnz .LBB0_241
	ds_read_b128 v[2:5], v228 offset:49152
	s_waitcnt vmcnt(3) lgkmcnt(0)
	v_mfma_f32_32x32x16_bf16 v[100:115], v[2:5], v[172:175], 0
	ds_read_b128 v[2:5], v228 offset:57344
	s_waitcnt lgkmcnt(0)
	v_mfma_f32_32x32x16_bf16 v[84:99], v[2:5], v[172:175], 0
	ds_read_b128 v[2:5], v229 offset:49152
	s_waitcnt lgkmcnt(0)
	v_mfma_f32_32x32x16_bf16 v[100:115], v[2:5], v[168:171], v[100:115]
	ds_read_b128 v[2:5], v229 offset:57344
	s_waitcnt lgkmcnt(0)
	v_mfma_f32_32x32x16_bf16 v[84:99], v[2:5], v[168:171], v[84:99]
	ds_read_b128 v[2:5], v230 offset:49152
	s_waitcnt lgkmcnt(0)
	v_mfma_f32_32x32x16_bf16 v[100:115], v[2:5], v[164:167], v[100:115]
	ds_read_b128 v[2:5], v230 offset:57344
	s_waitcnt lgkmcnt(0)
	v_mfma_f32_32x32x16_bf16 v[84:99], v[2:5], v[164:167], v[84:99]
	ds_read_b128 v[2:5], v231 offset:49152
	s_waitcnt lgkmcnt(0)
	v_mfma_f32_32x32x16_bf16 v[100:115], v[2:5], v[160:163], v[100:115]
	ds_read_b128 v[2:5], v231 offset:57344
	s_waitcnt lgkmcnt(0)
	v_mfma_f32_32x32x16_bf16 v[84:99], v[2:5], v[160:163], v[84:99]
	ds_read_b128 v[2:5], v228 offset:49280
	s_waitcnt lgkmcnt(0)
	v_mfma_f32_32x32x16_bf16 v[100:115], v[2:5], v[156:159], v[100:115]
	ds_read_b128 v[2:5], v228 offset:57472
	s_waitcnt lgkmcnt(0)
	v_mfma_f32_32x32x16_bf16 v[84:99], v[2:5], v[156:159], v[84:99]
	ds_read_b128 v[2:5], v229 offset:49280
	s_waitcnt vmcnt(2) lgkmcnt(0)
	v_mfma_f32_32x32x16_bf16 v[100:115], v[2:5], v[152:155], v[100:115]
	ds_read_b128 v[2:5], v229 offset:57472
	s_waitcnt lgkmcnt(0)
	v_mfma_f32_32x32x16_bf16 v[84:99], v[2:5], v[152:155], v[84:99]
	ds_read_b128 v[2:5], v230 offset:49280
	s_waitcnt vmcnt(1) lgkmcnt(0)
	v_mfma_f32_32x32x16_bf16 v[100:115], v[2:5], v[148:151], v[100:115]
	ds_read_b128 v[2:5], v230 offset:57472
	s_waitcnt lgkmcnt(0)
	v_mfma_f32_32x32x16_bf16 v[84:99], v[2:5], v[148:151], v[84:99]
	ds_read_b128 v[2:5], v231 offset:49280
	s_waitcnt vmcnt(0) lgkmcnt(0)
	v_mfma_f32_32x32x16_bf16 v[100:115], v[2:5], v[144:147], v[100:115]
	ds_read_b128 v[2:5], v231 offset:57472
	s_waitcnt lgkmcnt(0)
	v_mfma_f32_32x32x16_bf16 v[84:99], v[2:5], v[144:147], v[84:99]
	s_branch .LBB0_242

; __device__ __forceinline__ void finishSM(f32x16& p0, f32x16& p1, float alpha, float& l_reg, bf16x8& pa0, bf16x8& pa1, bf16x8& pa2, bf16x8& pa3) {
;     for (int r = 0; r < 16; ++r) p1[r] = __builtin_amdgcn_exp2f(p1[r]);
;     float ps = 0; for (int r = 0; r < 16; ++r) ps += p0[r]; for (int r = 0; r < 16; ++r) ps += p1[r];
;     { auto rr = __builtin_amdgcn_permlane32_swap(__float_as_uint(ps), __float_as_uint(ps), false, false);
;       ps = __uint_as_float(rr[0]) + __uint_as_float(rr[1]); }
;     l_reg = l_reg * alpha + ps;
;     ...
;     PK4(p0, 0, pa0); PK4(p0, 8, pa1); PK4(p1, 0, pa2); PK4(p1, 8, pa3);
;     ...
; }
; template <int VB, bool SK>
; __device__ __forceinline__ void pv_tile(f32x16* o, int vb0, bf16x8 pa0, bf16x8 pa1, bf16x8 pa2, bf16x8 pa3, bool act) {
;     if (SK && !act) return;
;     ...
;     PV_D0(0); PV_D0(1); PV_D0(2); PV_D0(3);
.LBB0_242:
	v_add_f32_e32 v2, 0, v189
	v_add_f32_e32 v2, v191, v2
	v_add_f32_e32 v2, v187, v2
	v_add_f32_e32 v2, v190, v2
	v_add_f32_e32 v2, v185, v2
	v_add_f32_e32 v2, v188, v2
	v_add_f32_e32 v2, v184, v2
	v_add_f32_e32 v2, v186, v2
	v_add_f32_e32 v2, v178, v2
	v_add_f32_e32 v2, v181, v2
	v_add_f32_e32 v2, v177, v2
	v_add_f32_e32 v2, v179, v2
	v_exp_f32_e32 v1, v142
	v_add_f32_e32 v2, v176, v2
	v_exp_f32_e32 v10, v143
	v_add_f32_e32 v2, v183, v2
	v_exp_f32_e32 v11, v140
	v_add_f32_e32 v2, v180, v2
	v_exp_f32_e32 v12, v141
	v_add_f32_e32 v2, v182, v2
	v_exp_f32_e32 v13, v138
	v_add_f32_e32 v2, v1, v2
	v_exp_f32_e32 v14, v139
	v_add_f32_e32 v2, v10, v2
	v_exp_f32_e32 v15, v136
	v_add_f32_e32 v2, v11, v2
	v_exp_f32_e32 v80, v137
	v_add_f32_e32 v2, v12, v2
	v_exp_f32_e32 v81, v134
	v_add_f32_e32 v2, v13, v2
	v_exp_f32_e32 v82, v135
	v_add_f32_e32 v2, v14, v2
	v_exp_f32_e32 v83, v132
	v_add_f32_e32 v2, v15, v2
	s_waitcnt vmcnt(2)
	v_exp_f32_e32 v116, v133
	v_add_f32_e32 v2, v80, v2
	v_exp_f32_e32 v117, v130
	v_add_f32_e32 v2, v81, v2
	v_exp_f32_e32 v118, v131
	v_add_f32_e32 v2, v82, v2
	v_exp_f32_e32 v119, v128
	v_add_f32_e32 v2, v83, v2
	s_waitcnt vmcnt(1)
	v_exp_f32_e32 v120, v129
	v_add_f32_e32 v2, v116, v2
	v_add_f32_e32 v2, v117, v2
	v_add_f32_e32 v2, v118, v2
	v_add_f32_e32 v2, v119, v2
	v_add_f32_e32 v232, v120, v2
	v_mov_b32_e32 v233, v232
	v_cvt_pk_bf16_f32 v2, v189, v191
	v_cvt_pk_bf16_f32 v3, v187, v190
	v_cvt_pk_bf16_f32 v4, v185, v188
	v_cvt_pk_bf16_f32 v5, v184, v186
	v_cvt_pk_bf16_f32 v6, v178, v181
	v_cvt_pk_bf16_f32 v7, v177, v179
	v_cvt_pk_bf16_f32 v8, v176, v183
	v_cvt_pk_bf16_f32 v9, v180, v182
	v_cvt_pk_bf16_f32 v10, v1, v10
	v_cvt_pk_bf16_f32 v11, v11, v12
	v_cvt_pk_bf16_f32 v12, v13, v14
	v_cvt_pk_bf16_f32 v13, v15, v80
	v_cvt_pk_bf16_f32 v80, v81, v82
	v_cvt_pk_bf16_f32 v81, v83, v116
	v_cvt_pk_bf16_f32 v82, v117, v118
	v_cvt_pk_bf16_f32 v83, v119, v120
	s_nop 1
	v_permlane32_swap_b32_e32 v232, v233
	v_permlane32_swap_b32_e32 v2, v4
	v_permlane32_swap_b32_e32 v3, v5
	v_permlane32_swap_b32_e32 v6, v8
	v_permlane32_swap_b32_e32 v7, v9
	v_permlane32_swap_b32_e32 v10, v12
	v_permlane32_swap_b32_e32 v11, v13
	v_permlane32_swap_b32_e32 v80, v82
	v_permlane32_swap_b32_e32 v81, v83
	v_add_u32_e32 v235, s60, v203
	v_add_u32_e32 v1, 0x80, v235
	v_mad_i64_i32 v[14:15], s[38:39], v1, s48, 0
	v_add_u32_e32 v1, 0xa0, v235
	v_lshlrev_b64 v[14:15], 1, v[14:15]
	v_mad_i64_i32 v[118:119], s[38:39], v1, s48, 0
	v_lshl_add_u64 v[116:117], v[204:205], 0, v[14:15]
	v_lshlrev_b64 v[118:119], 1, v[118:119]
	v_lshl_add_u64 v[14:15], v[206:207], 0, v[14:15]
	v_lshl_add_u64 v[120:121], v[204:205], 0, v[118:119]
	global_load_dwordx4 v[176:179], v[116:117], off
	global_load_dwordx4 v[180:183], v[120:121], off
	v_lshl_add_u64 v[116:117], v[206:207], 0, v[118:119]
	global_load_dwordx4 v[184:187], v[14:15], off
	global_load_dwordx4 v[188:191], v[116:117], off
	s_cmp_le_i32 s60, s55
	s_cselect_b64 s[38:39], -1, 0
	s_add_i32 s61, s60, 63
	s_cmp_ge_i32 s61, s56
	s_cselect_b64 s[62:63], -1, 0
	s_and_b64 s[38:39], s[38:39], s[62:63]
	s_andn2_b64 vcc, exec, s[38:39]
	s_cbranch_vccnz .LBB0_244
	ds_read_b64_tr_b16 v[116:117], v215 offset:0
	ds_read_b64_tr_b16 v[118:119], v215 offset:0x800
	ds_read_b64_tr_b16 v[120:121], v215 offset:0x1000
	ds_read_b64_tr_b16 v[122:123], v215 offset:0x1800
	s_waitcnt vmcnt(4)
	ds_read_b64_tr_b16 v[124:125], v215 offset:0x2000
	ds_read_b64_tr_b16 v[126:127], v215 offset:0x2800
	ds_read_b64_tr_b16 v[128:129], v215 offset:0x3000
	ds_read_b64_tr_b16 v[130:131], v215 offset:0x3800
	s_waitcnt lgkmcnt(0)
	v_mfma_f32_32x32x16_bf16 v[64:79], v[2:5], v[116:119], v[64:79]
	ds_read_b64_tr_b16 v[116:117], v215 offset:0x200
	ds_read_b64_tr_b16 v[118:119], v215 offset:0xa00
	v_mfma_f32_32x32x16_bf16 v[64:79], v[6:9], v[120:123], v[64:79]
	ds_read_b64_tr_b16 v[120:121], v215 offset:0x1200
	ds_read_b64_tr_b16 v[122:123], v215 offset:0x1a00
	v_mfma_f32_32x32x16_bf16 v[64:79], v[10:13], v[124:127], v[64:79]
	ds_read_b64_tr_b16 v[124:125], v215 offset:0x2200
	ds_read_b64_tr_b16 v[126:127], v215 offset:0x2a00
	v_mfma_f32_32x32x16_bf16 v[64:79], v[80:83], v[128:131], v[64:79]
	ds_read_b64_tr_b16 v[128:129], v215 offset:0x3200
	ds_read_b64_tr_b16 v[130:131], v215 offset:0x3a00
	s_waitcnt lgkmcnt(0)
	v_mfma_f32_32x32x16_bf16 v[48:63], v[2:5], v[116:119], v[48:63]
	ds_read_b64_tr_b16 v[116:117], v215 offset:0x400
	ds_read_b64_tr_b16 v[118:119], v215 offset:0xc00
	v_mfma_f32_32x32x16_bf16 v[48:63], v[6:9], v[120:123], v[48:63]
	ds_read_b64_tr_b16 v[120:121], v215 offset:0x1400
	ds_read_b64_tr_b16 v[122:123], v215 offset:0x1c00
	v_mfma_f32_32x32x16_bf16 v[48:63], v[10:13], v[124:127], v[48:63]
	ds_read_b64_tr_b16 v[124:125], v215 offset:0x2400
	ds_read_b64_tr_b16 v[126:127], v215 offset:0x2c00
	v_mfma_f32_32x32x16_bf16 v[48:63], v[80:83], v[128:131], v[48:63]
	ds_read_b64_tr_b16 v[128:129], v215 offset:0x3400
	ds_read_b64_tr_b16 v[130:131], v215 offset:0x3c00
	s_waitcnt lgkmcnt(0)
	v_mfma_f32_32x32x16_bf16 v[32:47], v[2:5], v[116:119], v[32:47]
	ds_read_b64_tr_b16 v[116:117], v215 offset:0x600
	ds_read_b64_tr_b16 v[118:119], v215 offset:0xe00
	v_mfma_f32_32x32x16_bf16 v[32:47], v[6:9], v[120:123], v[32:47]
	ds_read_b64_tr_b16 v[120:121], v215 offset:0x1600
	ds_read_b64_tr_b16 v[122:123], v215 offset:0x1e00
	v_mfma_f32_32x32x16_bf16 v[32:47], v[10:13], v[124:127], v[32:47]
	ds_read_b64_tr_b16 v[124:125], v215 offset:0x2600
	ds_read_b64_tr_b16 v[126:127], v215 offset:0x2e00
	v_mfma_f32_32x32x16_bf16 v[32:47], v[80:83], v[128:131], v[32:47]
	ds_read_b64_tr_b16 v[128:129], v215 offset:0x3600
	ds_read_b64_tr_b16 v[130:131], v215 offset:0x3e00
	s_waitcnt lgkmcnt(0)
	v_mfma_f32_32x32x16_bf16 v[16:31], v[2:5], v[116:119], v[16:31]
	v_mfma_f32_32x32x16_bf16 v[16:31], v[6:9], v[120:123], v[16:31]
	v_mfma_f32_32x32x16_bf16 v[16:31], v[10:13], v[124:127], v[16:31]
	v_mfma_f32_32x32x16_bf16 v[16:31], v[80:83], v[128:131], v[16:31]

; __device__ __forceinline__ void partialSM(f32x16& p0, f32x16& p1, float& m_reg, float& mn, float& alpha) {
;     ...
;     constexpr float C2 = 1.4426950408889634f * SCALE;
;     if (__builtin_expect(__all((pmax - m_reg) * SCALE <= THR), 1)) { mn = m_reg; alpha = 1.f; }
;     else { mn = fmaxf(m_reg, pmax); alpha = __builtin_amdgcn_exp2f((m_reg - mn) * C2); m_reg = mn; }
;     const float mnL = -mn * C2;
;     for (int r = 0; r < 16; ++r) p0[r] = fmaf(p0[r], C2, mnL); for (int r = 0; r < 16; ++r) p1[r] = fmaf(p1[r], C2, mnL);
;     for (int r = 0; r < 16; ++r) p0[r] = __builtin_amdgcn_exp2f(p0[r]);
; template <int KB, bool SK>
; __device__ __forceinline__ void qkt(f32x16& p0, f32x16& p1, const char* K_lds, int r32, int hi, const bf16x8* qr, bool act) {
;     if (SK && !act) { const float NEG = -__builtin_inff();
; #pragma unroll
;         for (int r = 0; r < 16; ++r) { p0[r] = NEG; p1[r] = NEG; } return; }
;     p0 = f32x16{}; p1 = f32x16{};
;     const char* kb[4];
; #pragma unroll
;     for (int dd = 0; dd < 4; ++dd) kb[dd] = K_lds + KB * SHM_K + KSWZ(r32, (dd * 16 + hi * 8) * 2);
; #pragma unroll
;     for (int d0 = 0; d0 < 8; ++d0) { const char* a = kb[d0 & 3] + (d0 >> 2) * 128;
;         bf16x8 b0 = *reinterpret_cast<const bf16x8*>(a);
;         bf16x8 b1 = *reinterpret_cast<const bf16x8*>(a + 32 * 256);
;         p0 = __builtin_amdgcn_mfma_f32_32x32x16_bf16(b0, qr[d0], p0, 0, 0, 0);
;         p1 = __builtin_amdgcn_mfma_f32_32x32x16_bf16(b1, qr[d0], p1, 0, 0, 0); }
; }
.LBB0_251:
	v_cndmask_b32_e64 v236, v1, v192, s[10:11]
	v_mul_f32_e32 v192, 0xbe0293ee, v236
	v_fmamk_f32 v1, v100, 0x3e0293ee, v192
	v_fmamk_f32 v2, v101, 0x3e0293ee, v192
	v_fmamk_f32 v3, v102, 0x3e0293ee, v192
	v_fmamk_f32 v4, v103, 0x3e0293ee, v192
	v_fmamk_f32 v5, v104, 0x3e0293ee, v192
	v_fmamk_f32 v6, v105, 0x3e0293ee, v192
	v_fmamk_f32 v7, v106, 0x3e0293ee, v192
	v_fmamk_f32 v8, v107, 0x3e0293ee, v192
	v_fmamk_f32 v9, v108, 0x3e0293ee, v192
	v_fmamk_f32 v10, v109, 0x3e0293ee, v192
	v_fmamk_f32 v11, v110, 0x3e0293ee, v192
	v_fmamk_f32 v12, v111, 0x3e0293ee, v192
	v_fmamk_f32 v13, v112, 0x3e0293ee, v192
	v_fmamk_f32 v14, v113, 0x3e0293ee, v192
	v_fmamk_f32 v15, v114, 0x3e0293ee, v192
	v_fmamk_f32 v112, v115, 0x3e0293ee, v192
	v_fmamk_f32 v100, v84, 0x3e0293ee, v192
	v_fmamk_f32 v101, v85, 0x3e0293ee, v192
	v_fmamk_f32 v102, v86, 0x3e0293ee, v192
	v_fmamk_f32 v103, v87, 0x3e0293ee, v192
	v_fmamk_f32 v104, v88, 0x3e0293ee, v192
	v_fmamk_f32 v105, v89, 0x3e0293ee, v192
	v_fmamk_f32 v106, v90, 0x3e0293ee, v192
	v_fmamk_f32 v107, v91, 0x3e0293ee, v192
	v_fmamk_f32 v108, v92, 0x3e0293ee, v192
	v_fmamk_f32 v109, v93, 0x3e0293ee, v192
	v_fmamk_f32 v110, v94, 0x3e0293ee, v192
	v_fmamk_f32 v111, v95, 0x3e0293ee, v192
	v_exp_f32_e32 v80, v1
	v_exp_f32_e32 v81, v2
	v_exp_f32_e32 v82, v3
	v_exp_f32_e32 v83, v4
	v_exp_f32_e32 v84, v5
	v_exp_f32_e32 v85, v6
	v_exp_f32_e32 v86, v7
	v_exp_f32_e32 v87, v8
	v_exp_f32_e32 v88, v9
	v_exp_f32_e32 v89, v10
	v_exp_f32_e32 v90, v11
	v_exp_f32_e32 v91, v12
	v_exp_f32_e32 v92, v13
	v_exp_f32_e32 v93, v14
	v_exp_f32_e32 v94, v15
	v_exp_f32_e32 v95, v112
	v_fmamk_f32 v193, v96, 0x3e0293ee, v192
	v_fmamk_f32 v194, v97, 0x3e0293ee, v192
	v_fmamk_f32 v195, v98, 0x3e0293ee, v192
	v_fmac_f32_e32 v192, 0x3e0293ee, v99
	s_add_i32 s61, s60, 0x80
	s_waitcnt lgkmcnt(0)
	s_barrier
	s_cmp_gt_i32 s61, s55
	s_cselect_b64 s[10:11], -1, 0
	s_addk_i32 s60, 0xbf
	s_cmp_lt_i32 s60, s56
	s_cselect_b64 s[38:39], -1, 0
	s_or_b64 s[10:11], s[10:11], s[38:39]
	s_and_b64 vcc, exec, s[10:11]
	s_cbranch_vccnz .LBB0_253
	ds_read_b128 v[2:5], v228 offset:32768
	s_waitcnt lgkmcnt(0)
	v_mfma_f32_32x32x16_bf16 v[128:143], v[2:5], v[172:175], 0
	ds_read_b128 v[2:5], v228 offset:40960
	s_waitcnt lgkmcnt(0)
	v_mfma_f32_32x32x16_bf16 v[112:127], v[2:5], v[172:175], 0
	ds_read_b128 v[2:5], v229 offset:32768
	s_waitcnt lgkmcnt(0)
	v_mfma_f32_32x32x16_bf16 v[128:143], v[2:5], v[168:171], v[128:143]
	ds_read_b128 v[2:5], v229 offset:40960
	s_waitcnt lgkmcnt(0)
	v_mfma_f32_32x32x16_bf16 v[112:127], v[2:5], v[168:171], v[112:127]
	ds_read_b128 v[2:5], v230 offset:32768
	s_waitcnt lgkmcnt(0)
	v_mfma_f32_32x32x16_bf16 v[128:143], v[2:5], v[164:167], v[128:143]
	ds_read_b128 v[2:5], v230 offset:40960
	s_waitcnt lgkmcnt(0)
	v_mfma_f32_32x32x16_bf16 v[112:127], v[2:5], v[164:167], v[112:127]
	ds_read_b128 v[2:5], v231 offset:32768
	s_waitcnt lgkmcnt(0)
	v_mfma_f32_32x32x16_bf16 v[128:143], v[2:5], v[160:163], v[128:143]
	ds_read_b128 v[2:5], v231 offset:40960
	s_waitcnt lgkmcnt(0)
	v_mfma_f32_32x32x16_bf16 v[112:127], v[2:5], v[160:163], v[112:127]
	ds_read_b128 v[2:5], v228 offset:32896
	s_waitcnt lgkmcnt(0)
	v_mfma_f32_32x32x16_bf16 v[128:143], v[2:5], v[156:159], v[128:143]
	ds_read_b128 v[2:5], v228 offset:41088
	s_waitcnt lgkmcnt(0)
	v_mfma_f32_32x32x16_bf16 v[112:127], v[2:5], v[156:159], v[112:127]
	ds_read_b128 v[2:5], v229 offset:32896
	s_waitcnt lgkmcnt(0)
	v_mfma_f32_32x32x16_bf16 v[128:143], v[2:5], v[152:155], v[128:143]
	ds_read_b128 v[2:5], v229 offset:41088
	s_waitcnt lgkmcnt(0)
	v_mfma_f32_32x32x16_bf16 v[112:127], v[2:5], v[152:155], v[112:127]
	ds_read_b128 v[2:5], v230 offset:32896
	s_waitcnt lgkmcnt(0)
	v_mfma_f32_32x32x16_bf16 v[128:143], v[2:5], v[148:151], v[128:143]
	ds_read_b128 v[2:5], v230 offset:41088
	s_waitcnt lgkmcnt(0)
	v_mfma_f32_32x32x16_bf16 v[112:127], v[2:5], v[148:151], v[112:127]
	ds_read_b128 v[2:5], v231 offset:32896
	s_waitcnt lgkmcnt(0)
	v_mfma_f32_32x32x16_bf16 v[128:143], v[2:5], v[144:147], v[128:143]
	ds_read_b128 v[2:5], v231 offset:41088
	s_waitcnt lgkmcnt(0)
	v_mfma_f32_32x32x16_bf16 v[112:127], v[2:5], v[144:147], v[112:127]
	s_branch .LBB0_254

; template <int VB, bool SK>
; __device__ __forceinline__ void pv_tile(f32x16* o, int vb0, bf16x8 pa0, bf16x8 pa1, bf16x8 pa2, bf16x8 pa3, bool act) {
;     if (SK && !act) return;
;     ...
;     PV_D0(0); PV_D0(1); PV_D0(2); PV_D0(3);
.LBB0_258:
	ds_read_b64_tr_b16 v[238:239], v215 offset:0x4000
	ds_read_b64_tr_b16 v[240:241], v215 offset:0x4800
	ds_read_b64_tr_b16 v[242:243], v215 offset:0x5000
	ds_read_b64_tr_b16 v[244:245], v215 offset:0x5800
	ds_read_b64_tr_b16 v[246:247], v215 offset:0x6000
	ds_read_b64_tr_b16 v[248:249], v215 offset:0x6800
	ds_read_b64_tr_b16 v[250:251], v215 offset:0x7000
	ds_read_b64_tr_b16 v[252:253], v215 offset:0x7800
	s_waitcnt lgkmcnt(0)
	s_nop 0
	v_mfma_f32_32x32x16_bf16 v[64:79], v[2:5], v[238:241], v[64:79]
	ds_read_b64_tr_b16 v[238:239], v215 offset:0x4200
	ds_read_b64_tr_b16 v[240:241], v215 offset:0x4a00
	v_mfma_f32_32x32x16_bf16 v[64:79], v[6:9], v[242:245], v[64:79]
	ds_read_b64_tr_b16 v[242:243], v215 offset:0x5200
	ds_read_b64_tr_b16 v[244:245], v215 offset:0x5a00
	v_mfma_f32_32x32x16_bf16 v[64:79], v[10:13], v[246:249], v[64:79]
	ds_read_b64_tr_b16 v[246:247], v215 offset:0x6200
	ds_read_b64_tr_b16 v[248:249], v215 offset:0x6a00
	v_mfma_f32_32x32x16_bf16 v[64:79], v[192:195], v[250:253], v[64:79]
	ds_read_b64_tr_b16 v[250:251], v215 offset:0x7200
	ds_read_b64_tr_b16 v[252:253], v215 offset:0x7a00
	s_waitcnt lgkmcnt(0)
	v_mfma_f32_32x32x16_bf16 v[48:63], v[2:5], v[238:241], v[48:63]
	ds_read_b64_tr_b16 v[238:239], v215 offset:0x4400
	ds_read_b64_tr_b16 v[240:241], v215 offset:0x4c00
	v_mfma_f32_32x32x16_bf16 v[48:63], v[6:9], v[242:245], v[48:63]
	ds_read_b64_tr_b16 v[242:243], v215 offset:0x5400
	ds_read_b64_tr_b16 v[244:245], v215 offset:0x5c00
	v_mfma_f32_32x32x16_bf16 v[48:63], v[10:13], v[246:249], v[48:63]
	ds_read_b64_tr_b16 v[246:247], v215 offset:0x6400
	ds_read_b64_tr_b16 v[248:249], v215 offset:0x6c00
	v_mfma_f32_32x32x16_bf16 v[48:63], v[192:195], v[250:253], v[48:63]
	ds_read_b64_tr_b16 v[250:251], v215 offset:0x7400
	ds_read_b64_tr_b16 v[252:253], v215 offset:0x7c00
	s_waitcnt lgkmcnt(0)
	v_mfma_f32_32x32x16_bf16 v[32:47], v[2:5], v[238:241], v[32:47]
	ds_read_b64_tr_b16 v[238:239], v215 offset:0x4600
	ds_read_b64_tr_b16 v[240:241], v215 offset:0x4e00
	v_mfma_f32_32x32x16_bf16 v[32:47], v[6:9], v[242:245], v[32:47]
	ds_read_b64_tr_b16 v[242:243], v215 offset:0x5600
	ds_read_b64_tr_b16 v[244:245], v215 offset:0x5e00
	v_mfma_f32_32x32x16_bf16 v[32:47], v[10:13], v[246:249], v[32:47]
	ds_read_b64_tr_b16 v[246:247], v215 offset:0x6600
	ds_read_b64_tr_b16 v[248:249], v215 offset:0x6e00
	v_mfma_f32_32x32x16_bf16 v[32:47], v[192:195], v[250:253], v[32:47]
	ds_read_b64_tr_b16 v[250:251], v215 offset:0x7600
	ds_read_b64_tr_b16 v[252:253], v215 offset:0x7e00
	s_waitcnt lgkmcnt(0)
	v_mfma_f32_32x32x16_bf16 v[16:31], v[2:5], v[238:241], v[16:31]
	v_mfma_f32_32x32x16_bf16 v[16:31], v[6:9], v[242:245], v[16:31]
	v_mfma_f32_32x32x16_bf16 v[16:31], v[10:13], v[246:249], v[16:31]
	v_mfma_f32_32x32x16_bf16 v[16:31], v[192:195], v[250:253], v[16:31]
	s_xor_b64 s[8:9], s[10:11], -1
	s_andn2_b64 vcc, exec, s[8:9]
	s_cbranch_vccnz .LBB0_261

; #define SBAR() __builtin_amdgcn_sched_barrier(0)
; #define SLOAD_HP(Kp, Vp, k0, pt) do { S.st_v0 = load8<TIn>(ROWP(Vp, k0, sr, pt)); S.st_v1 = load8<TIn>(ROWP(Vp, k0, 32 + sr, pt));              \
;                          S.st_k0 = load8<TIn>(ROWP(Kp, k0, sr, pt)); S.st_k1 = load8<TIn>(ROWP(Kp, k0, 32 + sr, pt)); } while (0)
; #define ACT(t) (KBASE(t) <= qlo + QBLK - 1 && KBASE(t) + KVBLK - 1 >= qlo - W + 1)
; template <int VB, bool SK>
; __device__ __forceinline__ void pv_tile(f32x16* o, int vb0, bf16x8 pa0, bf16x8 pa1, bf16x8 pa2, bf16x8 pa3, bool act) {
;     if (SK && !act) return;
;     ...
;     PV_D0(0); PV_D0(1); PV_D0(2); PV_D0(3);
; template <class TIn, class TOut>
; __device__ __forceinline__ void causal_swa_block(const BlockRef<TIn, TOut>& cur, const BlockRef<TIn, TOut>& nxt, int skv, int W, char* lds, Seam<TIn>& S) {
;     ...
;     else { SLOAD_HP(nxt.K, nxt.V, kbn, nxt.pitch); SBAR();
; #pragma unroll
;         for (int d0 = 0; d0 < 8; ++d0) S.qr[d0] = load8<TIn>(nxt.Q + (size_t)(wid * QBLK + r32) * (size_t)nxt.pitch + d0 * 16 + hi * 8); }
;     SBAR();
;     finishSM(pA0, pA1, alA, l_reg, pa0, pa1, pa2, pa3); SBAR();
;     if constexpr (F32) {
; #pragma unroll
;         for (int e = 8; e < 16; ++e) S.tq[e] = *(const f32x4*)QROW(e); SBAR(); }
;     ...
;     pv_tile<0, SK>(o, vb0, pa0, pa1, pa2, pa3, ACT(even ? NT - 2 : NT - 1));
.LBB0_274:
.LBB0_275:
	s_and_b32 s8, s51, 0xffffffc0
	s_addk_i32 s8, 0xff80
	s_cmpk_gt_i32 s51, 0x80
	s_cselect_b32 s10, s8, 0
	v_add_u32_e32 v1, s10, v203
	v_mad_i64_i32 v[2:3], s[8:9], v1, s49, 0
	v_add_u32_e32 v1, s10, v217
	v_lshlrev_b64 v[2:3], 1, v[2:3]
	v_mad_i64_i32 v[6:7], s[8:9], v1, s49, 0
	v_lshl_add_u64 v[4:5], s[28:29], 0, v[2:3]
	v_lshlrev_b64 v[6:7], 1, v[6:7]
	v_lshl_add_u64 v[4:5], v[4:5], 0, v[196:197]
	v_lshl_add_u64 v[8:9], s[28:29], 0, v[6:7]
	v_lshl_add_u64 v[2:3], s[26:27], 0, v[2:3]
	v_lshl_add_u64 v[8:9], v[8:9], 0, v[196:197]
	global_load_dwordx4 v[112:115], v[4:5], off
	global_load_dwordx4 v[116:119], v[8:9], off
	v_lshl_add_u64 v[2:3], v[2:3], 0, v[196:197]
	v_lshl_add_u64 v[4:5], s[26:27], 0, v[6:7]
	v_lshl_add_u64 v[4:5], v[4:5], 0, v[196:197]
	global_load_dwordx4 v[120:123], v[2:3], off
	global_load_dwordx4 v[124:127], v[4:5], off
	v_or_b32_e32 v1, s52, v210
	v_mad_i64_i32 v[2:3], s[8:9], v1, s49, 0
	v_lshl_add_u64 v[2:3], v[2:3], 1, s[36:37]
	v_mov_b32_e32 v203, v197
	v_lshl_add_u64 v[2:3], v[2:3], 0, v[202:203]
	global_load_dwordx4 v[172:175], v[2:3], off
	global_load_dwordx4 v[168:171], v[2:3], off offset:32
	global_load_dwordx4 v[164:167], v[2:3], off offset:64
	global_load_dwordx4 v[160:163], v[2:3], off offset:96
	global_load_dwordx4 v[156:159], v[2:3], off offset:128
	global_load_dwordx4 v[152:155], v[2:3], off offset:160
	global_load_dwordx4 v[148:151], v[2:3], off offset:192
	global_load_dwordx4 v[144:147], v[2:3], off offset:224
	v_add_f32_e32 v2, 0, v189
	v_add_f32_e32 v2, v191, v2
	v_add_f32_e32 v2, v187, v2
	v_add_f32_e32 v2, v190, v2
	v_add_f32_e32 v2, v185, v2
	v_add_f32_e32 v2, v188, v2
	v_add_f32_e32 v2, v184, v2
	v_add_f32_e32 v2, v186, v2
	v_add_f32_e32 v2, v178, v2
	v_add_f32_e32 v2, v181, v2
	v_add_f32_e32 v2, v177, v2
	v_add_f32_e32 v2, v179, v2
	v_exp_f32_e32 v10, v142
	v_add_f32_e32 v2, v176, v2
	v_exp_f32_e32 v11, v143
	v_add_f32_e32 v2, v183, v2
	v_exp_f32_e32 v12, v140
	v_add_f32_e32 v2, v180, v2
	v_exp_f32_e32 v13, v141
	v_add_f32_e32 v2, v182, v2
	v_exp_f32_e32 v138, v138
	v_add_f32_e32 v2, v10, v2
	v_exp_f32_e32 v139, v139
	v_add_f32_e32 v2, v11, v2
	v_exp_f32_e32 v136, v136
	v_add_f32_e32 v2, v12, v2
	v_exp_f32_e32 v137, v137
	v_add_f32_e32 v2, v13, v2
	v_exp_f32_e32 v134, v134
	v_add_f32_e32 v2, v138, v2
	v_exp_f32_e32 v135, v135
	v_add_f32_e32 v2, v139, v2
	v_exp_f32_e32 v132, v132
	v_add_f32_e32 v2, v136, v2
	v_exp_f32_e32 v133, v133
	v_add_f32_e32 v2, v137, v2
	v_exp_f32_e32 v130, v130
	v_add_f32_e32 v2, v134, v2
	v_exp_f32_e32 v131, v131
	v_add_f32_e32 v2, v135, v2
	v_exp_f32_e32 v140, v128
	v_add_f32_e32 v2, v132, v2
	v_exp_f32_e32 v141, v129
	v_add_f32_e32 v2, v133, v2
	v_add_f32_e32 v2, v130, v2
	v_add_f32_e32 v2, v131, v2
	v_add_f32_e32 v2, v140, v2
	v_add_f32_e32 v14, v141, v2
	v_mov_b32_e32 v15, v14
	v_cvt_pk_bf16_f32 v2, v189, v191
	v_cvt_pk_bf16_f32 v3, v187, v190
	v_cvt_pk_bf16_f32 v4, v185, v188
	v_cvt_pk_bf16_f32 v5, v184, v186
	v_cvt_pk_bf16_f32 v6, v178, v181
	v_cvt_pk_bf16_f32 v7, v177, v179
	v_cvt_pk_bf16_f32 v8, v176, v183
	v_cvt_pk_bf16_f32 v9, v180, v182
	v_cvt_pk_bf16_f32 v10, v10, v11
	v_cvt_pk_bf16_f32 v11, v12, v13
	v_cvt_pk_bf16_f32 v12, v138, v139
	v_cvt_pk_bf16_f32 v13, v136, v137
	v_cvt_pk_bf16_f32 v128, v134, v135
	v_cvt_pk_bf16_f32 v129, v132, v133
	v_cvt_pk_bf16_f32 v130, v130, v131
	v_cvt_pk_bf16_f32 v131, v140, v141
	s_nop 1
	v_permlane32_swap_b32_e32 v14, v15
	v_permlane32_swap_b32_e32 v2, v4
	v_permlane32_swap_b32_e32 v3, v5
	v_permlane32_swap_b32_e32 v6, v8
	v_permlane32_swap_b32_e32 v7, v9
	v_permlane32_swap_b32_e32 v10, v12
	v_permlane32_swap_b32_e32 v11, v13
	v_permlane32_swap_b32_e32 v128, v130
	v_permlane32_swap_b32_e32 v129, v131
	s_or_b32 s8, s57, -2
	s_add_i32 s8, s8, s53
	s_lshl_b32 s10, s8, 6
	s_cmp_le_i32 s10, s55
	s_cselect_b64 s[8:9], -1, 0
	s_or_b32 s10, s10, 63
	s_cmp_ge_i32 s10, s56
	s_cselect_b64 s[10:11], -1, 0
	s_and_b64 s[8:9], s[8:9], s[10:11]
	s_andn2_b64 vcc, exec, s[8:9]
	s_cbranch_vccnz .LBB0_277
	ds_read_b64_tr_b16 v[132:133], v215 offset:0
	ds_read_b64_tr_b16 v[134:135], v215 offset:0x800
	ds_read_b64_tr_b16 v[136:137], v215 offset:0x1000
	ds_read_b64_tr_b16 v[138:139], v215 offset:0x1800
	ds_read_b64_tr_b16 v[140:141], v215 offset:0x2000
	ds_read_b64_tr_b16 v[142:143], v215 offset:0x2800
	ds_read_b64_tr_b16 v[176:177], v215 offset:0x3000
	ds_read_b64_tr_b16 v[178:179], v215 offset:0x3800
	s_waitcnt lgkmcnt(0)
	s_nop 0
	v_mfma_f32_32x32x16_bf16 v[64:79], v[2:5], v[132:135], v[64:79]
	ds_read_b64_tr_b16 v[132:133], v215 offset:0x200
	ds_read_b64_tr_b16 v[134:135], v215 offset:0xa00
	v_mfma_f32_32x32x16_bf16 v[64:79], v[6:9], v[136:139], v[64:79]
	ds_read_b64_tr_b16 v[136:137], v215 offset:0x1200
	ds_read_b64_tr_b16 v[138:139], v215 offset:0x1a00
	v_mfma_f32_32x32x16_bf16 v[64:79], v[10:13], v[140:143], v[64:79]
	ds_read_b64_tr_b16 v[140:141], v215 offset:0x2200
	ds_read_b64_tr_b16 v[142:143], v215 offset:0x2a00
	v_mfma_f32_32x32x16_bf16 v[64:79], v[128:131], v[176:179], v[64:79]
	ds_read_b64_tr_b16 v[176:177], v215 offset:0x3200
	ds_read_b64_tr_b16 v[178:179], v215 offset:0x3a00
	s_waitcnt lgkmcnt(0)
	v_mfma_f32_32x32x16_bf16 v[48:63], v[2:5], v[132:135], v[48:63]
	ds_read_b64_tr_b16 v[132:133], v215 offset:0x400
	ds_read_b64_tr_b16 v[134:135], v215 offset:0xc00
	v_mfma_f32_32x32x16_bf16 v[48:63], v[6:9], v[136:139], v[48:63]
	ds_read_b64_tr_b16 v[136:137], v215 offset:0x1400
	ds_read_b64_tr_b16 v[138:139], v215 offset:0x1c00
	v_mfma_f32_32x32x16_bf16 v[48:63], v[10:13], v[140:143], v[48:63]
	ds_read_b64_tr_b16 v[140:141], v215 offset:0x2400
	ds_read_b64_tr_b16 v[142:143], v215 offset:0x2c00
	v_mfma_f32_32x32x16_bf16 v[48:63], v[128:131], v[176:179], v[48:63]
	ds_read_b64_tr_b16 v[176:177], v215 offset:0x3400
	ds_read_b64_tr_b16 v[178:179], v215 offset:0x3c00
	s_waitcnt lgkmcnt(0)
	v_mfma_f32_32x32x16_bf16 v[32:47], v[2:5], v[132:135], v[32:47]
	ds_read_b64_tr_b16 v[132:133], v215 offset:0x600
	ds_read_b64_tr_b16 v[134:135], v215 offset:0xe00
	v_mfma_f32_32x32x16_bf16 v[32:47], v[6:9], v[136:139], v[32:47]
	ds_read_b64_tr_b16 v[136:137], v215 offset:0x1600
	ds_read_b64_tr_b16 v[138:139], v215 offset:0x1e00
	v_mfma_f32_32x32x16_bf16 v[32:47], v[10:13], v[140:143], v[32:47]
	ds_read_b64_tr_b16 v[140:141], v215 offset:0x2600
	ds_read_b64_tr_b16 v[142:143], v215 offset:0x2e00
	v_mfma_f32_32x32x16_bf16 v[32:47], v[128:131], v[176:179], v[32:47]
	ds_read_b64_tr_b16 v[176:177], v215 offset:0x3600
	ds_read_b64_tr_b16 v[178:179], v215 offset:0x3e00
	s_waitcnt lgkmcnt(0)
	v_mfma_f32_32x32x16_bf16 v[16:31], v[2:5], v[132:135], v[16:31]
	v_mfma_f32_32x32x16_bf16 v[16:31], v[6:9], v[136:139], v[16:31]
	v_mfma_f32_32x32x16_bf16 v[16:31], v[10:13], v[140:143], v[16:31]
	v_mfma_f32_32x32x16_bf16 v[16:31], v[128:131], v[176:179], v[16:31]

; __device__ __forceinline__ void partialSM(f32x16& p0, f32x16& p1, float& m_reg, float& mn, float& alpha) {
;     ...
;     constexpr float C2 = 1.4426950408889634f * SCALE;
;     if (__builtin_expect(__all((pmax - m_reg) * SCALE <= THR), 1)) { mn = m_reg; alpha = 1.f; }
;     else { mn = fmaxf(m_reg, pmax); alpha = __builtin_amdgcn_exp2f((m_reg - mn) * C2); m_reg = mn; }
;     const float mnL = -mn * C2;
;     for (int r = 0; r < 16; ++r) p0[r] = fmaf(p0[r], C2, mnL); for (int r = 0; r < 16; ++r) p1[r] = fmaf(p1[r], C2, mnL);
;     for (int r = 0; r < 16; ++r) p0[r] = __builtin_amdgcn_exp2f(p0[r]);
; }
; __device__ __forceinline__ void finishSM(f32x16& p0, f32x16& p1, float alpha, float& l_reg, bf16x8& pa0, bf16x8& pa1, bf16x8& pa2, bf16x8& pa3) {
;     for (int r = 0; r < 16; ++r) p1[r] = __builtin_amdgcn_exp2f(p1[r]);
;     float ps = 0; for (int r = 0; r < 16; ++r) ps += p0[r]; for (int r = 0; r < 16; ++r) ps += p1[r];
;     { auto rr = __builtin_amdgcn_permlane32_swap(__float_as_uint(ps), __float_as_uint(ps), false, false);
;       ps = __uint_as_float(rr[0]) + __uint_as_float(rr[1]); }
;     l_reg = l_reg * alpha + ps;
;     ...
;     PK4(p0, 0, pa0); PK4(p0, 8, pa1); PK4(p1, 0, pa2); PK4(p1, 8, pa3);
; template <int VB, bool SK>
; __device__ __forceinline__ void pv_tile(f32x16* o, int vb0, bf16x8 pa0, bf16x8 pa1, bf16x8 pa2, bf16x8 pa3, bool act) {
;     if (SK && !act) return;
;     ...
;     PV_D0(0); PV_D0(1); PV_D0(2); PV_D0(3);
.LBB0_285:
	v_cndmask_b32_e64 v192, v2, v192, s[8:9]
	v_mul_f32_e32 v128, 0xbe0293ee, v192
	v_fmamk_f32 v2, v80, 0x3e0293ee, v128
	v_fmamk_f32 v3, v81, 0x3e0293ee, v128
	v_exp_f32_e32 v2, v2
	v_fmamk_f32 v4, v82, 0x3e0293ee, v128
	v_fmamk_f32 v5, v83, 0x3e0293ee, v128
	v_exp_f32_e32 v83, v3
	v_exp_f32_e32 v3, v4
	v_fmamk_f32 v6, v84, 0x3e0293ee, v128
	v_fmamk_f32 v84, v96, 0x3e0293ee, v128
	v_exp_f32_e32 v82, v5
	v_fmamk_f32 v7, v85, 0x3e0293ee, v128
	v_fmamk_f32 v9, v87, 0x3e0293ee, v128
	v_fmamk_f32 v87, v99, 0x3e0293ee, v128
	v_exp_f32_e32 v4, v6
	v_exp_f32_e32 v99, v84
	v_add_f32_e32 v84, 0, v2
	v_fmamk_f32 v8, v86, 0x3e0293ee, v128
	v_exp_f32_e32 v81, v7
	v_add_f32_e32 v84, v83, v84
	v_exp_f32_e32 v5, v8
	v_add_f32_e32 v84, v3, v84
	v_fmamk_f32 v10, v88, 0x3e0293ee, v128
	v_exp_f32_e32 v80, v9
	v_add_f32_e32 v84, v82, v84
	v_fmamk_f32 v11, v89, 0x3e0293ee, v128
	v_exp_f32_e32 v6, v10
	v_add_f32_e32 v84, v4, v84
	v_fmamk_f32 v12, v90, 0x3e0293ee, v128
	v_exp_f32_e32 v13, v11
	v_add_f32_e32 v84, v81, v84
	v_fmamk_f32 v129, v91, 0x3e0293ee, v128
	v_exp_f32_e32 v7, v12
	v_add_f32_e32 v84, v5, v84
	v_fmamk_f32 v130, v92, 0x3e0293ee, v128
	v_exp_f32_e32 v12, v129
	v_add_f32_e32 v84, v80, v84
	v_fmamk_f32 v131, v93, 0x3e0293ee, v128
	v_exp_f32_e32 v8, v130
	v_add_f32_e32 v84, v6, v84
	v_fmamk_f32 v132, v94, 0x3e0293ee, v128
	v_exp_f32_e32 v11, v131
	v_add_f32_e32 v84, v13, v84
	v_fmamk_f32 v133, v95, 0x3e0293ee, v128
	v_exp_f32_e32 v9, v132
	v_add_f32_e32 v84, v7, v84
	v_exp_f32_e32 v10, v133
	v_add_f32_e32 v84, v12, v84
	v_fmamk_f32 v85, v97, 0x3e0293ee, v128
	v_add_f32_e32 v84, v8, v84
	v_fmamk_f32 v86, v98, 0x3e0293ee, v128
	v_fmamk_f32 v88, v100, 0x3e0293ee, v128
	v_exp_f32_e32 v100, v85
	v_add_f32_e32 v84, v11, v84
	v_exp_f32_e32 v86, v86
	v_add_f32_e32 v84, v9, v84
	v_exp_f32_e32 v87, v87
	v_add_f32_e32 v84, v10, v84
	v_fmamk_f32 v89, v101, 0x3e0293ee, v128
	v_exp_f32_e32 v88, v88
	v_add_f32_e32 v84, v99, v84
	v_fmamk_f32 v90, v102, 0x3e0293ee, v128
	v_exp_f32_e32 v89, v89
	v_add_f32_e32 v84, v100, v84
	v_fmamk_f32 v91, v103, 0x3e0293ee, v128
	v_exp_f32_e32 v90, v90
	v_add_f32_e32 v84, v86, v84
	v_fmamk_f32 v92, v104, 0x3e0293ee, v128
	v_exp_f32_e32 v91, v91
	v_add_f32_e32 v84, v87, v84
	v_fmamk_f32 v93, v105, 0x3e0293ee, v128
	v_exp_f32_e32 v92, v92
	v_add_f32_e32 v84, v88, v84
	v_fmamk_f32 v94, v106, 0x3e0293ee, v128
	v_exp_f32_e32 v93, v93
	v_add_f32_e32 v84, v89, v84
	v_fmamk_f32 v95, v107, 0x3e0293ee, v128
	v_exp_f32_e32 v94, v94
	v_add_f32_e32 v84, v90, v84
	v_fmamk_f32 v96, v108, 0x3e0293ee, v128
	v_exp_f32_e32 v95, v95
	v_add_f32_e32 v84, v91, v84
	v_fmamk_f32 v97, v109, 0x3e0293ee, v128
	v_exp_f32_e32 v96, v96
	v_add_f32_e32 v84, v92, v84
	v_fmamk_f32 v98, v110, 0x3e0293ee, v128
	v_exp_f32_e32 v97, v97
	v_add_f32_e32 v84, v93, v84
	v_fmac_f32_e32 v128, 0x3e0293ee, v111
	v_exp_f32_e32 v98, v98
	v_add_f32_e32 v84, v94, v84
	v_exp_f32_e32 v101, v128
	v_add_f32_e32 v84, v95, v84
	v_add_f32_e32 v84, v96, v84
	v_add_f32_e32 v84, v97, v84
	v_add_f32_e32 v84, v98, v84
	v_add_f32_e32 v84, v101, v84
	v_mov_b32_e32 v85, v84
	v_cvt_pk_bf16_f32 v2, v2, v83
	v_cvt_pk_bf16_f32 v3, v3, v82
	v_cvt_pk_bf16_f32 v4, v4, v81
	v_cvt_pk_bf16_f32 v5, v5, v80
	v_cvt_pk_bf16_f32 v6, v6, v13
	v_cvt_pk_bf16_f32 v7, v7, v12
	v_cvt_pk_bf16_f32 v8, v8, v11
	v_cvt_pk_bf16_f32 v9, v9, v10
	v_cvt_pk_bf16_f32 v10, v99, v100
	v_cvt_pk_bf16_f32 v11, v86, v87
	v_cvt_pk_bf16_f32 v12, v88, v89
	v_cvt_pk_bf16_f32 v13, v90, v91
	v_cvt_pk_bf16_f32 v80, v92, v93
	v_cvt_pk_bf16_f32 v81, v94, v95
	v_cvt_pk_bf16_f32 v82, v96, v97
	v_cvt_pk_bf16_f32 v83, v98, v101
	s_nop 1
	v_permlane32_swap_b32_e32 v84, v85
	v_permlane32_swap_b32_e32 v2, v4
	v_permlane32_swap_b32_e32 v3, v5
	v_permlane32_swap_b32_e32 v6, v8
	v_permlane32_swap_b32_e32 v7, v9
	v_permlane32_swap_b32_e32 v10, v12
	v_permlane32_swap_b32_e32 v11, v13
	v_permlane32_swap_b32_e32 v80, v82
	v_permlane32_swap_b32_e32 v81, v83
	s_and_b64 vcc, exec, s[6:7]
	s_cbranch_vccnz .LBB0_287
	ds_read_b64_tr_b16 v[86:87], v215 offset:0x4000
	ds_read_b64_tr_b16 v[88:89], v215 offset:0x4800
	ds_read_b64_tr_b16 v[90:91], v215 offset:0x5000
	ds_read_b64_tr_b16 v[92:93], v215 offset:0x5800
	ds_read_b64_tr_b16 v[94:95], v215 offset:0x6000
	ds_read_b64_tr_b16 v[96:97], v215 offset:0x6800
	ds_read_b64_tr_b16 v[98:99], v215 offset:0x7000
	ds_read_b64_tr_b16 v[100:101], v215 offset:0x7800
	s_waitcnt lgkmcnt(0)
	s_nop 0
	v_mfma_f32_32x32x16_bf16 v[64:79], v[2:5], v[86:89], v[64:79]
	ds_read_b64_tr_b16 v[86:87], v215 offset:0x4200
	ds_read_b64_tr_b16 v[88:89], v215 offset:0x4a00
	v_mfma_f32_32x32x16_bf16 v[64:79], v[6:9], v[90:93], v[64:79]
	ds_read_b64_tr_b16 v[90:91], v215 offset:0x5200
	ds_read_b64_tr_b16 v[92:93], v215 offset:0x5a00
	v_mfma_f32_32x32x16_bf16 v[64:79], v[10:13], v[94:97], v[64:79]
	ds_read_b64_tr_b16 v[94:95], v215 offset:0x6200
	ds_read_b64_tr_b16 v[96:97], v215 offset:0x6a00
	v_mfma_f32_32x32x16_bf16 v[64:79], v[80:83], v[98:101], v[64:79]
	ds_read_b64_tr_b16 v[98:99], v215 offset:0x7200
	ds_read_b64_tr_b16 v[100:101], v215 offset:0x7a00
	s_waitcnt lgkmcnt(0)
	v_mfma_f32_32x32x16_bf16 v[48:63], v[2:5], v[86:89], v[48:63]
	ds_read_b64_tr_b16 v[86:87], v215 offset:0x4400
	ds_read_b64_tr_b16 v[88:89], v215 offset:0x4c00
	v_mfma_f32_32x32x16_bf16 v[48:63], v[6:9], v[90:93], v[48:63]
	ds_read_b64_tr_b16 v[90:91], v215 offset:0x5400
	ds_read_b64_tr_b16 v[92:93], v215 offset:0x5c00
	v_mfma_f32_32x32x16_bf16 v[48:63], v[10:13], v[94:97], v[48:63]
	ds_read_b64_tr_b16 v[94:95], v215 offset:0x6400
	ds_read_b64_tr_b16 v[96:97], v215 offset:0x6c00
	v_mfma_f32_32x32x16_bf16 v[48:63], v[80:83], v[98:101], v[48:63]
	ds_read_b64_tr_b16 v[98:99], v215 offset:0x7400
	ds_read_b64_tr_b16 v[100:101], v215 offset:0x7c00
	s_waitcnt lgkmcnt(0)
	v_mfma_f32_32x32x16_bf16 v[32:47], v[2:5], v[86:89], v[32:47]
	ds_read_b64_tr_b16 v[86:87], v215 offset:0x4600
	ds_read_b64_tr_b16 v[88:89], v215 offset:0x4e00
	v_mfma_f32_32x32x16_bf16 v[32:47], v[6:9], v[90:93], v[32:47]
	ds_read_b64_tr_b16 v[90:91], v215 offset:0x5600
	ds_read_b64_tr_b16 v[92:93], v215 offset:0x5e00
	v_mfma_f32_32x32x16_bf16 v[32:47], v[10:13], v[94:97], v[32:47]
	ds_read_b64_tr_b16 v[94:95], v215 offset:0x6600
	ds_read_b64_tr_b16 v[96:97], v215 offset:0x6e00
	v_mfma_f32_32x32x16_bf16 v[32:47], v[80:83], v[98:101], v[32:47]
	ds_read_b64_tr_b16 v[98:99], v215 offset:0x7600
	ds_read_b64_tr_b16 v[100:101], v215 offset:0x7e00
	s_waitcnt lgkmcnt(0)
	v_mfma_f32_32x32x16_bf16 v[16:31], v[2:5], v[86:89], v[16:31]
	v_mfma_f32_32x32x16_bf16 v[16:31], v[6:9], v[90:93], v[16:31]
	v_mfma_f32_32x32x16_bf16 v[16:31], v[10:13], v[94:97], v[16:31]
	v_mfma_f32_32x32x16_bf16 v[16:31], v[80:83], v[98:101], v[16:31]

; #define PH_COMMON() KARGS(A); const int tid = ltid(), lane = tid & 63, wave = __builtin_amdgcn_readfirstlane(tid >> 6); const int G = gridDim.x, gw = blockIdx.x * NWAVES + wave, ngw = G * NWAVES; \
;     unsigned char* ws = A->ws; (void)lane; (void)gw; (void)ngw; (void)ws
; __global__ void __launch_bounds__(NWAVES * 64, 2) fwd_kernel(Args args_) {
;     ...
;         case 1: {
;             PH_COMMON(); bf16_t* Z = (bf16_t*)(ws + WS_Z);
;             const float* lng = A->in[3] + (size_t)l * 1024; const float* lnb = A->in[4] + (size_t)l * 1024;
;             const float* wsp = A->in[5] + (size_t)l * 8 * 128 * 128; const float* bsp = A->in[6] + (size_t)l * 1024;
;             {
;                 const int u0 = blockIdx.x, u1 = u0 + 256, u2 = u0 + 512, u3 = u0 + 768; GMLP_DECL(a_); GMLP_DECL(b_);
;                 GMLP_LOAD(a_, Z, wsp, u0 >> 3, u0 & 7); GMLP_LOAD(b_, Z, wsp, u1 >> 3, u1 & 7);
.LBB0_421:
	s_andn2_b64 vcc, exec, s[0:1]
	s_cbranch_vccnz .LBB0_423
	s_load_dwordx2 s[6:7], s[92:93], 0x88
	s_load_dwordx8 s[8:15], s[92:93], 0x18
	v_readlane_b32 s22, v255, 18
	v_readlane_b32 s23, v255, 13
	v_lshrrev_b32_e32 v8, 2, v218
	v_and_b32_e32 v9, 3, v218
	v_and_b32_e32 v10, 15, v222
	v_lshrrev_b32_e32 v11, 4, v222
	v_lshrrev_b32_e32 v12, 6, v218
	v_lshl_add_u32 v13, v12, 4, v10
	s_lshl_b32 s16, s22, 1
	s_add_i32 s17, s16, 0x800
	v_mul_u32_u24_e32 v1, 0x3800, v8
	v_lshl_add_u32 v1, v9, 6, v1
	v_add_u32_e32 v1, s17, v1
	v_mul_u32_u24_e32 v2, 0x3800, v13
	v_lshl_add_u32 v2, v11, 3, v2
	v_add_u32_e32 v2, s16, v2
	v_mul_u32_u24_e32 v3, 0x2200, v9
	v_lshl_add_u32 v3, v8, 1, v3
	v_mul_u32_u24_e32 v4, 0x110, v10
	v_lshl_add_u32 v4, v11, 4, v4
	v_mul_u32_u24_e32 v5, 0x110, v13
	v_lshl_add_u32 v5, v11, 4, v5
	v_add_u32_e32 v5, 0x11000, v5
	v_mul_u32_u24_e32 v6, 0x110, v8
	v_lshl_add_u32 v6, v9, 6, v6
	v_add_u32_e32 v6, 0x11000, v6
	v_lshlrev_b32_e32 v14, 7, v9
	v_lshlrev_b32_e32 v15, 2, v13
	v_lshl_add_u32 v12, v8, 9, v14
	v_lshlrev_b32_e32 v13, 5, v9
	v_sub_u32_e32 v13, v8, v13
	s_waitcnt lgkmcnt(0)
	s_add_u32 s6, s6, 0x11400000
	s_addc_u32 s7, s7, 0
	s_lshl_b32 s16, s74, 12
	s_lshl_b32 s17, s22, 2
	s_add_u32 s16, s16, s17
	s_add_u32 s8, s8, s16
	s_addc_u32 s9, s9, 0
	s_add_u32 s10, s10, s16
	s_addc_u32 s11, s11, 0
	s_add_u32 s14, s14, s16
	s_addc_u32 s15, s15, 0
	s_lshl_b32 s16, s74, 19
	s_lshl_b32 s17, s22, 9
	s_add_u32 s16, s16, s17
	s_add_u32 s12, s12, s16
	s_addc_u32 s13, s13, 0
	s_mul_i32 s18, s23, 0x3800
	s_add_u32 s20, s6, s18
	s_addc_u32 s21, s7, 0
	s_add_u32 s24, s20, 0x3800000
	s_addc_u32 s25, s21, 0
	s_add_u32 s26, s24, 0x3800000
	s_addc_u32 s27, s25, 0
	s_add_u32 s28, s26, 0x3800000
	s_addc_u32 s29, s27, 0
	global_load_dwordx4 v[160:163], v12, s[12:13]
	global_load_dwordx4 v[164:167], v12, s[12:13] offset:16
	global_load_dwordx4 v[168:171], v12, s[12:13] offset:32
	global_load_dwordx4 v[172:175], v12, s[12:13] offset:48
	global_load_dwordx4 v[176:179], v12, s[12:13] offset:64
	global_load_dwordx4 v[180:183], v12, s[12:13] offset:80
	global_load_dwordx4 v[184:187], v12, s[12:13] offset:96
	global_load_dwordx4 v[188:191], v12, s[12:13] offset:112
	global_load_dwordx4 v[16:19], v14, s[8:9]
	global_load_dwordx4 v[20:23], v14, s[8:9] offset:16
	global_load_dwordx4 v[24:27], v14, s[8:9] offset:32
	global_load_dwordx4 v[28:31], v14, s[8:9] offset:48
	global_load_dwordx4 v[32:35], v14, s[8:9] offset:64
	global_load_dwordx4 v[36:39], v14, s[8:9] offset:80
	global_load_dwordx4 v[40:43], v14, s[8:9] offset:96
	global_load_dwordx4 v[44:47], v14, s[8:9] offset:112
	global_load_dwordx4 v[48:51], v14, s[10:11]
	global_load_dwordx4 v[52:55], v14, s[10:11] offset:16
	global_load_dwordx4 v[56:59], v14, s[10:11] offset:32
	global_load_dwordx4 v[60:63], v14, s[10:11] offset:48
	global_load_dwordx4 v[64:67], v14, s[10:11] offset:64
	global_load_dwordx4 v[68:71], v14, s[10:11] offset:80
	global_load_dwordx4 v[72:75], v14, s[10:11] offset:96
	global_load_dwordx4 v[76:79], v14, s[10:11] offset:112
	global_load_dword v7, v15, s[14:15]
	global_load_dwordx4 v[96:99], v1, s[20:21]
	global_load_dwordx4 v[100:103], v1, s[20:21] offset:16
	global_load_dwordx4 v[104:107], v1, s[20:21] offset:32
	global_load_dwordx4 v[108:111], v1, s[20:21] offset:48
	global_load_dwordx2 v[112:113], v2, s[20:21]
	global_load_dwordx2 v[114:115], v2, s[20:21] offset:32
	global_load_dwordx2 v[116:117], v2, s[20:21] offset:64
	global_load_dwordx2 v[118:119], v2, s[20:21] offset:96
	global_load_dwordx2 v[120:121], v2, s[20:21] offset:128
	global_load_dwordx2 v[122:123], v2, s[20:21] offset:160
	global_load_dwordx2 v[124:125], v2, s[20:21] offset:192
	global_load_dwordx2 v[126:127], v2, s[20:21] offset:224
	global_load_dwordx4 v[128:131], v1, s[24:25]
	global_load_dwordx4 v[132:135], v1, s[24:25] offset:16
	global_load_dwordx4 v[136:139], v1, s[24:25] offset:32
	global_load_dwordx4 v[140:143], v1, s[24:25] offset:48
	global_load_dwordx2 v[144:145], v2, s[24:25]
	global_load_dwordx2 v[146:147], v2, s[24:25] offset:32
	global_load_dwordx2 v[148:149], v2, s[24:25] offset:64
	global_load_dwordx2 v[150:151], v2, s[24:25] offset:96
	global_load_dwordx2 v[152:153], v2, s[24:25] offset:128
	global_load_dwordx2 v[154:155], v2, s[24:25] offset:160
	global_load_dwordx2 v[156:157], v2, s[24:25] offset:192
	global_load_dwordx2 v[158:159], v2, s[24:25] offset:224
	s_waitcnt vmcnt(41)
; #define LAS __attribute__((address_space(3)))
; __device__ __forceinline__ unsigned pk2(float lo, float hi) { return pg8::cvt_pk_bf16(lo, hi); }
; __device__ __forceinline__ void gmlp_unit(LAS unsigned char* lds, bf16_t* Z, const float* ln_g, const float* ln_b, const float* b_s, const u32x2 (&uu)[8], const f32x4 (&wreg)[8], const u32x4 (&raw)[4], int cidx, int g, int tid) {
;     ...
;         const int j = tid >> 2, cq = (tid & 3) * 32;
;         float x[32];
; #pragma unroll
;         for (int q = 0; q < 4; ++q)
; #pragma unroll
;             for (int e = 0; e < 4; ++e) { x[8 * q + 2 * e] = bf_lo(raw[q][e]); x[8 * q + 2 * e + 1] = bf_hi(raw[q][e]); }
;         float s = 0.f;
; #pragma unroll
;         for (int c = 0; c < 32; ++c) s += x[c];
;         s += __shfl_xor(s, 1); s += __shfl_xor(s, 2);
;         const float mean = s * (1.f / 128.f); float q2 = 0.f;
; #pragma unroll
;         for (int c = 0; c < 32; ++c) { x[c] -= mean; q2 += x[c] * x[c]; }
;         q2 += __shfl_xor(q2, 1); q2 += __shfl_xor(q2, 2);
;         const float rstd = __builtin_amdgcn_rsqf(q2 * (1.f / 128.f) + EPS);
;     ...
;         const int i = tid >> 2, jq = (tid & 3) * 32;
; #pragma unroll
;         for (int q = 0; q < 4; ++q) { f32x4 a = wreg[2 * q], b = wreg[2 * q + 1];
;             const int j0 = jq + 8 * q;
; #pragma unroll
;             for (int e = 0; e < 4; ++e) { if (j0 + e > i) a[e] = 0.f; if (j0 + 4 + e > i) b[e] = 0.f; }
;             u32x4 w; w.x = pk2(a[0], a[1]); w.y = pk2(a[2], a[3]); w.z = pk2(b[0], b[1]); w.w = pk2(b[2], b[3]);
;             *(LAS u32x4*)(WS + i * LSTR + j0 * 2) = w; }
;     }
	v_cmp_gt_i32_e64 s[30:31], 0, v13
	v_cmp_gt_i32_e64 s[34:35], 1, v13
	v_cmp_gt_i32_e64 s[36:37], 2, v13
	v_cmp_gt_i32_e64 s[38:39], 3, v13
	v_cmp_gt_i32_e64 s[40:41], 4, v13
	v_cmp_gt_i32_e64 s[42:43], 5, v13
	v_cmp_gt_i32_e64 s[44:45], 6, v13
	v_cmp_gt_i32_e64 s[46:47], 7, v13
	v_cmp_gt_i32_e64 s[48:49], 8, v13
	v_cmp_gt_i32_e64 s[50:51], 9, v13
	v_cmp_gt_i32_e64 s[52:53], 10, v13
	v_cmp_gt_i32_e64 s[54:55], 11, v13
	v_cmp_gt_i32_e64 s[56:57], 12, v13
	v_cmp_gt_i32_e64 s[58:59], 13, v13
	v_cmp_gt_i32_e64 s[60:61], 14, v13
	v_cmp_gt_i32_e64 s[62:63], 15, v13
	v_cndmask_b32_e64 v160, v160, 0, s[30:31]
	v_cndmask_b32_e64 v161, v161, 0, s[34:35]
	v_cndmask_b32_e64 v162, v162, 0, s[36:37]
	v_cndmask_b32_e64 v163, v163, 0, s[38:39]
	v_cndmask_b32_e64 v164, v164, 0, s[40:41]
	v_cndmask_b32_e64 v165, v165, 0, s[42:43]
	v_cndmask_b32_e64 v166, v166, 0, s[44:45]
	v_cndmask_b32_e64 v167, v167, 0, s[46:47]
	v_cndmask_b32_e64 v168, v168, 0, s[48:49]
	v_cndmask_b32_e64 v169, v169, 0, s[50:51]
	v_cndmask_b32_e64 v170, v170, 0, s[52:53]
	v_cndmask_b32_e64 v171, v171, 0, s[54:55]
	v_cndmask_b32_e64 v172, v172, 0, s[56:57]
	v_cndmask_b32_e64 v173, v173, 0, s[58:59]
	v_cndmask_b32_e64 v174, v174, 0, s[60:61]
	v_cndmask_b32_e64 v175, v175, 0, s[62:63]
	v_cmp_gt_i32_e64 s[30:31], 16, v13
	v_cmp_gt_i32_e64 s[34:35], 17, v13
	v_cmp_gt_i32_e64 s[36:37], 18, v13
	v_cmp_gt_i32_e64 s[38:39], 19, v13
	v_cmp_gt_i32_e64 s[40:41], 20, v13
	v_cmp_gt_i32_e64 s[42:43], 21, v13
	v_cmp_gt_i32_e64 s[44:45], 22, v13
	v_cmp_gt_i32_e64 s[46:47], 23, v13
	v_cmp_gt_i32_e64 s[48:49], 24, v13
	v_cmp_gt_i32_e64 s[50:51], 25, v13
	v_cmp_gt_i32_e64 s[52:53], 26, v13
	v_cmp_gt_i32_e64 s[54:55], 27, v13
	v_cmp_gt_i32_e64 s[56:57], 28, v13
	v_cmp_gt_i32_e64 s[58:59], 29, v13
	v_cmp_gt_i32_e64 s[60:61], 30, v13
	v_cmp_gt_i32_e64 s[62:63], 31, v13
	v_cndmask_b32_e64 v176, v176, 0, s[30:31]
	v_cndmask_b32_e64 v177, v177, 0, s[34:35]
	v_cndmask_b32_e64 v178, v178, 0, s[36:37]
	v_cndmask_b32_e64 v179, v179, 0, s[38:39]
	v_cndmask_b32_e64 v180, v180, 0, s[40:41]
	v_cndmask_b32_e64 v181, v181, 0, s[42:43]
	v_cndmask_b32_e64 v182, v182, 0, s[44:45]
	v_cndmask_b32_e64 v183, v183, 0, s[46:47]
	v_cndmask_b32_e64 v184, v184, 0, s[48:49]
	v_cndmask_b32_e64 v185, v185, 0, s[50:51]
	v_cndmask_b32_e64 v186, v186, 0, s[52:53]
	v_cndmask_b32_e64 v187, v187, 0, s[54:55]
	v_cndmask_b32_e64 v188, v188, 0, s[56:57]
	v_cndmask_b32_e64 v189, v189, 0, s[58:59]
	v_cndmask_b32_e64 v190, v190, 0, s[60:61]
	v_cndmask_b32_e64 v191, v191, 0, s[62:63]
	v_cvt_pk_bf16_f32 v160, v160, v161
	v_cvt_pk_bf16_f32 v161, v162, v163
	v_cvt_pk_bf16_f32 v162, v164, v165
	v_cvt_pk_bf16_f32 v163, v166, v167
	v_cvt_pk_bf16_f32 v164, v168, v169
	v_cvt_pk_bf16_f32 v165, v170, v171
	v_cvt_pk_bf16_f32 v166, v172, v173
	v_cvt_pk_bf16_f32 v167, v174, v175
	v_cvt_pk_bf16_f32 v168, v176, v177
	v_cvt_pk_bf16_f32 v169, v178, v179
	v_cvt_pk_bf16_f32 v170, v180, v181
	v_cvt_pk_bf16_f32 v171, v182, v183
	v_cvt_pk_bf16_f32 v172, v184, v185
	v_cvt_pk_bf16_f32 v173, v186, v187
	v_cvt_pk_bf16_f32 v174, v188, v189
	v_cvt_pk_bf16_f32 v175, v190, v191
	ds_write_b128 v6, v[160:163]
	ds_write_b128 v6, v[164:167] offset:16
	ds_write_b128 v6, v[168:171] offset:32
	ds_write_b128 v6, v[172:175] offset:48
	s_waitcnt vmcnt(20)
	v_lshlrev_b32_e32 v160, 16, v96
	v_and_b32_e32 v161, 0xffff0000, v96
	v_lshlrev_b32_e32 v162, 16, v97
	v_and_b32_e32 v163, 0xffff0000, v97
	v_lshlrev_b32_e32 v164, 16, v98
	v_and_b32_e32 v165, 0xffff0000, v98
	v_lshlrev_b32_e32 v166, 16, v99
	v_and_b32_e32 v167, 0xffff0000, v99
	v_lshlrev_b32_e32 v168, 16, v100
	v_and_b32_e32 v169, 0xffff0000, v100
	v_lshlrev_b32_e32 v170, 16, v101
	v_and_b32_e32 v171, 0xffff0000, v101
	v_lshlrev_b32_e32 v172, 16, v102
	v_and_b32_e32 v173, 0xffff0000, v102
	v_lshlrev_b32_e32 v174, 16, v103
	v_and_b32_e32 v175, 0xffff0000, v103
	v_lshlrev_b32_e32 v176, 16, v104
	v_and_b32_e32 v177, 0xffff0000, v104
	v_lshlrev_b32_e32 v178, 16, v105
	v_and_b32_e32 v179, 0xffff0000, v105
	v_lshlrev_b32_e32 v180, 16, v106
	v_and_b32_e32 v181, 0xffff0000, v106
	v_lshlrev_b32_e32 v182, 16, v107
	v_and_b32_e32 v183, 0xffff0000, v107
	v_lshlrev_b32_e32 v184, 16, v108
	v_and_b32_e32 v185, 0xffff0000, v108
	v_lshlrev_b32_e32 v186, 16, v109
	v_and_b32_e32 v187, 0xffff0000, v109
	v_lshlrev_b32_e32 v188, 16, v110
	v_and_b32_e32 v189, 0xffff0000, v110
	v_lshlrev_b32_e32 v190, 16, v111
	v_and_b32_e32 v191, 0xffff0000, v111
	v_add_f32_e32 v8, v160, v164
	v_add_f32_e32 v9, v161, v165
	v_add_f32_e32 v10, v162, v166
	v_add_f32_e32 v11, v163, v167
	v_add_f32_e32 v8, v8, v168
	v_add_f32_e32 v9, v9, v169
	v_add_f32_e32 v10, v10, v170
	v_add_f32_e32 v11, v11, v171
	v_add_f32_e32 v8, v8, v172
	v_add_f32_e32 v9, v9, v173
	v_add_f32_e32 v10, v10, v174
	v_add_f32_e32 v11, v11, v175
	v_add_f32_e32 v8, v8, v176
	v_add_f32_e32 v9, v9, v177
	v_add_f32_e32 v10, v10, v178
	v_add_f32_e32 v11, v11, v179
	v_add_f32_e32 v8, v8, v180
	v_add_f32_e32 v9, v9, v181
	v_add_f32_e32 v10, v10, v182
	v_add_f32_e32 v11, v11, v183
	v_add_f32_e32 v8, v8, v184
	v_add_f32_e32 v9, v9, v185
	v_add_f32_e32 v10, v10, v186
	v_add_f32_e32 v11, v11, v187
	v_add_f32_e32 v8, v8, v188
	v_add_f32_e32 v9, v9, v189
	v_add_f32_e32 v10, v10, v190
	v_add_f32_e32 v11, v11, v191
	v_add_f32_e32 v8, v8, v9
	v_add_f32_e32 v10, v10, v11
	v_add_f32_e32 v8, v8, v10
	s_nop 1
	v_add_f32_dpp v8, v8, v8 quad_perm:[1,0,3,2] row_mask:0xf bank_mask:0xf
	s_nop 1
	v_add_f32_dpp v8, v8, v8 quad_perm:[2,3,0,1] row_mask:0xf bank_mask:0xf
	v_mul_f32_e32 v8, 0xbc000000, v8
	v_add_f32_e32 v160, v160, v8
	v_add_f32_e32 v161, v161, v8
	v_add_f32_e32 v162, v162, v8
	v_add_f32_e32 v163, v163, v8
; #define LAS __attribute__((address_space(3)))
; __device__ __forceinline__ unsigned f2bf(float f) { unsigned u = __builtin_bit_cast(unsigned, f); return (u + 0x7fffu + ((u >> 16) & 1u)) >> 16; }
; __device__ __forceinline__ void gmlp_unit(LAS unsigned char* lds, bf16_t* Z, const float* ln_g, const float* ln_b, const float* b_s, const u32x2 (&uu)[8], const f32x4 (&wreg)[8], const u32x4 (&raw)[4], int cidx, int g, int tid) {
;     ...
;         s += __shfl_xor(s, 1); s += __shfl_xor(s, 2);
;         const float mean = s * (1.f / 128.f); float q2 = 0.f;
; #pragma unroll
;         for (int c = 0; c < 32; ++c) { x[c] -= mean; q2 += x[c] * x[c]; }
;         q2 += __shfl_xor(q2, 1); q2 += __shfl_xor(q2, 2);
;         const float rstd = __builtin_amdgcn_rsqf(q2 * (1.f / 128.f) + EPS);
;         const float* gp = ln_g + g * 128 + cq; const float* bp = ln_b + g * 128 + cq;
; #pragma unroll
;         for (int c4 = 0; c4 < 8; ++c4) { const f32x4 gg = *(const f32x4*)(gp + 4 * c4), bb = *(const f32x4*)(bp + 4 * c4);
; #pragma unroll
;             for (int e = 0; e < 4; ++e) { const int c = 4 * c4 + e; const float y = x[c] * rstd * gg[e] + bb[e];
;                 *(LAS unsigned short*)(VT + (cq + c) * LSTR + j * 2) = (unsigned short)f2bf(y); } }
	v_add_f32_e32 v164, v164, v8
	v_add_f32_e32 v165, v165, v8
	v_add_f32_e32 v166, v166, v8
	v_add_f32_e32 v167, v167, v8
	v_add_f32_e32 v168, v168, v8
	v_add_f32_e32 v169, v169, v8
	v_add_f32_e32 v170, v170, v8
	v_add_f32_e32 v171, v171, v8
	v_add_f32_e32 v172, v172, v8
	v_add_f32_e32 v173, v173, v8
	v_add_f32_e32 v174, v174, v8
	v_add_f32_e32 v175, v175, v8
	v_add_f32_e32 v176, v176, v8
	v_add_f32_e32 v177, v177, v8
	v_add_f32_e32 v178, v178, v8
	v_add_f32_e32 v179, v179, v8
	v_add_f32_e32 v180, v180, v8
	v_add_f32_e32 v181, v181, v8
	v_add_f32_e32 v182, v182, v8
	v_add_f32_e32 v183, v183, v8
	v_add_f32_e32 v184, v184, v8
	v_add_f32_e32 v185, v185, v8
	v_add_f32_e32 v186, v186, v8
	v_add_f32_e32 v187, v187, v8
	v_add_f32_e32 v188, v188, v8
	v_add_f32_e32 v189, v189, v8
	v_add_f32_e32 v190, v190, v8
	v_add_f32_e32 v191, v191, v8
	v_mul_f32_e32 v8, v160, v160
	v_mul_f32_e32 v9, v161, v161
	v_mul_f32_e32 v10, v162, v162
	v_mul_f32_e32 v11, v163, v163
	v_fmac_f32_e32 v8, v164, v164
	v_fmac_f32_e32 v9, v165, v165
	v_fmac_f32_e32 v10, v166, v166
	v_fmac_f32_e32 v11, v167, v167
	v_fmac_f32_e32 v8, v168, v168
	v_fmac_f32_e32 v9, v169, v169
	v_fmac_f32_e32 v10, v170, v170
	v_fmac_f32_e32 v11, v171, v171
	v_fmac_f32_e32 v8, v172, v172
	v_fmac_f32_e32 v9, v173, v173
	v_fmac_f32_e32 v10, v174, v174
	v_fmac_f32_e32 v11, v175, v175
	v_fmac_f32_e32 v8, v176, v176
	v_fmac_f32_e32 v9, v177, v177
	v_fmac_f32_e32 v10, v178, v178
	v_fmac_f32_e32 v11, v179, v179
	v_fmac_f32_e32 v8, v180, v180
	v_fmac_f32_e32 v9, v181, v181
	v_fmac_f32_e32 v10, v182, v182
	v_fmac_f32_e32 v11, v183, v183
	v_fmac_f32_e32 v8, v184, v184
	v_fmac_f32_e32 v9, v185, v185
	v_fmac_f32_e32 v10, v186, v186
	v_fmac_f32_e32 v11, v187, v187
	v_fmac_f32_e32 v8, v188, v188
	v_fmac_f32_e32 v9, v189, v189
	v_fmac_f32_e32 v10, v190, v190
	v_fmac_f32_e32 v11, v191, v191
	v_add_f32_e32 v8, v8, v9
	v_add_f32_e32 v10, v10, v11
	v_add_f32_e32 v8, v8, v10
	s_nop 1
	v_add_f32_dpp v8, v8, v8 quad_perm:[1,0,3,2] row_mask:0xf bank_mask:0xf
	s_nop 1
	v_add_f32_dpp v8, v8, v8 quad_perm:[2,3,0,1] row_mask:0xf bank_mask:0xf
	v_fmamk_f32 v8, v8, 0x3c000000, v219
	v_rsq_f32_e32 v8, v8
	s_nop 0
	v_mul_f32_e32 v160, v160, v8
	v_fma_f32 v160, v16, v160, v48
	v_bfe_u32 v9, v160, 16, 1
	v_add3_u32 v160, v160, v9, s81
	ds_write_b16_d16_hi v3, v160
	v_mul_f32_e32 v161, v161, v8
	v_fma_f32 v161, v17, v161, v49
	v_bfe_u32 v10, v161, 16, 1
	v_add3_u32 v161, v161, v10, s81
	ds_write_b16_d16_hi v3, v161 offset:272
	v_mul_f32_e32 v162, v162, v8
	v_fma_f32 v162, v18, v162, v50
	v_bfe_u32 v9, v162, 16, 1
	v_add3_u32 v162, v162, v9, s81
	ds_write_b16_d16_hi v3, v162 offset:544
	v_mul_f32_e32 v163, v163, v8
	v_fma_f32 v163, v19, v163, v51
	v_bfe_u32 v10, v163, 16, 1
	v_add3_u32 v163, v163, v10, s81
	ds_write_b16_d16_hi v3, v163 offset:816
	v_mul_f32_e32 v164, v164, v8
	v_fma_f32 v164, v20, v164, v52
	v_bfe_u32 v9, v164, 16, 1
	v_add3_u32 v164, v164, v9, s81
	ds_write_b16_d16_hi v3, v164 offset:1088
	v_mul_f32_e32 v165, v165, v8
	v_fma_f32 v165, v21, v165, v53
	v_bfe_u32 v10, v165, 16, 1
	v_add3_u32 v165, v165, v10, s81
	ds_write_b16_d16_hi v3, v165 offset:1360
	v_mul_f32_e32 v166, v166, v8
	v_fma_f32 v166, v22, v166, v54
	v_bfe_u32 v9, v166, 16, 1
	v_add3_u32 v166, v166, v9, s81
	ds_write_b16_d16_hi v3, v166 offset:1632
	v_mul_f32_e32 v167, v167, v8
	v_fma_f32 v167, v23, v167, v55
	v_bfe_u32 v10, v167, 16, 1
	v_add3_u32 v167, v167, v10, s81
	ds_write_b16_d16_hi v3, v167 offset:1904
	v_mul_f32_e32 v168, v168, v8
	v_fma_f32 v168, v24, v168, v56
	v_bfe_u32 v9, v168, 16, 1
	v_add3_u32 v168, v168, v9, s81
	ds_write_b16_d16_hi v3, v168 offset:2176
	v_mul_f32_e32 v169, v169, v8
	v_fma_f32 v169, v25, v169, v57
	v_bfe_u32 v10, v169, 16, 1
	v_add3_u32 v169, v169, v10, s81
	ds_write_b16_d16_hi v3, v169 offset:2448
	v_mul_f32_e32 v170, v170, v8
	v_fma_f32 v170, v26, v170, v58
	v_bfe_u32 v9, v170, 16, 1
	v_add3_u32 v170, v170, v9, s81
	ds_write_b16_d16_hi v3, v170 offset:2720
	v_mul_f32_e32 v171, v171, v8
	v_fma_f32 v171, v27, v171, v59
	v_bfe_u32 v10, v171, 16, 1
	v_add3_u32 v171, v171, v10, s81
	ds_write_b16_d16_hi v3, v171 offset:2992
	v_mul_f32_e32 v172, v172, v8
	v_fma_f32 v172, v28, v172, v60
	v_bfe_u32 v9, v172, 16, 1
	v_add3_u32 v172, v172, v9, s81
	ds_write_b16_d16_hi v3, v172 offset:3264
	v_mul_f32_e32 v173, v173, v8
	v_fma_f32 v173, v29, v173, v61
	v_bfe_u32 v10, v173, 16, 1
	v_add3_u32 v173, v173, v10, s81
	ds_write_b16_d16_hi v3, v173 offset:3536
	v_mul_f32_e32 v174, v174, v8
	v_fma_f32 v174, v30, v174, v62
	v_bfe_u32 v9, v174, 16, 1
	v_add3_u32 v174, v174, v9, s81
	ds_write_b16_d16_hi v3, v174 offset:3808
	v_mul_f32_e32 v175, v175, v8
	v_fma_f32 v175, v31, v175, v63
	v_bfe_u32 v10, v175, 16, 1
	v_add3_u32 v175, v175, v10, s81
	ds_write_b16_d16_hi v3, v175 offset:4080
	v_mul_f32_e32 v176, v176, v8
	v_fma_f32 v176, v32, v176, v64
	v_bfe_u32 v9, v176, 16, 1
	v_add3_u32 v176, v176, v9, s81
	ds_write_b16_d16_hi v3, v176 offset:4352
	v_mul_f32_e32 v177, v177, v8
	v_fma_f32 v177, v33, v177, v65
	v_bfe_u32 v10, v177, 16, 1
	v_add3_u32 v177, v177, v10, s81
	ds_write_b16_d16_hi v3, v177 offset:4624
	v_mul_f32_e32 v178, v178, v8
	v_fma_f32 v178, v34, v178, v66
	v_bfe_u32 v9, v178, 16, 1
	v_add3_u32 v178, v178, v9, s81
	ds_write_b16_d16_hi v3, v178 offset:4896
	v_mul_f32_e32 v179, v179, v8
	v_fma_f32 v179, v35, v179, v67
	v_bfe_u32 v10, v179, 16, 1
	v_add3_u32 v179, v179, v10, s81
	ds_write_b16_d16_hi v3, v179 offset:5168
	v_mul_f32_e32 v180, v180, v8
	v_fma_f32 v180, v36, v180, v68
	v_bfe_u32 v9, v180, 16, 1
	v_add3_u32 v180, v180, v9, s81
	ds_write_b16_d16_hi v3, v180 offset:5440
	v_mul_f32_e32 v181, v181, v8
	v_fma_f32 v181, v37, v181, v69
; #define LAS __attribute__((address_space(3)))
; __device__ __forceinline__ unsigned pk2(float lo, float hi) { return pg8::cvt_pk_bf16(lo, hi); }
; __device__ __forceinline__ void gmlp_unit(LAS unsigned char* lds, bf16_t* Z, const float* ln_g, const float* ln_b, const float* b_s, const u32x2 (&uu)[8], const f32x4 (&wreg)[8], const u32x4 (&raw)[4], int cidx, int g, int tid) {
;     ...
;     const int wv = tid >> 6, lane = tid & 63, fr = lane & 15, fq = lane >> 4;
;     f32x4 acc[8];
; #pragma unroll
;     for (int ct = 0; ct < 8; ++ct) acc[ct] = (f32x4){0.f, 0.f, 0.f, 0.f};
; #pragma unroll
;     for (int ks = 0; ks < 4; ++ks) {
;         const bf16x8 bw = *(const LAS bf16x8*)(WS + (wv * 16 + fr) * LSTR + (ks * 32 + fq * 8) * 2);
; #pragma unroll
;         for (int ct = 0; ct < 8; ++ct) { const bf16x8 av = *(const LAS bf16x8*)(VT + (ct * 16 + fr) * LSTR + (ks * 32 + fq * 8) * 2);
;             acc[ct] = __builtin_amdgcn_mfma_f32_16x16x32_bf16(av, bw, acc[ct], 0, 0, 0); }
;     }
;     ...
;         const int i = wv * 16 + fr; const float bs = b_s[g * 128 + i];
;         bf16_t* up = Z + (size_t)(row0 + i) * INW + g * 128 + 4 * fq;
; #pragma unroll
;         for (int ct = 0; ct < 8; ++ct) {
;             u32x2 w; w.x = pk2(bf_lo(uu[ct].x) * (acc[ct][0] + bs), bf_hi(uu[ct].x) * (acc[ct][1] + bs)); w.y = pk2(bf_lo(uu[ct].y) * (acc[ct][2] + bs), bf_hi(uu[ct].y) * (acc[ct][3] + bs));
;             *(u32x2*)(up + 16 * ct) = w; }
	v_bfe_u32 v10, v181, 16, 1
	v_add3_u32 v181, v181, v10, s81
	ds_write_b16_d16_hi v3, v181 offset:5712
	v_mul_f32_e32 v182, v182, v8
	v_fma_f32 v182, v38, v182, v70
	v_bfe_u32 v9, v182, 16, 1
	v_add3_u32 v182, v182, v9, s81
	ds_write_b16_d16_hi v3, v182 offset:5984
	v_mul_f32_e32 v183, v183, v8
	v_fma_f32 v183, v39, v183, v71
	v_bfe_u32 v10, v183, 16, 1
	v_add3_u32 v183, v183, v10, s81
	ds_write_b16_d16_hi v3, v183 offset:6256
	v_mul_f32_e32 v184, v184, v8
	v_fma_f32 v184, v40, v184, v72
	v_bfe_u32 v9, v184, 16, 1
	v_add3_u32 v184, v184, v9, s81
	ds_write_b16_d16_hi v3, v184 offset:6528
	v_mul_f32_e32 v185, v185, v8
	v_fma_f32 v185, v41, v185, v73
	v_bfe_u32 v10, v185, 16, 1
	v_add3_u32 v185, v185, v10, s81
	ds_write_b16_d16_hi v3, v185 offset:6800
	v_mul_f32_e32 v186, v186, v8
	v_fma_f32 v186, v42, v186, v74
	v_bfe_u32 v9, v186, 16, 1
	v_add3_u32 v186, v186, v9, s81
	ds_write_b16_d16_hi v3, v186 offset:7072
	v_mul_f32_e32 v187, v187, v8
	v_fma_f32 v187, v43, v187, v75
	v_bfe_u32 v10, v187, 16, 1
	v_add3_u32 v187, v187, v10, s81
	ds_write_b16_d16_hi v3, v187 offset:7344
	v_mul_f32_e32 v188, v188, v8
	v_fma_f32 v188, v44, v188, v76
	v_bfe_u32 v9, v188, 16, 1
	v_add3_u32 v188, v188, v9, s81
	ds_write_b16_d16_hi v3, v188 offset:7616
	v_mul_f32_e32 v189, v189, v8
	v_fma_f32 v189, v45, v189, v77
	v_bfe_u32 v10, v189, 16, 1
	v_add3_u32 v189, v189, v10, s81
	ds_write_b16_d16_hi v3, v189 offset:7888
	v_mul_f32_e32 v190, v190, v8
	v_fma_f32 v190, v46, v190, v78
	v_bfe_u32 v9, v190, 16, 1
	v_add3_u32 v190, v190, v9, s81
	ds_write_b16_d16_hi v3, v190 offset:8160
	v_mul_f32_e32 v191, v191, v8
	v_fma_f32 v191, v47, v191, v79
	v_bfe_u32 v10, v191, 16, 1
	v_add3_u32 v191, v191, v10, s81
	ds_write_b16_d16_hi v3, v191 offset:8432
	s_waitcnt lgkmcnt(0)
	s_barrier
	ds_read_b128 v[80:83], v5
	ds_read_b128 v[84:87], v5 offset:64
	ds_read_b128 v[88:91], v5 offset:128
	ds_read_b128 v[92:95], v5 offset:192
	ds_read_b128 v[200:203], v4
	ds_read_b128 v[204:207], v4 offset:4352
	ds_read_b128 v[208:211], v4 offset:8704
	ds_read_b128 v[212:215], v4 offset:13056
	ds_read_b128 v[224:227], v4 offset:17408
	ds_read_b128 v[228:231], v4 offset:21760
	ds_read_b128 v[232:235], v4 offset:26112
	ds_read_b128 v[236:239], v4 offset:30464
	s_waitcnt lgkmcnt(7)
	v_mfma_f32_16x16x32_bf16 v[160:163], v[200:203], v[80:83], 0
	ds_read_b128 v[200:203], v4 offset:64
	s_waitcnt lgkmcnt(7)
	v_mfma_f32_16x16x32_bf16 v[164:167], v[204:207], v[80:83], 0
	ds_read_b128 v[204:207], v4 offset:4416
	s_waitcnt lgkmcnt(7)
	v_mfma_f32_16x16x32_bf16 v[168:171], v[208:211], v[80:83], 0
	ds_read_b128 v[208:211], v4 offset:8768
	s_waitcnt lgkmcnt(7)
	v_mfma_f32_16x16x32_bf16 v[172:175], v[212:215], v[80:83], 0
	ds_read_b128 v[212:215], v4 offset:13120
	s_waitcnt lgkmcnt(7)
	v_mfma_f32_16x16x32_bf16 v[176:179], v[224:227], v[80:83], 0
	ds_read_b128 v[224:227], v4 offset:17472
	s_waitcnt lgkmcnt(7)
	v_mfma_f32_16x16x32_bf16 v[180:183], v[228:231], v[80:83], 0
	ds_read_b128 v[228:231], v4 offset:21824
	s_waitcnt lgkmcnt(7)
	v_mfma_f32_16x16x32_bf16 v[184:187], v[232:235], v[80:83], 0
	ds_read_b128 v[232:235], v4 offset:26176
	s_waitcnt lgkmcnt(7)
	v_mfma_f32_16x16x32_bf16 v[188:191], v[236:239], v[80:83], 0
	ds_read_b128 v[236:239], v4 offset:30528
	s_waitcnt lgkmcnt(7)
	v_mfma_f32_16x16x32_bf16 v[160:163], v[200:203], v[84:87], v[160:163]
	ds_read_b128 v[200:203], v4 offset:128
	s_waitcnt lgkmcnt(7)
	v_mfma_f32_16x16x32_bf16 v[164:167], v[204:207], v[84:87], v[164:167]
	ds_read_b128 v[204:207], v4 offset:4480
	s_waitcnt lgkmcnt(7)
	v_mfma_f32_16x16x32_bf16 v[168:171], v[208:211], v[84:87], v[168:171]
	ds_read_b128 v[208:211], v4 offset:8832
	s_waitcnt lgkmcnt(7)
	v_mfma_f32_16x16x32_bf16 v[172:175], v[212:215], v[84:87], v[172:175]
	ds_read_b128 v[212:215], v4 offset:13184
	s_waitcnt lgkmcnt(7)
	v_mfma_f32_16x16x32_bf16 v[176:179], v[224:227], v[84:87], v[176:179]
	ds_read_b128 v[224:227], v4 offset:17536
	s_waitcnt lgkmcnt(7)
	v_mfma_f32_16x16x32_bf16 v[180:183], v[228:231], v[84:87], v[180:183]
	ds_read_b128 v[228:231], v4 offset:21888
	s_waitcnt lgkmcnt(7)
	v_mfma_f32_16x16x32_bf16 v[184:187], v[232:235], v[84:87], v[184:187]
	ds_read_b128 v[232:235], v4 offset:26240
	s_waitcnt lgkmcnt(7)
	v_mfma_f32_16x16x32_bf16 v[188:191], v[236:239], v[84:87], v[188:191]
	ds_read_b128 v[236:239], v4 offset:30592
	s_waitcnt lgkmcnt(7)
	v_mfma_f32_16x16x32_bf16 v[160:163], v[200:203], v[88:91], v[160:163]
	ds_read_b128 v[200:203], v4 offset:192
	s_waitcnt lgkmcnt(7)
	v_mfma_f32_16x16x32_bf16 v[164:167], v[204:207], v[88:91], v[164:167]
	ds_read_b128 v[204:207], v4 offset:4544
	s_waitcnt lgkmcnt(7)
	v_mfma_f32_16x16x32_bf16 v[168:171], v[208:211], v[88:91], v[168:171]
	ds_read_b128 v[208:211], v4 offset:8896
	s_waitcnt lgkmcnt(7)
	v_mfma_f32_16x16x32_bf16 v[172:175], v[212:215], v[88:91], v[172:175]
	ds_read_b128 v[212:215], v4 offset:13248
	s_waitcnt lgkmcnt(7)
	v_mfma_f32_16x16x32_bf16 v[176:179], v[224:227], v[88:91], v[176:179]
	ds_read_b128 v[224:227], v4 offset:17600
	s_waitcnt lgkmcnt(7)
	v_mfma_f32_16x16x32_bf16 v[180:183], v[228:231], v[88:91], v[180:183]
	ds_read_b128 v[228:231], v4 offset:21952
	s_waitcnt lgkmcnt(7)
	v_mfma_f32_16x16x32_bf16 v[184:187], v[232:235], v[88:91], v[184:187]
	ds_read_b128 v[232:235], v4 offset:26304
	s_waitcnt lgkmcnt(7)
	v_mfma_f32_16x16x32_bf16 v[188:191], v[236:239], v[88:91], v[188:191]
	ds_read_b128 v[236:239], v4 offset:30656
	s_waitcnt lgkmcnt(7)
	v_mfma_f32_16x16x32_bf16 v[160:163], v[200:203], v[92:95], v[160:163]
	s_waitcnt lgkmcnt(6)
	v_mfma_f32_16x16x32_bf16 v[164:167], v[204:207], v[92:95], v[164:167]
	s_waitcnt lgkmcnt(5)
; __device__ __forceinline__ unsigned pk2(float lo, float hi) { return pg8::cvt_pk_bf16(lo, hi); }
; __device__ __forceinline__ void gmlp_unit(LAS unsigned char* lds, bf16_t* Z, const float* ln_g, const float* ln_b, const float* b_s, const u32x2 (&uu)[8], const f32x4 (&wreg)[8], const u32x4 (&raw)[4], int cidx, int g, int tid) {
;     ...
;     {
;         const int i = wv * 16 + fr; const float bs = b_s[g * 128 + i];
;         bf16_t* up = Z + (size_t)(row0 + i) * INW + g * 128 + 4 * fq;
; #pragma unroll
;         for (int ct = 0; ct < 8; ++ct) {
;             u32x2 w; w.x = pk2(bf_lo(uu[ct].x) * (acc[ct][0] + bs), bf_hi(uu[ct].x) * (acc[ct][1] + bs)); w.y = pk2(bf_lo(uu[ct].y) * (acc[ct][2] + bs), bf_hi(uu[ct].y) * (acc[ct][3] + bs));
;             *(u32x2*)(up + 16 * ct) = w; }
;     }
	v_mfma_f32_16x16x32_bf16 v[168:171], v[208:211], v[92:95], v[168:171]
	s_waitcnt lgkmcnt(4)
	v_mfma_f32_16x16x32_bf16 v[172:175], v[212:215], v[92:95], v[172:175]
	s_waitcnt lgkmcnt(3)
	v_mfma_f32_16x16x32_bf16 v[176:179], v[224:227], v[92:95], v[176:179]
	s_waitcnt lgkmcnt(2)
	v_mfma_f32_16x16x32_bf16 v[180:183], v[228:231], v[92:95], v[180:183]
	s_waitcnt lgkmcnt(1)
	v_mfma_f32_16x16x32_bf16 v[184:187], v[232:235], v[92:95], v[184:187]
	s_waitcnt lgkmcnt(0)
	v_mfma_f32_16x16x32_bf16 v[188:191], v[236:239], v[92:95], v[188:191]
	s_waitcnt vmcnt(12)
	v_add_f32_e32 v160, v160, v7
	v_add_f32_e32 v161, v161, v7
	v_add_f32_e32 v162, v162, v7
	v_add_f32_e32 v163, v163, v7
	v_lshlrev_b32_e32 v8, 16, v112
	v_and_b32_e32 v9, 0xffff0000, v112
	v_lshlrev_b32_e32 v10, 16, v113
	v_and_b32_e32 v11, 0xffff0000, v113
	v_mul_f32_e32 v160, v8, v160
	v_mul_f32_e32 v161, v9, v161
	v_mul_f32_e32 v162, v10, v162
	v_mul_f32_e32 v163, v11, v163
	v_cvt_pk_bf16_f32 v12, v160, v161
	v_cvt_pk_bf16_f32 v13, v162, v163
	global_store_dwordx2 v2, v[12:13], s[20:21]
	s_nop 0
	v_add_f32_e32 v164, v164, v7
	v_add_f32_e32 v165, v165, v7
	v_add_f32_e32 v166, v166, v7
	v_add_f32_e32 v167, v167, v7
	v_lshlrev_b32_e32 v8, 16, v114
	v_and_b32_e32 v9, 0xffff0000, v114
	v_lshlrev_b32_e32 v10, 16, v115
	v_and_b32_e32 v11, 0xffff0000, v115
	v_mul_f32_e32 v164, v8, v164
	v_mul_f32_e32 v165, v9, v165
	v_mul_f32_e32 v166, v10, v166
	v_mul_f32_e32 v167, v11, v167
	v_cvt_pk_bf16_f32 v12, v164, v165
	v_cvt_pk_bf16_f32 v13, v166, v167
	global_store_dwordx2 v2, v[12:13], s[20:21] offset:32
	s_nop 0
	v_add_f32_e32 v168, v168, v7
	v_add_f32_e32 v169, v169, v7
	v_add_f32_e32 v170, v170, v7
	v_add_f32_e32 v171, v171, v7
	v_lshlrev_b32_e32 v8, 16, v116
	v_and_b32_e32 v9, 0xffff0000, v116
	v_lshlrev_b32_e32 v10, 16, v117
	v_and_b32_e32 v11, 0xffff0000, v117
	v_mul_f32_e32 v168, v8, v168
	v_mul_f32_e32 v169, v9, v169
	v_mul_f32_e32 v170, v10, v170
	v_mul_f32_e32 v171, v11, v171
	v_cvt_pk_bf16_f32 v12, v168, v169
	v_cvt_pk_bf16_f32 v13, v170, v171
	global_store_dwordx2 v2, v[12:13], s[20:21] offset:64
	s_nop 0
	v_add_f32_e32 v172, v172, v7
	v_add_f32_e32 v173, v173, v7
	v_add_f32_e32 v174, v174, v7
	v_add_f32_e32 v175, v175, v7
	v_lshlrev_b32_e32 v8, 16, v118
	v_and_b32_e32 v9, 0xffff0000, v118
	v_lshlrev_b32_e32 v10, 16, v119
	v_and_b32_e32 v11, 0xffff0000, v119
	v_mul_f32_e32 v172, v8, v172
	v_mul_f32_e32 v173, v9, v173
	v_mul_f32_e32 v174, v10, v174
	v_mul_f32_e32 v175, v11, v175
	v_cvt_pk_bf16_f32 v12, v172, v173
	v_cvt_pk_bf16_f32 v13, v174, v175
	global_store_dwordx2 v2, v[12:13], s[20:21] offset:96
	s_nop 0
	v_add_f32_e32 v176, v176, v7
	v_add_f32_e32 v177, v177, v7
	v_add_f32_e32 v178, v178, v7
	v_add_f32_e32 v179, v179, v7
	v_lshlrev_b32_e32 v8, 16, v120
	v_and_b32_e32 v9, 0xffff0000, v120
	v_lshlrev_b32_e32 v10, 16, v121
	v_and_b32_e32 v11, 0xffff0000, v121
	v_mul_f32_e32 v176, v8, v176
	v_mul_f32_e32 v177, v9, v177
	v_mul_f32_e32 v178, v10, v178
	v_mul_f32_e32 v179, v11, v179
	v_cvt_pk_bf16_f32 v12, v176, v177
	v_cvt_pk_bf16_f32 v13, v178, v179
	global_store_dwordx2 v2, v[12:13], s[20:21] offset:128
	s_nop 0
	v_add_f32_e32 v180, v180, v7
	v_add_f32_e32 v181, v181, v7
	v_add_f32_e32 v182, v182, v7
	v_add_f32_e32 v183, v183, v7
	v_lshlrev_b32_e32 v8, 16, v122
	v_and_b32_e32 v9, 0xffff0000, v122
	v_lshlrev_b32_e32 v10, 16, v123
	v_and_b32_e32 v11, 0xffff0000, v123
	v_mul_f32_e32 v180, v8, v180
	v_mul_f32_e32 v181, v9, v181
	v_mul_f32_e32 v182, v10, v182
	v_mul_f32_e32 v183, v11, v183
	v_cvt_pk_bf16_f32 v12, v180, v181
	v_cvt_pk_bf16_f32 v13, v182, v183
	global_store_dwordx2 v2, v[12:13], s[20:21] offset:160
	s_nop 0
	v_add_f32_e32 v184, v184, v7
	v_add_f32_e32 v185, v185, v7
	v_add_f32_e32 v186, v186, v7
	v_add_f32_e32 v187, v187, v7
	v_lshlrev_b32_e32 v8, 16, v124
	v_and_b32_e32 v9, 0xffff0000, v124
	v_lshlrev_b32_e32 v10, 16, v125
	v_and_b32_e32 v11, 0xffff0000, v125
	v_mul_f32_e32 v184, v8, v184
	v_mul_f32_e32 v185, v9, v185
	v_mul_f32_e32 v186, v10, v186
	v_mul_f32_e32 v187, v11, v187
	v_cvt_pk_bf16_f32 v12, v184, v185
	v_cvt_pk_bf16_f32 v13, v186, v187
	global_store_dwordx2 v2, v[12:13], s[20:21] offset:192
	s_nop 0
	v_add_f32_e32 v188, v188, v7
	v_add_f32_e32 v189, v189, v7
	v_add_f32_e32 v190, v190, v7
	v_add_f32_e32 v191, v191, v7
	v_lshlrev_b32_e32 v8, 16, v126
	v_and_b32_e32 v9, 0xffff0000, v126
	v_lshlrev_b32_e32 v10, 16, v127
	v_and_b32_e32 v11, 0xffff0000, v127
	v_mul_f32_e32 v188, v8, v188
	v_mul_f32_e32 v189, v9, v189
	v_mul_f32_e32 v190, v10, v190
	v_mul_f32_e32 v191, v11, v191
	v_cvt_pk_bf16_f32 v12, v188, v189
	v_cvt_pk_bf16_f32 v13, v190, v191
	global_store_dwordx2 v2, v[12:13], s[20:21] offset:224
	global_load_dwordx4 v[96:99], v1, s[26:27]
	global_load_dwordx4 v[100:103], v1, s[26:27] offset:16
	global_load_dwordx4 v[104:107], v1, s[26:27] offset:32
	global_load_dwordx4 v[108:111], v1, s[26:27] offset:48
	global_load_dwordx2 v[112:113], v2, s[26:27]
	global_load_dwordx2 v[114:115], v2, s[26:27] offset:32
	global_load_dwordx2 v[116:117], v2, s[26:27] offset:64
	global_load_dwordx2 v[118:119], v2, s[26:27] offset:96
	global_load_dwordx2 v[120:121], v2, s[26:27] offset:128
	global_load_dwordx2 v[122:123], v2, s[26:27] offset:160
	global_load_dwordx2 v[124:125], v2, s[26:27] offset:192
	global_load_dwordx2 v[126:127], v2, s[26:27] offset:224
	s_waitcnt vmcnt(28)
; #define LAS __attribute__((address_space(3)))
; __device__ __forceinline__ unsigned f2bf(float f) { unsigned u = __builtin_bit_cast(unsigned, f); return (u + 0x7fffu + ((u >> 16) & 1u)) >> 16; }
; __device__ __forceinline__ void gmlp_unit(LAS unsigned char* lds, bf16_t* Z, const float* ln_g, const float* ln_b, const float* b_s, const u32x2 (&uu)[8], const f32x4 (&wreg)[8], const u32x4 (&raw)[4], int cidx, int g, int tid) {
;     ...
;         const int j = tid >> 2, cq = (tid & 3) * 32;
;         float x[32];
; #pragma unroll
;         for (int q = 0; q < 4; ++q)
; #pragma unroll
;             for (int e = 0; e < 4; ++e) { x[8 * q + 2 * e] = bf_lo(raw[q][e]); x[8 * q + 2 * e + 1] = bf_hi(raw[q][e]); }
;         float s = 0.f;
; #pragma unroll
;         for (int c = 0; c < 32; ++c) s += x[c];
;         s += __shfl_xor(s, 1); s += __shfl_xor(s, 2);
;         const float mean = s * (1.f / 128.f); float q2 = 0.f;
; #pragma unroll
;         for (int c = 0; c < 32; ++c) { x[c] -= mean; q2 += x[c] * x[c]; }
;         q2 += __shfl_xor(q2, 1); q2 += __shfl_xor(q2, 2);
;         const float rstd = __builtin_amdgcn_rsqf(q2 * (1.f / 128.f) + EPS);
;         const float* gp = ln_g + g * 128 + cq; const float* bp = ln_b + g * 128 + cq;
; #pragma unroll
;         for (int c4 = 0; c4 < 8; ++c4) { const f32x4 gg = *(const f32x4*)(gp + 4 * c4), bb = *(const f32x4*)(bp + 4 * c4);
; #pragma unroll
;             for (int e = 0; e < 4; ++e) { const int c = 4 * c4 + e; const float y = x[c] * rstd * gg[e] + bb[e];
;                 *(LAS unsigned short*)(VT + (cq + c) * LSTR + j * 2) = (unsigned short)f2bf(y); } }
	v_lshlrev_b32_e32 v160, 16, v128
	v_and_b32_e32 v161, 0xffff0000, v128
	v_lshlrev_b32_e32 v162, 16, v129
	v_and_b32_e32 v163, 0xffff0000, v129
	v_lshlrev_b32_e32 v164, 16, v130
	v_and_b32_e32 v165, 0xffff0000, v130
	v_lshlrev_b32_e32 v166, 16, v131
	v_and_b32_e32 v167, 0xffff0000, v131
	v_lshlrev_b32_e32 v168, 16, v132
	v_and_b32_e32 v169, 0xffff0000, v132
	v_lshlrev_b32_e32 v170, 16, v133
	v_and_b32_e32 v171, 0xffff0000, v133
	v_lshlrev_b32_e32 v172, 16, v134
	v_and_b32_e32 v173, 0xffff0000, v134
	v_lshlrev_b32_e32 v174, 16, v135
	v_and_b32_e32 v175, 0xffff0000, v135
	v_lshlrev_b32_e32 v176, 16, v136
	v_and_b32_e32 v177, 0xffff0000, v136
	v_lshlrev_b32_e32 v178, 16, v137
	v_and_b32_e32 v179, 0xffff0000, v137
	v_lshlrev_b32_e32 v180, 16, v138
	v_and_b32_e32 v181, 0xffff0000, v138
	v_lshlrev_b32_e32 v182, 16, v139
	v_and_b32_e32 v183, 0xffff0000, v139
	v_lshlrev_b32_e32 v184, 16, v140
	v_and_b32_e32 v185, 0xffff0000, v140
	v_lshlrev_b32_e32 v186, 16, v141
	v_and_b32_e32 v187, 0xffff0000, v141
	v_lshlrev_b32_e32 v188, 16, v142
	v_and_b32_e32 v189, 0xffff0000, v142
	v_lshlrev_b32_e32 v190, 16, v143
	v_and_b32_e32 v191, 0xffff0000, v143
	v_add_f32_e32 v8, v160, v164
	v_add_f32_e32 v9, v161, v165
	v_add_f32_e32 v10, v162, v166
	v_add_f32_e32 v11, v163, v167
	v_add_f32_e32 v8, v8, v168
	v_add_f32_e32 v9, v9, v169
	v_add_f32_e32 v10, v10, v170
	v_add_f32_e32 v11, v11, v171
	v_add_f32_e32 v8, v8, v172
	v_add_f32_e32 v9, v9, v173
	v_add_f32_e32 v10, v10, v174
	v_add_f32_e32 v11, v11, v175
	v_add_f32_e32 v8, v8, v176
	v_add_f32_e32 v9, v9, v177
	v_add_f32_e32 v10, v10, v178
	v_add_f32_e32 v11, v11, v179
	v_add_f32_e32 v8, v8, v180
	v_add_f32_e32 v9, v9, v181
	v_add_f32_e32 v10, v10, v182
	v_add_f32_e32 v11, v11, v183
	v_add_f32_e32 v8, v8, v184
	v_add_f32_e32 v9, v9, v185
	v_add_f32_e32 v10, v10, v186
	v_add_f32_e32 v11, v11, v187
	v_add_f32_e32 v8, v8, v188
	v_add_f32_e32 v9, v9, v189
	v_add_f32_e32 v10, v10, v190
	v_add_f32_e32 v11, v11, v191
	v_add_f32_e32 v8, v8, v9
	v_add_f32_e32 v10, v10, v11
	v_add_f32_e32 v8, v8, v10
	s_nop 1
	v_add_f32_dpp v8, v8, v8 quad_perm:[1,0,3,2] row_mask:0xf bank_mask:0xf
	s_nop 1
	v_add_f32_dpp v8, v8, v8 quad_perm:[2,3,0,1] row_mask:0xf bank_mask:0xf
	v_mul_f32_e32 v8, 0xbc000000, v8
	v_add_f32_e32 v160, v160, v8
	v_add_f32_e32 v161, v161, v8
	v_add_f32_e32 v162, v162, v8
	v_add_f32_e32 v163, v163, v8
	v_add_f32_e32 v164, v164, v8
	v_add_f32_e32 v165, v165, v8
	v_add_f32_e32 v166, v166, v8
	v_add_f32_e32 v167, v167, v8
	v_add_f32_e32 v168, v168, v8
	v_add_f32_e32 v169, v169, v8
	v_add_f32_e32 v170, v170, v8
	v_add_f32_e32 v171, v171, v8
	v_add_f32_e32 v172, v172, v8
	v_add_f32_e32 v173, v173, v8
	v_add_f32_e32 v174, v174, v8
	v_add_f32_e32 v175, v175, v8
	v_add_f32_e32 v176, v176, v8
	v_add_f32_e32 v177, v177, v8
	v_add_f32_e32 v178, v178, v8
	v_add_f32_e32 v179, v179, v8
	v_add_f32_e32 v180, v180, v8
	v_add_f32_e32 v181, v181, v8
	v_add_f32_e32 v182, v182, v8
	v_add_f32_e32 v183, v183, v8
	v_add_f32_e32 v184, v184, v8
	v_add_f32_e32 v185, v185, v8
	v_add_f32_e32 v186, v186, v8
	v_add_f32_e32 v187, v187, v8
	v_add_f32_e32 v188, v188, v8
	v_add_f32_e32 v189, v189, v8
	v_add_f32_e32 v190, v190, v8
	v_add_f32_e32 v191, v191, v8
	v_mul_f32_e32 v8, v160, v160
	v_mul_f32_e32 v9, v161, v161
	v_mul_f32_e32 v10, v162, v162
	v_mul_f32_e32 v11, v163, v163
	v_fmac_f32_e32 v8, v164, v164
	v_fmac_f32_e32 v9, v165, v165
	v_fmac_f32_e32 v10, v166, v166
	v_fmac_f32_e32 v11, v167, v167
	v_fmac_f32_e32 v8, v168, v168
	v_fmac_f32_e32 v9, v169, v169
	v_fmac_f32_e32 v10, v170, v170
	v_fmac_f32_e32 v11, v171, v171
	v_fmac_f32_e32 v8, v172, v172
	v_fmac_f32_e32 v9, v173, v173
	v_fmac_f32_e32 v10, v174, v174
	v_fmac_f32_e32 v11, v175, v175
	v_fmac_f32_e32 v8, v176, v176
	v_fmac_f32_e32 v9, v177, v177
	v_fmac_f32_e32 v10, v178, v178
	v_fmac_f32_e32 v11, v179, v179
	v_fmac_f32_e32 v8, v180, v180
	v_fmac_f32_e32 v9, v181, v181
	v_fmac_f32_e32 v10, v182, v182
	v_fmac_f32_e32 v11, v183, v183
	v_fmac_f32_e32 v8, v184, v184
	v_fmac_f32_e32 v9, v185, v185
	v_fmac_f32_e32 v10, v186, v186
	v_fmac_f32_e32 v11, v187, v187
	v_fmac_f32_e32 v8, v188, v188
	v_fmac_f32_e32 v9, v189, v189
	v_fmac_f32_e32 v10, v190, v190
	v_fmac_f32_e32 v11, v191, v191
	v_add_f32_e32 v8, v8, v9
	v_add_f32_e32 v10, v10, v11
	v_add_f32_e32 v8, v8, v10
	s_nop 1
	v_add_f32_dpp v8, v8, v8 quad_perm:[1,0,3,2] row_mask:0xf bank_mask:0xf
	s_nop 1
	v_add_f32_dpp v8, v8, v8 quad_perm:[2,3,0,1] row_mask:0xf bank_mask:0xf
	v_fmamk_f32 v8, v8, 0x3c000000, v219
	v_rsq_f32_e32 v8, v8
	s_nop 0
	v_mul_f32_e32 v160, v160, v8
	v_fma_f32 v160, v16, v160, v48
	v_bfe_u32 v9, v160, 16, 1
	v_add3_u32 v160, v160, v9, s81
	ds_write_b16_d16_hi v3, v160 offset:34816
	v_mul_f32_e32 v161, v161, v8
	v_fma_f32 v161, v17, v161, v49
	v_bfe_u32 v10, v161, 16, 1
	v_add3_u32 v161, v161, v10, s81
	ds_write_b16_d16_hi v3, v161 offset:35088
	v_mul_f32_e32 v162, v162, v8
	v_fma_f32 v162, v18, v162, v50
	v_bfe_u32 v9, v162, 16, 1
	v_add3_u32 v162, v162, v9, s81
	ds_write_b16_d16_hi v3, v162 offset:35360
	v_mul_f32_e32 v163, v163, v8
	v_fma_f32 v163, v19, v163, v51
	v_bfe_u32 v10, v163, 16, 1
	v_add3_u32 v163, v163, v10, s81
	ds_write_b16_d16_hi v3, v163 offset:35632
	v_mul_f32_e32 v164, v164, v8
	v_fma_f32 v164, v20, v164, v52
	v_bfe_u32 v9, v164, 16, 1
	v_add3_u32 v164, v164, v9, s81
	ds_write_b16_d16_hi v3, v164 offset:35904
	v_mul_f32_e32 v165, v165, v8
	v_fma_f32 v165, v21, v165, v53
	v_bfe_u32 v10, v165, 16, 1
	v_add3_u32 v165, v165, v10, s81
	ds_write_b16_d16_hi v3, v165 offset:36176
	v_mul_f32_e32 v166, v166, v8
	v_fma_f32 v166, v22, v166, v54
	v_bfe_u32 v9, v166, 16, 1
	v_add3_u32 v166, v166, v9, s81
; #define LAS __attribute__((address_space(3)))
; __device__ __forceinline__ unsigned f2bf(float f) { unsigned u = __builtin_bit_cast(unsigned, f); return (u + 0x7fffu + ((u >> 16) & 1u)) >> 16; }
; __device__ __forceinline__ void gmlp_unit(LAS unsigned char* lds, bf16_t* Z, const float* ln_g, const float* ln_b, const float* b_s, const u32x2 (&uu)[8], const f32x4 (&wreg)[8], const u32x4 (&raw)[4], int cidx, int g, int tid) {
;     ...
;             for (int e = 0; e < 4; ++e) { const int c = 4 * c4 + e; const float y = x[c] * rstd * gg[e] + bb[e];
;                 *(LAS unsigned short*)(VT + (cq + c) * LSTR + j * 2) = (unsigned short)f2bf(y); } }
;     ...
;     __syncthreads();
;     const int wv = tid >> 6, lane = tid & 63, fr = lane & 15, fq = lane >> 4;
;     f32x4 acc[8];
; #pragma unroll
;     for (int ct = 0; ct < 8; ++ct) acc[ct] = (f32x4){0.f, 0.f, 0.f, 0.f};
; #pragma unroll
;     for (int ks = 0; ks < 4; ++ks) {
;         const bf16x8 bw = *(const LAS bf16x8*)(WS + (wv * 16 + fr) * LSTR + (ks * 32 + fq * 8) * 2);
; #pragma unroll
;         for (int ct = 0; ct < 8; ++ct) { const bf16x8 av = *(const LAS bf16x8*)(VT + (ct * 16 + fr) * LSTR + (ks * 32 + fq * 8) * 2);
;             acc[ct] = __builtin_amdgcn_mfma_f32_16x16x32_bf16(av, bw, acc[ct], 0, 0, 0); }
;     }
	ds_write_b16_d16_hi v3, v166 offset:36448
	v_mul_f32_e32 v167, v167, v8
	v_fma_f32 v167, v23, v167, v55
	v_bfe_u32 v10, v167, 16, 1
	v_add3_u32 v167, v167, v10, s81
	ds_write_b16_d16_hi v3, v167 offset:36720
	v_mul_f32_e32 v168, v168, v8
	v_fma_f32 v168, v24, v168, v56
	v_bfe_u32 v9, v168, 16, 1
	v_add3_u32 v168, v168, v9, s81
	ds_write_b16_d16_hi v3, v168 offset:36992
	v_mul_f32_e32 v169, v169, v8
	v_fma_f32 v169, v25, v169, v57
	v_bfe_u32 v10, v169, 16, 1
	v_add3_u32 v169, v169, v10, s81
	ds_write_b16_d16_hi v3, v169 offset:37264
	v_mul_f32_e32 v170, v170, v8
	v_fma_f32 v170, v26, v170, v58
	v_bfe_u32 v9, v170, 16, 1
	v_add3_u32 v170, v170, v9, s81
	ds_write_b16_d16_hi v3, v170 offset:37536
	v_mul_f32_e32 v171, v171, v8
	v_fma_f32 v171, v27, v171, v59
	v_bfe_u32 v10, v171, 16, 1
	v_add3_u32 v171, v171, v10, s81
	ds_write_b16_d16_hi v3, v171 offset:37808
	v_mul_f32_e32 v172, v172, v8
	v_fma_f32 v172, v28, v172, v60
	v_bfe_u32 v9, v172, 16, 1
	v_add3_u32 v172, v172, v9, s81
	ds_write_b16_d16_hi v3, v172 offset:38080
	v_mul_f32_e32 v173, v173, v8
	v_fma_f32 v173, v29, v173, v61
	v_bfe_u32 v10, v173, 16, 1
	v_add3_u32 v173, v173, v10, s81
	ds_write_b16_d16_hi v3, v173 offset:38352
	v_mul_f32_e32 v174, v174, v8
	v_fma_f32 v174, v30, v174, v62
	v_bfe_u32 v9, v174, 16, 1
	v_add3_u32 v174, v174, v9, s81
	ds_write_b16_d16_hi v3, v174 offset:38624
	v_mul_f32_e32 v175, v175, v8
	v_fma_f32 v175, v31, v175, v63
	v_bfe_u32 v10, v175, 16, 1
	v_add3_u32 v175, v175, v10, s81
	ds_write_b16_d16_hi v3, v175 offset:38896
	v_mul_f32_e32 v176, v176, v8
	v_fma_f32 v176, v32, v176, v64
	v_bfe_u32 v9, v176, 16, 1
	v_add3_u32 v176, v176, v9, s81
	ds_write_b16_d16_hi v3, v176 offset:39168
	v_mul_f32_e32 v177, v177, v8
	v_fma_f32 v177, v33, v177, v65
	v_bfe_u32 v10, v177, 16, 1
	v_add3_u32 v177, v177, v10, s81
	ds_write_b16_d16_hi v3, v177 offset:39440
	v_mul_f32_e32 v178, v178, v8
	v_fma_f32 v178, v34, v178, v66
	v_bfe_u32 v9, v178, 16, 1
	v_add3_u32 v178, v178, v9, s81
	ds_write_b16_d16_hi v3, v178 offset:39712
	v_mul_f32_e32 v179, v179, v8
	v_fma_f32 v179, v35, v179, v67
	v_bfe_u32 v10, v179, 16, 1
	v_add3_u32 v179, v179, v10, s81
	ds_write_b16_d16_hi v3, v179 offset:39984
	v_mul_f32_e32 v180, v180, v8
	v_fma_f32 v180, v36, v180, v68
	v_bfe_u32 v9, v180, 16, 1
	v_add3_u32 v180, v180, v9, s81
	ds_write_b16_d16_hi v3, v180 offset:40256
	v_mul_f32_e32 v181, v181, v8
	v_fma_f32 v181, v37, v181, v69
	v_bfe_u32 v10, v181, 16, 1
	v_add3_u32 v181, v181, v10, s81
	ds_write_b16_d16_hi v3, v181 offset:40528
	v_mul_f32_e32 v182, v182, v8
	v_fma_f32 v182, v38, v182, v70
	v_bfe_u32 v9, v182, 16, 1
	v_add3_u32 v182, v182, v9, s81
	ds_write_b16_d16_hi v3, v182 offset:40800
	v_mul_f32_e32 v183, v183, v8
	v_fma_f32 v183, v39, v183, v71
	v_bfe_u32 v10, v183, 16, 1
	v_add3_u32 v183, v183, v10, s81
	ds_write_b16_d16_hi v3, v183 offset:41072
	v_mul_f32_e32 v184, v184, v8
	v_fma_f32 v184, v40, v184, v72
	v_bfe_u32 v9, v184, 16, 1
	v_add3_u32 v184, v184, v9, s81
	ds_write_b16_d16_hi v3, v184 offset:41344
	v_mul_f32_e32 v185, v185, v8
	v_fma_f32 v185, v41, v185, v73
	v_bfe_u32 v10, v185, 16, 1
	v_add3_u32 v185, v185, v10, s81
	ds_write_b16_d16_hi v3, v185 offset:41616
	v_mul_f32_e32 v186, v186, v8
	v_fma_f32 v186, v42, v186, v74
	v_bfe_u32 v9, v186, 16, 1
	v_add3_u32 v186, v186, v9, s81
	ds_write_b16_d16_hi v3, v186 offset:41888
	v_mul_f32_e32 v187, v187, v8
	v_fma_f32 v187, v43, v187, v75
	v_bfe_u32 v10, v187, 16, 1
	v_add3_u32 v187, v187, v10, s81
	ds_write_b16_d16_hi v3, v187 offset:42160
	v_mul_f32_e32 v188, v188, v8
	v_fma_f32 v188, v44, v188, v76
	v_bfe_u32 v9, v188, 16, 1
	v_add3_u32 v188, v188, v9, s81
	ds_write_b16_d16_hi v3, v188 offset:42432
	v_mul_f32_e32 v189, v189, v8
	v_fma_f32 v189, v45, v189, v77
	v_bfe_u32 v10, v189, 16, 1
	v_add3_u32 v189, v189, v10, s81
	ds_write_b16_d16_hi v3, v189 offset:42704
	v_mul_f32_e32 v190, v190, v8
	v_fma_f32 v190, v46, v190, v78
	v_bfe_u32 v9, v190, 16, 1
	v_add3_u32 v190, v190, v9, s81
	ds_write_b16_d16_hi v3, v190 offset:42976
	v_mul_f32_e32 v191, v191, v8
	v_fma_f32 v191, v47, v191, v79
	v_bfe_u32 v10, v191, 16, 1
	v_add3_u32 v191, v191, v10, s81
	ds_write_b16_d16_hi v3, v191 offset:43248
	s_waitcnt lgkmcnt(0)
	s_barrier
	ds_read_b128 v[200:203], v4 offset:34816
	ds_read_b128 v[204:207], v4 offset:39168
	ds_read_b128 v[208:211], v4 offset:43520
	ds_read_b128 v[212:215], v4 offset:47872
	ds_read_b128 v[224:227], v4 offset:52224
	ds_read_b128 v[228:231], v4 offset:56576
	ds_read_b128 v[232:235], v4 offset:60928
	ds_read_b128 v[236:239], v4 offset:65280
	s_waitcnt lgkmcnt(7)
	v_mfma_f32_16x16x32_bf16 v[160:163], v[200:203], v[80:83], 0
	ds_read_b128 v[200:203], v4 offset:34880
	s_waitcnt lgkmcnt(7)
	v_mfma_f32_16x16x32_bf16 v[164:167], v[204:207], v[80:83], 0
	ds_read_b128 v[204:207], v4 offset:39232
	s_waitcnt lgkmcnt(7)
	v_mfma_f32_16x16x32_bf16 v[168:171], v[208:211], v[80:83], 0
	ds_read_b128 v[208:211], v4 offset:43584
	s_waitcnt lgkmcnt(7)
	v_mfma_f32_16x16x32_bf16 v[172:175], v[212:215], v[80:83], 0
	ds_read_b128 v[212:215], v4 offset:47936
	s_waitcnt lgkmcnt(7)
	v_mfma_f32_16x16x32_bf16 v[176:179], v[224:227], v[80:83], 0
	ds_read_b128 v[224:227], v4 offset:52288
	s_waitcnt lgkmcnt(7)
	v_mfma_f32_16x16x32_bf16 v[180:183], v[228:231], v[80:83], 0
	ds_read_b128 v[228:231], v4 offset:56640
	s_waitcnt lgkmcnt(7)
	v_mfma_f32_16x16x32_bf16 v[184:187], v[232:235], v[80:83], 0
	ds_read_b128 v[232:235], v4 offset:60992
	s_waitcnt lgkmcnt(7)
	v_mfma_f32_16x16x32_bf16 v[188:191], v[236:239], v[80:83], 0
	ds_read_b128 v[236:239], v4 offset:65344
	s_waitcnt lgkmcnt(7)
	v_mfma_f32_16x16x32_bf16 v[160:163], v[200:203], v[84:87], v[160:163]
	ds_read_b128 v[200:203], v4 offset:34944
	s_waitcnt lgkmcnt(7)
; #define LAS __attribute__((address_space(3)))
; __device__ __forceinline__ unsigned pk2(float lo, float hi) { return pg8::cvt_pk_bf16(lo, hi); }
; __device__ __forceinline__ void gmlp_unit(LAS unsigned char* lds, bf16_t* Z, const float* ln_g, const float* ln_b, const float* b_s, const u32x2 (&uu)[8], const f32x4 (&wreg)[8], const u32x4 (&raw)[4], int cidx, int g, int tid) {
;     ...
;         for (int ct = 0; ct < 8; ++ct) { const bf16x8 av = *(const LAS bf16x8*)(VT + (ct * 16 + fr) * LSTR + (ks * 32 + fq * 8) * 2);
;             acc[ct] = __builtin_amdgcn_mfma_f32_16x16x32_bf16(av, bw, acc[ct], 0, 0, 0); }
;     }
;     {
;         const int i = wv * 16 + fr; const float bs = b_s[g * 128 + i];
;         bf16_t* up = Z + (size_t)(row0 + i) * INW + g * 128 + 4 * fq;
; #pragma unroll
;         for (int ct = 0; ct < 8; ++ct) {
;             u32x2 w; w.x = pk2(bf_lo(uu[ct].x) * (acc[ct][0] + bs), bf_hi(uu[ct].x) * (acc[ct][1] + bs)); w.y = pk2(bf_lo(uu[ct].y) * (acc[ct][2] + bs), bf_hi(uu[ct].y) * (acc[ct][3] + bs));
;             *(u32x2*)(up + 16 * ct) = w; }
	v_mfma_f32_16x16x32_bf16 v[164:167], v[204:207], v[84:87], v[164:167]
	ds_read_b128 v[204:207], v4 offset:39296
	s_waitcnt lgkmcnt(7)
	v_mfma_f32_16x16x32_bf16 v[168:171], v[208:211], v[84:87], v[168:171]
	ds_read_b128 v[208:211], v4 offset:43648
	s_waitcnt lgkmcnt(7)
	v_mfma_f32_16x16x32_bf16 v[172:175], v[212:215], v[84:87], v[172:175]
	ds_read_b128 v[212:215], v4 offset:48000
	s_waitcnt lgkmcnt(7)
	v_mfma_f32_16x16x32_bf16 v[176:179], v[224:227], v[84:87], v[176:179]
	ds_read_b128 v[224:227], v4 offset:52352
	s_waitcnt lgkmcnt(7)
	v_mfma_f32_16x16x32_bf16 v[180:183], v[228:231], v[84:87], v[180:183]
	ds_read_b128 v[228:231], v4 offset:56704
	s_waitcnt lgkmcnt(7)
	v_mfma_f32_16x16x32_bf16 v[184:187], v[232:235], v[84:87], v[184:187]
	ds_read_b128 v[232:235], v4 offset:61056
	s_waitcnt lgkmcnt(7)
	v_mfma_f32_16x16x32_bf16 v[188:191], v[236:239], v[84:87], v[188:191]
	ds_read_b128 v[236:239], v4 offset:65408
	s_waitcnt lgkmcnt(7)
	v_mfma_f32_16x16x32_bf16 v[160:163], v[200:203], v[88:91], v[160:163]
	ds_read_b128 v[200:203], v4 offset:35008
	s_waitcnt lgkmcnt(7)
	v_mfma_f32_16x16x32_bf16 v[164:167], v[204:207], v[88:91], v[164:167]
	ds_read_b128 v[204:207], v4 offset:39360
	s_waitcnt lgkmcnt(7)
	v_mfma_f32_16x16x32_bf16 v[168:171], v[208:211], v[88:91], v[168:171]
	ds_read_b128 v[208:211], v4 offset:43712
	s_waitcnt lgkmcnt(7)
	v_mfma_f32_16x16x32_bf16 v[172:175], v[212:215], v[88:91], v[172:175]
	ds_read_b128 v[212:215], v4 offset:48064
	s_waitcnt lgkmcnt(7)
	v_mfma_f32_16x16x32_bf16 v[176:179], v[224:227], v[88:91], v[176:179]
	ds_read_b128 v[224:227], v4 offset:52416
	s_waitcnt lgkmcnt(7)
	v_mfma_f32_16x16x32_bf16 v[180:183], v[228:231], v[88:91], v[180:183]
	ds_read_b128 v[228:231], v4 offset:56768
	s_waitcnt lgkmcnt(7)
	v_mfma_f32_16x16x32_bf16 v[184:187], v[232:235], v[88:91], v[184:187]
	ds_read_b128 v[232:235], v4 offset:61120
	s_waitcnt lgkmcnt(7)
	v_mfma_f32_16x16x32_bf16 v[188:191], v[236:239], v[88:91], v[188:191]
	ds_read_b128 v[236:239], v4 offset:65472
	s_waitcnt lgkmcnt(7)
	v_mfma_f32_16x16x32_bf16 v[160:163], v[200:203], v[92:95], v[160:163]
	s_waitcnt lgkmcnt(6)
	v_mfma_f32_16x16x32_bf16 v[164:167], v[204:207], v[92:95], v[164:167]
	s_waitcnt lgkmcnt(5)
	v_mfma_f32_16x16x32_bf16 v[168:171], v[208:211], v[92:95], v[168:171]
	s_waitcnt lgkmcnt(4)
	v_mfma_f32_16x16x32_bf16 v[172:175], v[212:215], v[92:95], v[172:175]
	s_waitcnt lgkmcnt(3)
	v_mfma_f32_16x16x32_bf16 v[176:179], v[224:227], v[92:95], v[176:179]
	s_waitcnt lgkmcnt(2)
	v_mfma_f32_16x16x32_bf16 v[180:183], v[228:231], v[92:95], v[180:183]
	s_waitcnt lgkmcnt(1)
	v_mfma_f32_16x16x32_bf16 v[184:187], v[232:235], v[92:95], v[184:187]
	s_waitcnt lgkmcnt(0)
	v_mfma_f32_16x16x32_bf16 v[188:191], v[236:239], v[92:95], v[188:191]
	s_waitcnt vmcnt(20)
	v_add_f32_e32 v160, v160, v7
	v_add_f32_e32 v161, v161, v7
	v_add_f32_e32 v162, v162, v7
	v_add_f32_e32 v163, v163, v7
	v_lshlrev_b32_e32 v8, 16, v144
	v_and_b32_e32 v9, 0xffff0000, v144
	v_lshlrev_b32_e32 v10, 16, v145
	v_and_b32_e32 v11, 0xffff0000, v145
	v_mul_f32_e32 v160, v8, v160
	v_mul_f32_e32 v161, v9, v161
	v_mul_f32_e32 v162, v10, v162
	v_mul_f32_e32 v163, v11, v163
	v_cvt_pk_bf16_f32 v12, v160, v161
	v_cvt_pk_bf16_f32 v13, v162, v163
	global_store_dwordx2 v2, v[12:13], s[24:25]
	s_nop 0
	v_add_f32_e32 v164, v164, v7
	v_add_f32_e32 v165, v165, v7
	v_add_f32_e32 v166, v166, v7
	v_add_f32_e32 v167, v167, v7
	v_lshlrev_b32_e32 v8, 16, v146
	v_and_b32_e32 v9, 0xffff0000, v146
	v_lshlrev_b32_e32 v10, 16, v147
	v_and_b32_e32 v11, 0xffff0000, v147
	v_mul_f32_e32 v164, v8, v164
	v_mul_f32_e32 v165, v9, v165
	v_mul_f32_e32 v166, v10, v166
	v_mul_f32_e32 v167, v11, v167
	v_cvt_pk_bf16_f32 v12, v164, v165
	v_cvt_pk_bf16_f32 v13, v166, v167
	global_store_dwordx2 v2, v[12:13], s[24:25] offset:32
	s_nop 0
	v_add_f32_e32 v168, v168, v7
	v_add_f32_e32 v169, v169, v7
	v_add_f32_e32 v170, v170, v7
	v_add_f32_e32 v171, v171, v7
	v_lshlrev_b32_e32 v8, 16, v148
	v_and_b32_e32 v9, 0xffff0000, v148
	v_lshlrev_b32_e32 v10, 16, v149
	v_and_b32_e32 v11, 0xffff0000, v149
	v_mul_f32_e32 v168, v8, v168
	v_mul_f32_e32 v169, v9, v169
	v_mul_f32_e32 v170, v10, v170
	v_mul_f32_e32 v171, v11, v171
	v_cvt_pk_bf16_f32 v12, v168, v169
	v_cvt_pk_bf16_f32 v13, v170, v171
	global_store_dwordx2 v2, v[12:13], s[24:25] offset:64
	s_nop 0
	v_add_f32_e32 v172, v172, v7
	v_add_f32_e32 v173, v173, v7
	v_add_f32_e32 v174, v174, v7
	v_add_f32_e32 v175, v175, v7
	v_lshlrev_b32_e32 v8, 16, v150
	v_and_b32_e32 v9, 0xffff0000, v150
	v_lshlrev_b32_e32 v10, 16, v151
	v_and_b32_e32 v11, 0xffff0000, v151
	v_mul_f32_e32 v172, v8, v172
	v_mul_f32_e32 v173, v9, v173
	v_mul_f32_e32 v174, v10, v174
	v_mul_f32_e32 v175, v11, v175
	v_cvt_pk_bf16_f32 v12, v172, v173
	v_cvt_pk_bf16_f32 v13, v174, v175
	global_store_dwordx2 v2, v[12:13], s[24:25] offset:96
	s_nop 0
	v_add_f32_e32 v176, v176, v7
	v_add_f32_e32 v177, v177, v7
	v_add_f32_e32 v178, v178, v7
	v_add_f32_e32 v179, v179, v7
	v_lshlrev_b32_e32 v8, 16, v152
	v_and_b32_e32 v9, 0xffff0000, v152
	v_lshlrev_b32_e32 v10, 16, v153
	v_and_b32_e32 v11, 0xffff0000, v153
	v_mul_f32_e32 v176, v8, v176
	v_mul_f32_e32 v177, v9, v177
	v_mul_f32_e32 v178, v10, v178
	v_mul_f32_e32 v179, v11, v179
	v_cvt_pk_bf16_f32 v12, v176, v177
	v_cvt_pk_bf16_f32 v13, v178, v179
	global_store_dwordx2 v2, v[12:13], s[24:25] offset:128
	s_nop 0
	v_add_f32_e32 v180, v180, v7
	v_add_f32_e32 v181, v181, v7
	v_add_f32_e32 v182, v182, v7
	v_add_f32_e32 v183, v183, v7
	v_lshlrev_b32_e32 v8, 16, v154
	v_and_b32_e32 v9, 0xffff0000, v154
	v_lshlrev_b32_e32 v10, 16, v155
	v_and_b32_e32 v11, 0xffff0000, v155
	v_mul_f32_e32 v180, v8, v180
	v_mul_f32_e32 v181, v9, v181
; __device__ __forceinline__ unsigned pk2(float lo, float hi) { return pg8::cvt_pk_bf16(lo, hi); }
; __device__ __forceinline__ void gmlp_unit(LAS unsigned char* lds, bf16_t* Z, const float* ln_g, const float* ln_b, const float* b_s, const u32x2 (&uu)[8], const f32x4 (&wreg)[8], const u32x4 (&raw)[4], int cidx, int g, int tid) {
;     ...
;         const int j = tid >> 2, cq = (tid & 3) * 32;
;         float x[32];
; #pragma unroll
;         for (int q = 0; q < 4; ++q)
; #pragma unroll
;             for (int e = 0; e < 4; ++e) { x[8 * q + 2 * e] = bf_lo(raw[q][e]); x[8 * q + 2 * e + 1] = bf_hi(raw[q][e]); }
;         float s = 0.f;
; #pragma unroll
;         for (int c = 0; c < 32; ++c) s += x[c];
;         s += __shfl_xor(s, 1); s += __shfl_xor(s, 2);
;         const float mean = s * (1.f / 128.f); float q2 = 0.f;
; #pragma unroll
;         for (int c = 0; c < 32; ++c) { x[c] -= mean; q2 += x[c] * x[c]; }
;         q2 += __shfl_xor(q2, 1); q2 += __shfl_xor(q2, 2);
;         const float rstd = __builtin_amdgcn_rsqf(q2 * (1.f / 128.f) + EPS);
;         const float* gp = ln_g + g * 128 + cq; const float* bp = ln_b + g * 128 + cq;
;     ...
;         const int i = wv * 16 + fr; const float bs = b_s[g * 128 + i];
;         bf16_t* up = Z + (size_t)(row0 + i) * INW + g * 128 + 4 * fq;
; #pragma unroll
;         for (int ct = 0; ct < 8; ++ct) {
;             u32x2 w; w.x = pk2(bf_lo(uu[ct].x) * (acc[ct][0] + bs), bf_hi(uu[ct].x) * (acc[ct][1] + bs)); w.y = pk2(bf_lo(uu[ct].y) * (acc[ct][2] + bs), bf_hi(uu[ct].y) * (acc[ct][3] + bs));
;             *(u32x2*)(up + 16 * ct) = w; }
;     }
	v_mul_f32_e32 v182, v10, v182
	v_mul_f32_e32 v183, v11, v183
	v_cvt_pk_bf16_f32 v12, v180, v181
	v_cvt_pk_bf16_f32 v13, v182, v183
	global_store_dwordx2 v2, v[12:13], s[24:25] offset:160
	s_nop 0
	v_add_f32_e32 v184, v184, v7
	v_add_f32_e32 v185, v185, v7
	v_add_f32_e32 v186, v186, v7
	v_add_f32_e32 v187, v187, v7
	v_lshlrev_b32_e32 v8, 16, v156
	v_and_b32_e32 v9, 0xffff0000, v156
	v_lshlrev_b32_e32 v10, 16, v157
	v_and_b32_e32 v11, 0xffff0000, v157
	v_mul_f32_e32 v184, v8, v184
	v_mul_f32_e32 v185, v9, v185
	v_mul_f32_e32 v186, v10, v186
	v_mul_f32_e32 v187, v11, v187
	v_cvt_pk_bf16_f32 v12, v184, v185
	v_cvt_pk_bf16_f32 v13, v186, v187
	global_store_dwordx2 v2, v[12:13], s[24:25] offset:192
	s_nop 0
	v_add_f32_e32 v188, v188, v7
	v_add_f32_e32 v189, v189, v7
	v_add_f32_e32 v190, v190, v7
	v_add_f32_e32 v191, v191, v7
	v_lshlrev_b32_e32 v8, 16, v158
	v_and_b32_e32 v9, 0xffff0000, v158
	v_lshlrev_b32_e32 v10, 16, v159
	v_and_b32_e32 v11, 0xffff0000, v159
	v_mul_f32_e32 v188, v8, v188
	v_mul_f32_e32 v189, v9, v189
	v_mul_f32_e32 v190, v10, v190
	v_mul_f32_e32 v191, v11, v191
	v_cvt_pk_bf16_f32 v12, v188, v189
	v_cvt_pk_bf16_f32 v13, v190, v191
	global_store_dwordx2 v2, v[12:13], s[24:25] offset:224
	global_load_dwordx4 v[128:131], v1, s[28:29]
	global_load_dwordx4 v[132:135], v1, s[28:29] offset:16
	global_load_dwordx4 v[136:139], v1, s[28:29] offset:32
	global_load_dwordx4 v[140:143], v1, s[28:29] offset:48
	global_load_dwordx2 v[144:145], v2, s[28:29]
	global_load_dwordx2 v[146:147], v2, s[28:29] offset:32
	global_load_dwordx2 v[148:149], v2, s[28:29] offset:64
	global_load_dwordx2 v[150:151], v2, s[28:29] offset:96
	global_load_dwordx2 v[152:153], v2, s[28:29] offset:128
	global_load_dwordx2 v[154:155], v2, s[28:29] offset:160
	global_load_dwordx2 v[156:157], v2, s[28:29] offset:192
	global_load_dwordx2 v[158:159], v2, s[28:29] offset:224
	s_waitcnt vmcnt(28)
	v_lshlrev_b32_e32 v160, 16, v96
	v_and_b32_e32 v161, 0xffff0000, v96
	v_lshlrev_b32_e32 v162, 16, v97
	v_and_b32_e32 v163, 0xffff0000, v97
	v_lshlrev_b32_e32 v164, 16, v98
	v_and_b32_e32 v165, 0xffff0000, v98
	v_lshlrev_b32_e32 v166, 16, v99
	v_and_b32_e32 v167, 0xffff0000, v99
	v_lshlrev_b32_e32 v168, 16, v100
	v_and_b32_e32 v169, 0xffff0000, v100
	v_lshlrev_b32_e32 v170, 16, v101
	v_and_b32_e32 v171, 0xffff0000, v101
	v_lshlrev_b32_e32 v172, 16, v102
	v_and_b32_e32 v173, 0xffff0000, v102
	v_lshlrev_b32_e32 v174, 16, v103
	v_and_b32_e32 v175, 0xffff0000, v103
	v_lshlrev_b32_e32 v176, 16, v104
	v_and_b32_e32 v177, 0xffff0000, v104
	v_lshlrev_b32_e32 v178, 16, v105
	v_and_b32_e32 v179, 0xffff0000, v105
	v_lshlrev_b32_e32 v180, 16, v106
	v_and_b32_e32 v181, 0xffff0000, v106
	v_lshlrev_b32_e32 v182, 16, v107
	v_and_b32_e32 v183, 0xffff0000, v107
	v_lshlrev_b32_e32 v184, 16, v108
	v_and_b32_e32 v185, 0xffff0000, v108
	v_lshlrev_b32_e32 v186, 16, v109
	v_and_b32_e32 v187, 0xffff0000, v109
	v_lshlrev_b32_e32 v188, 16, v110
	v_and_b32_e32 v189, 0xffff0000, v110
	v_lshlrev_b32_e32 v190, 16, v111
	v_and_b32_e32 v191, 0xffff0000, v111
	v_add_f32_e32 v8, v160, v164
	v_add_f32_e32 v9, v161, v165
	v_add_f32_e32 v10, v162, v166
	v_add_f32_e32 v11, v163, v167
	v_add_f32_e32 v8, v8, v168
	v_add_f32_e32 v9, v9, v169
	v_add_f32_e32 v10, v10, v170
	v_add_f32_e32 v11, v11, v171
	v_add_f32_e32 v8, v8, v172
	v_add_f32_e32 v9, v9, v173
	v_add_f32_e32 v10, v10, v174
	v_add_f32_e32 v11, v11, v175
	v_add_f32_e32 v8, v8, v176
	v_add_f32_e32 v9, v9, v177
	v_add_f32_e32 v10, v10, v178
	v_add_f32_e32 v11, v11, v179
	v_add_f32_e32 v8, v8, v180
	v_add_f32_e32 v9, v9, v181
	v_add_f32_e32 v10, v10, v182
	v_add_f32_e32 v11, v11, v183
	v_add_f32_e32 v8, v8, v184
	v_add_f32_e32 v9, v9, v185
	v_add_f32_e32 v10, v10, v186
	v_add_f32_e32 v11, v11, v187
	v_add_f32_e32 v8, v8, v188
	v_add_f32_e32 v9, v9, v189
	v_add_f32_e32 v10, v10, v190
	v_add_f32_e32 v11, v11, v191
	v_add_f32_e32 v8, v8, v9
	v_add_f32_e32 v10, v10, v11
	v_add_f32_e32 v8, v8, v10
	s_nop 1
	v_add_f32_dpp v8, v8, v8 quad_perm:[1,0,3,2] row_mask:0xf bank_mask:0xf
	s_nop 1
	v_add_f32_dpp v8, v8, v8 quad_perm:[2,3,0,1] row_mask:0xf bank_mask:0xf
	v_mul_f32_e32 v8, 0xbc000000, v8
	v_add_f32_e32 v160, v160, v8
	v_add_f32_e32 v161, v161, v8
	v_add_f32_e32 v162, v162, v8
	v_add_f32_e32 v163, v163, v8
	v_add_f32_e32 v164, v164, v8
	v_add_f32_e32 v165, v165, v8
	v_add_f32_e32 v166, v166, v8
	v_add_f32_e32 v167, v167, v8
	v_add_f32_e32 v168, v168, v8
	v_add_f32_e32 v169, v169, v8
	v_add_f32_e32 v170, v170, v8
	v_add_f32_e32 v171, v171, v8
	v_add_f32_e32 v172, v172, v8
	v_add_f32_e32 v173, v173, v8
	v_add_f32_e32 v174, v174, v8
	v_add_f32_e32 v175, v175, v8
	v_add_f32_e32 v176, v176, v8
	v_add_f32_e32 v177, v177, v8
	v_add_f32_e32 v178, v178, v8
	v_add_f32_e32 v179, v179, v8
	v_add_f32_e32 v180, v180, v8
	v_add_f32_e32 v181, v181, v8
	v_add_f32_e32 v182, v182, v8
	v_add_f32_e32 v183, v183, v8
	v_add_f32_e32 v184, v184, v8
	v_add_f32_e32 v185, v185, v8
	v_add_f32_e32 v186, v186, v8
	v_add_f32_e32 v187, v187, v8
	v_add_f32_e32 v188, v188, v8
	v_add_f32_e32 v189, v189, v8
	v_add_f32_e32 v190, v190, v8
	v_add_f32_e32 v191, v191, v8
	v_mul_f32_e32 v8, v160, v160
	v_mul_f32_e32 v9, v161, v161
	v_mul_f32_e32 v10, v162, v162
	v_mul_f32_e32 v11, v163, v163
	v_fmac_f32_e32 v8, v164, v164
	v_fmac_f32_e32 v9, v165, v165
	v_fmac_f32_e32 v10, v166, v166
	v_fmac_f32_e32 v11, v167, v167
	v_fmac_f32_e32 v8, v168, v168
	v_fmac_f32_e32 v9, v169, v169
	v_fmac_f32_e32 v10, v170, v170
	v_fmac_f32_e32 v11, v171, v171
	v_fmac_f32_e32 v8, v172, v172
	v_fmac_f32_e32 v9, v173, v173
	v_fmac_f32_e32 v10, v174, v174
	v_fmac_f32_e32 v11, v175, v175
	v_fmac_f32_e32 v8, v176, v176
; #define LAS __attribute__((address_space(3)))
; __device__ __forceinline__ unsigned f2bf(float f) { unsigned u = __builtin_bit_cast(unsigned, f); return (u + 0x7fffu + ((u >> 16) & 1u)) >> 16; }
; __device__ __forceinline__ void gmlp_unit(LAS unsigned char* lds, bf16_t* Z, const float* ln_g, const float* ln_b, const float* b_s, const u32x2 (&uu)[8], const f32x4 (&wreg)[8], const u32x4 (&raw)[4], int cidx, int g, int tid) {
;     ...
;         s += __shfl_xor(s, 1); s += __shfl_xor(s, 2);
;         const float mean = s * (1.f / 128.f); float q2 = 0.f;
; #pragma unroll
;         for (int c = 0; c < 32; ++c) { x[c] -= mean; q2 += x[c] * x[c]; }
;         q2 += __shfl_xor(q2, 1); q2 += __shfl_xor(q2, 2);
;         const float rstd = __builtin_amdgcn_rsqf(q2 * (1.f / 128.f) + EPS);
;         const float* gp = ln_g + g * 128 + cq; const float* bp = ln_b + g * 128 + cq;
; #pragma unroll
;         for (int c4 = 0; c4 < 8; ++c4) { const f32x4 gg = *(const f32x4*)(gp + 4 * c4), bb = *(const f32x4*)(bp + 4 * c4);
; #pragma unroll
;             for (int e = 0; e < 4; ++e) { const int c = 4 * c4 + e; const float y = x[c] * rstd * gg[e] + bb[e];
;                 *(LAS unsigned short*)(VT + (cq + c) * LSTR + j * 2) = (unsigned short)f2bf(y); } }
;     ...
;     __syncthreads();
	v_fmac_f32_e32 v9, v177, v177
	v_fmac_f32_e32 v10, v178, v178
	v_fmac_f32_e32 v11, v179, v179
	v_fmac_f32_e32 v8, v180, v180
	v_fmac_f32_e32 v9, v181, v181
	v_fmac_f32_e32 v10, v182, v182
	v_fmac_f32_e32 v11, v183, v183
	v_fmac_f32_e32 v8, v184, v184
	v_fmac_f32_e32 v9, v185, v185
	v_fmac_f32_e32 v10, v186, v186
	v_fmac_f32_e32 v11, v187, v187
	v_fmac_f32_e32 v8, v188, v188
	v_fmac_f32_e32 v9, v189, v189
	v_fmac_f32_e32 v10, v190, v190
	v_fmac_f32_e32 v11, v191, v191
	v_add_f32_e32 v8, v8, v9
	v_add_f32_e32 v10, v10, v11
	v_add_f32_e32 v8, v8, v10
	s_nop 1
	v_add_f32_dpp v8, v8, v8 quad_perm:[1,0,3,2] row_mask:0xf bank_mask:0xf
	s_nop 1
	v_add_f32_dpp v8, v8, v8 quad_perm:[2,3,0,1] row_mask:0xf bank_mask:0xf
	v_fmamk_f32 v8, v8, 0x3c000000, v219
	v_rsq_f32_e32 v8, v8
	s_nop 0
	v_mul_f32_e32 v160, v160, v8
	v_fma_f32 v160, v16, v160, v48
	v_bfe_u32 v9, v160, 16, 1
	v_add3_u32 v160, v160, v9, s81
	ds_write_b16_d16_hi v3, v160
	v_mul_f32_e32 v161, v161, v8
	v_fma_f32 v161, v17, v161, v49
	v_bfe_u32 v10, v161, 16, 1
	v_add3_u32 v161, v161, v10, s81
	ds_write_b16_d16_hi v3, v161 offset:272
	v_mul_f32_e32 v162, v162, v8
	v_fma_f32 v162, v18, v162, v50
	v_bfe_u32 v9, v162, 16, 1
	v_add3_u32 v162, v162, v9, s81
	ds_write_b16_d16_hi v3, v162 offset:544
	v_mul_f32_e32 v163, v163, v8
	v_fma_f32 v163, v19, v163, v51
	v_bfe_u32 v10, v163, 16, 1
	v_add3_u32 v163, v163, v10, s81
	ds_write_b16_d16_hi v3, v163 offset:816
	v_mul_f32_e32 v164, v164, v8
	v_fma_f32 v164, v20, v164, v52
	v_bfe_u32 v9, v164, 16, 1
	v_add3_u32 v164, v164, v9, s81
	ds_write_b16_d16_hi v3, v164 offset:1088
	v_mul_f32_e32 v165, v165, v8
	v_fma_f32 v165, v21, v165, v53
	v_bfe_u32 v10, v165, 16, 1
	v_add3_u32 v165, v165, v10, s81
	ds_write_b16_d16_hi v3, v165 offset:1360
	v_mul_f32_e32 v166, v166, v8
	v_fma_f32 v166, v22, v166, v54
	v_bfe_u32 v9, v166, 16, 1
	v_add3_u32 v166, v166, v9, s81
	ds_write_b16_d16_hi v3, v166 offset:1632
	v_mul_f32_e32 v167, v167, v8
	v_fma_f32 v167, v23, v167, v55
	v_bfe_u32 v10, v167, 16, 1
	v_add3_u32 v167, v167, v10, s81
	ds_write_b16_d16_hi v3, v167 offset:1904
	v_mul_f32_e32 v168, v168, v8
	v_fma_f32 v168, v24, v168, v56
	v_bfe_u32 v9, v168, 16, 1
	v_add3_u32 v168, v168, v9, s81
	ds_write_b16_d16_hi v3, v168 offset:2176
	v_mul_f32_e32 v169, v169, v8
	v_fma_f32 v169, v25, v169, v57
	v_bfe_u32 v10, v169, 16, 1
	v_add3_u32 v169, v169, v10, s81
	ds_write_b16_d16_hi v3, v169 offset:2448
	v_mul_f32_e32 v170, v170, v8
	v_fma_f32 v170, v26, v170, v58
	v_bfe_u32 v9, v170, 16, 1
	v_add3_u32 v170, v170, v9, s81
	ds_write_b16_d16_hi v3, v170 offset:2720
	v_mul_f32_e32 v171, v171, v8
	v_fma_f32 v171, v27, v171, v59
	v_bfe_u32 v10, v171, 16, 1
	v_add3_u32 v171, v171, v10, s81
	ds_write_b16_d16_hi v3, v171 offset:2992
	v_mul_f32_e32 v172, v172, v8
	v_fma_f32 v172, v28, v172, v60
	v_bfe_u32 v9, v172, 16, 1
	v_add3_u32 v172, v172, v9, s81
	ds_write_b16_d16_hi v3, v172 offset:3264
	v_mul_f32_e32 v173, v173, v8
	v_fma_f32 v173, v29, v173, v61
	v_bfe_u32 v10, v173, 16, 1
	v_add3_u32 v173, v173, v10, s81
	ds_write_b16_d16_hi v3, v173 offset:3536
	v_mul_f32_e32 v174, v174, v8
	v_fma_f32 v174, v30, v174, v62
	v_bfe_u32 v9, v174, 16, 1
	v_add3_u32 v174, v174, v9, s81
	ds_write_b16_d16_hi v3, v174 offset:3808
	v_mul_f32_e32 v175, v175, v8
	v_fma_f32 v175, v31, v175, v63
	v_bfe_u32 v10, v175, 16, 1
	v_add3_u32 v175, v175, v10, s81
	ds_write_b16_d16_hi v3, v175 offset:4080
	v_mul_f32_e32 v176, v176, v8
	v_fma_f32 v176, v32, v176, v64
	v_bfe_u32 v9, v176, 16, 1
	v_add3_u32 v176, v176, v9, s81
	ds_write_b16_d16_hi v3, v176 offset:4352
	v_mul_f32_e32 v177, v177, v8
	v_fma_f32 v177, v33, v177, v65
	v_bfe_u32 v10, v177, 16, 1
	v_add3_u32 v177, v177, v10, s81
	ds_write_b16_d16_hi v3, v177 offset:4624
	v_mul_f32_e32 v178, v178, v8
	v_fma_f32 v178, v34, v178, v66
	v_bfe_u32 v9, v178, 16, 1
	v_add3_u32 v178, v178, v9, s81
	ds_write_b16_d16_hi v3, v178 offset:4896
	v_mul_f32_e32 v179, v179, v8
	v_fma_f32 v179, v35, v179, v67
	v_bfe_u32 v10, v179, 16, 1
	v_add3_u32 v179, v179, v10, s81
	ds_write_b16_d16_hi v3, v179 offset:5168
	v_mul_f32_e32 v180, v180, v8
	v_fma_f32 v180, v36, v180, v68
	v_bfe_u32 v9, v180, 16, 1
	v_add3_u32 v180, v180, v9, s81
	ds_write_b16_d16_hi v3, v180 offset:5440
	v_mul_f32_e32 v181, v181, v8
	v_fma_f32 v181, v37, v181, v69
	v_bfe_u32 v10, v181, 16, 1
	v_add3_u32 v181, v181, v10, s81
	ds_write_b16_d16_hi v3, v181 offset:5712
	v_mul_f32_e32 v182, v182, v8
	v_fma_f32 v182, v38, v182, v70
	v_bfe_u32 v9, v182, 16, 1
	v_add3_u32 v182, v182, v9, s81
	ds_write_b16_d16_hi v3, v182 offset:5984
	v_mul_f32_e32 v183, v183, v8
	v_fma_f32 v183, v39, v183, v71
	v_bfe_u32 v10, v183, 16, 1
	v_add3_u32 v183, v183, v10, s81
	ds_write_b16_d16_hi v3, v183 offset:6256
	v_mul_f32_e32 v184, v184, v8
	v_fma_f32 v184, v40, v184, v72
	v_bfe_u32 v9, v184, 16, 1
	v_add3_u32 v184, v184, v9, s81
	ds_write_b16_d16_hi v3, v184 offset:6528
	v_mul_f32_e32 v185, v185, v8
	v_fma_f32 v185, v41, v185, v73
	v_bfe_u32 v10, v185, 16, 1
	v_add3_u32 v185, v185, v10, s81
	ds_write_b16_d16_hi v3, v185 offset:6800
	v_mul_f32_e32 v186, v186, v8
	v_fma_f32 v186, v42, v186, v74
	v_bfe_u32 v9, v186, 16, 1
	v_add3_u32 v186, v186, v9, s81
	ds_write_b16_d16_hi v3, v186 offset:7072
	v_mul_f32_e32 v187, v187, v8
	v_fma_f32 v187, v43, v187, v75
	v_bfe_u32 v10, v187, 16, 1
	v_add3_u32 v187, v187, v10, s81
	ds_write_b16_d16_hi v3, v187 offset:7344
	v_mul_f32_e32 v188, v188, v8
	v_fma_f32 v188, v44, v188, v76
	v_bfe_u32 v9, v188, 16, 1
	v_add3_u32 v188, v188, v9, s81
	ds_write_b16_d16_hi v3, v188 offset:7616
	v_mul_f32_e32 v189, v189, v8
	v_fma_f32 v189, v45, v189, v77
	v_bfe_u32 v10, v189, 16, 1
	v_add3_u32 v189, v189, v10, s81
	ds_write_b16_d16_hi v3, v189 offset:7888
	v_mul_f32_e32 v190, v190, v8
	v_fma_f32 v190, v46, v190, v78
	v_bfe_u32 v9, v190, 16, 1
	v_add3_u32 v190, v190, v9, s81
	ds_write_b16_d16_hi v3, v190 offset:8160
	v_mul_f32_e32 v191, v191, v8
	v_fma_f32 v191, v47, v191, v79
	v_bfe_u32 v10, v191, 16, 1
	v_add3_u32 v191, v191, v10, s81
	ds_write_b16_d16_hi v3, v191 offset:8432
	s_waitcnt lgkmcnt(0)
	s_barrier
; #define LAS __attribute__((address_space(3)))
; __device__ __forceinline__ void gmlp_unit(LAS unsigned char* lds, bf16_t* Z, const float* ln_g, const float* ln_b, const float* b_s, const u32x2 (&uu)[8], const f32x4 (&wreg)[8], const u32x4 (&raw)[4], int cidx, int g, int tid) {
;     ...
;     const int wv = tid >> 6, lane = tid & 63, fr = lane & 15, fq = lane >> 4;
;     f32x4 acc[8];
; #pragma unroll
;     for (int ct = 0; ct < 8; ++ct) acc[ct] = (f32x4){0.f, 0.f, 0.f, 0.f};
; #pragma unroll
;     for (int ks = 0; ks < 4; ++ks) {
;         const bf16x8 bw = *(const LAS bf16x8*)(WS + (wv * 16 + fr) * LSTR + (ks * 32 + fq * 8) * 2);
; #pragma unroll
;         for (int ct = 0; ct < 8; ++ct) { const bf16x8 av = *(const LAS bf16x8*)(VT + (ct * 16 + fr) * LSTR + (ks * 32 + fq * 8) * 2);
;             acc[ct] = __builtin_amdgcn_mfma_f32_16x16x32_bf16(av, bw, acc[ct], 0, 0, 0); }
;     }
	ds_read_b128 v[200:203], v4
	ds_read_b128 v[204:207], v4 offset:4352
	ds_read_b128 v[208:211], v4 offset:8704
	ds_read_b128 v[212:215], v4 offset:13056
	ds_read_b128 v[224:227], v4 offset:17408
	ds_read_b128 v[228:231], v4 offset:21760
	ds_read_b128 v[232:235], v4 offset:26112
	ds_read_b128 v[236:239], v4 offset:30464
	s_waitcnt lgkmcnt(7)
	v_mfma_f32_16x16x32_bf16 v[160:163], v[200:203], v[80:83], 0
	ds_read_b128 v[200:203], v4 offset:64
	s_waitcnt lgkmcnt(7)
	v_mfma_f32_16x16x32_bf16 v[164:167], v[204:207], v[80:83], 0
	ds_read_b128 v[204:207], v4 offset:4416
	s_waitcnt lgkmcnt(7)
	v_mfma_f32_16x16x32_bf16 v[168:171], v[208:211], v[80:83], 0
	ds_read_b128 v[208:211], v4 offset:8768
	s_waitcnt lgkmcnt(7)
	v_mfma_f32_16x16x32_bf16 v[172:175], v[212:215], v[80:83], 0
	ds_read_b128 v[212:215], v4 offset:13120
	s_waitcnt lgkmcnt(7)
	v_mfma_f32_16x16x32_bf16 v[176:179], v[224:227], v[80:83], 0
	ds_read_b128 v[224:227], v4 offset:17472
	s_waitcnt lgkmcnt(7)
	v_mfma_f32_16x16x32_bf16 v[180:183], v[228:231], v[80:83], 0
	ds_read_b128 v[228:231], v4 offset:21824
	s_waitcnt lgkmcnt(7)
	v_mfma_f32_16x16x32_bf16 v[184:187], v[232:235], v[80:83], 0
	ds_read_b128 v[232:235], v4 offset:26176
	s_waitcnt lgkmcnt(7)
	v_mfma_f32_16x16x32_bf16 v[188:191], v[236:239], v[80:83], 0
	ds_read_b128 v[236:239], v4 offset:30528
	s_waitcnt lgkmcnt(7)
	v_mfma_f32_16x16x32_bf16 v[160:163], v[200:203], v[84:87], v[160:163]
	ds_read_b128 v[200:203], v4 offset:128
	s_waitcnt lgkmcnt(7)
	v_mfma_f32_16x16x32_bf16 v[164:167], v[204:207], v[84:87], v[164:167]
	ds_read_b128 v[204:207], v4 offset:4480
	s_waitcnt lgkmcnt(7)
	v_mfma_f32_16x16x32_bf16 v[168:171], v[208:211], v[84:87], v[168:171]
	ds_read_b128 v[208:211], v4 offset:8832
	s_waitcnt lgkmcnt(7)
	v_mfma_f32_16x16x32_bf16 v[172:175], v[212:215], v[84:87], v[172:175]
	ds_read_b128 v[212:215], v4 offset:13184
	s_waitcnt lgkmcnt(7)
	v_mfma_f32_16x16x32_bf16 v[176:179], v[224:227], v[84:87], v[176:179]
	ds_read_b128 v[224:227], v4 offset:17536
	s_waitcnt lgkmcnt(7)
	v_mfma_f32_16x16x32_bf16 v[180:183], v[228:231], v[84:87], v[180:183]
	ds_read_b128 v[228:231], v4 offset:21888
	s_waitcnt lgkmcnt(7)
	v_mfma_f32_16x16x32_bf16 v[184:187], v[232:235], v[84:87], v[184:187]
	ds_read_b128 v[232:235], v4 offset:26240
	s_waitcnt lgkmcnt(7)
	v_mfma_f32_16x16x32_bf16 v[188:191], v[236:239], v[84:87], v[188:191]
	ds_read_b128 v[236:239], v4 offset:30592
	s_waitcnt lgkmcnt(7)
	v_mfma_f32_16x16x32_bf16 v[160:163], v[200:203], v[88:91], v[160:163]
	ds_read_b128 v[200:203], v4 offset:192
	s_waitcnt lgkmcnt(7)
	v_mfma_f32_16x16x32_bf16 v[164:167], v[204:207], v[88:91], v[164:167]
	ds_read_b128 v[204:207], v4 offset:4544
	s_waitcnt lgkmcnt(7)
	v_mfma_f32_16x16x32_bf16 v[168:171], v[208:211], v[88:91], v[168:171]
	ds_read_b128 v[208:211], v4 offset:8896
	s_waitcnt lgkmcnt(7)
	v_mfma_f32_16x16x32_bf16 v[172:175], v[212:215], v[88:91], v[172:175]
	ds_read_b128 v[212:215], v4 offset:13248
	s_waitcnt lgkmcnt(7)
	v_mfma_f32_16x16x32_bf16 v[176:179], v[224:227], v[88:91], v[176:179]
	ds_read_b128 v[224:227], v4 offset:17600
	s_waitcnt lgkmcnt(7)
	v_mfma_f32_16x16x32_bf16 v[180:183], v[228:231], v[88:91], v[180:183]
	ds_read_b128 v[228:231], v4 offset:21952
	s_waitcnt lgkmcnt(7)
	v_mfma_f32_16x16x32_bf16 v[184:187], v[232:235], v[88:91], v[184:187]
	ds_read_b128 v[232:235], v4 offset:26304
	s_waitcnt lgkmcnt(7)
	v_mfma_f32_16x16x32_bf16 v[188:191], v[236:239], v[88:91], v[188:191]
	ds_read_b128 v[236:239], v4 offset:30656
	s_waitcnt lgkmcnt(7)
	v_mfma_f32_16x16x32_bf16 v[160:163], v[200:203], v[92:95], v[160:163]
	s_waitcnt lgkmcnt(6)
	v_mfma_f32_16x16x32_bf16 v[164:167], v[204:207], v[92:95], v[164:167]
	s_waitcnt lgkmcnt(5)
	v_mfma_f32_16x16x32_bf16 v[168:171], v[208:211], v[92:95], v[168:171]
	s_waitcnt lgkmcnt(4)
	v_mfma_f32_16x16x32_bf16 v[172:175], v[212:215], v[92:95], v[172:175]
	s_waitcnt lgkmcnt(3)
	v_mfma_f32_16x16x32_bf16 v[176:179], v[224:227], v[92:95], v[176:179]
	s_waitcnt lgkmcnt(2)
	v_mfma_f32_16x16x32_bf16 v[180:183], v[228:231], v[92:95], v[180:183]
	s_waitcnt lgkmcnt(1)
	v_mfma_f32_16x16x32_bf16 v[184:187], v[232:235], v[92:95], v[184:187]
	s_waitcnt lgkmcnt(0)
	v_mfma_f32_16x16x32_bf16 v[188:191], v[236:239], v[92:95], v[188:191]
	s_waitcnt vmcnt(20)
; __device__ __forceinline__ unsigned pk2(float lo, float hi) { return pg8::cvt_pk_bf16(lo, hi); }
; __device__ __forceinline__ void gmlp_unit(LAS unsigned char* lds, bf16_t* Z, const float* ln_g, const float* ln_b, const float* b_s, const u32x2 (&uu)[8], const f32x4 (&wreg)[8], const u32x4 (&raw)[4], int cidx, int g, int tid) {
;     ...
;         const int j = tid >> 2, cq = (tid & 3) * 32;
;         float x[32];
; #pragma unroll
;         for (int q = 0; q < 4; ++q)
; #pragma unroll
;             for (int e = 0; e < 4; ++e) { x[8 * q + 2 * e] = bf_lo(raw[q][e]); x[8 * q + 2 * e + 1] = bf_hi(raw[q][e]); }
;         float s = 0.f;
; #pragma unroll
;         for (int c = 0; c < 32; ++c) s += x[c];
;         s += __shfl_xor(s, 1); s += __shfl_xor(s, 2);
;         const float mean = s * (1.f / 128.f); float q2 = 0.f;
; #pragma unroll
;     ...
;     {
;         const int i = wv * 16 + fr; const float bs = b_s[g * 128 + i];
;         bf16_t* up = Z + (size_t)(row0 + i) * INW + g * 128 + 4 * fq;
; #pragma unroll
;         for (int ct = 0; ct < 8; ++ct) {
;             u32x2 w; w.x = pk2(bf_lo(uu[ct].x) * (acc[ct][0] + bs), bf_hi(uu[ct].x) * (acc[ct][1] + bs)); w.y = pk2(bf_lo(uu[ct].y) * (acc[ct][2] + bs), bf_hi(uu[ct].y) * (acc[ct][3] + bs));
;             *(u32x2*)(up + 16 * ct) = w; }
;     }
	v_add_f32_e32 v160, v160, v7
	v_add_f32_e32 v161, v161, v7
	v_add_f32_e32 v162, v162, v7
	v_add_f32_e32 v163, v163, v7
	v_lshlrev_b32_e32 v8, 16, v112
	v_and_b32_e32 v9, 0xffff0000, v112
	v_lshlrev_b32_e32 v10, 16, v113
	v_and_b32_e32 v11, 0xffff0000, v113
	v_mul_f32_e32 v160, v8, v160
	v_mul_f32_e32 v161, v9, v161
	v_mul_f32_e32 v162, v10, v162
	v_mul_f32_e32 v163, v11, v163
	v_cvt_pk_bf16_f32 v12, v160, v161
	v_cvt_pk_bf16_f32 v13, v162, v163
	global_store_dwordx2 v2, v[12:13], s[26:27]
	s_nop 0
	v_add_f32_e32 v164, v164, v7
	v_add_f32_e32 v165, v165, v7
	v_add_f32_e32 v166, v166, v7
	v_add_f32_e32 v167, v167, v7
	v_lshlrev_b32_e32 v8, 16, v114
	v_and_b32_e32 v9, 0xffff0000, v114
	v_lshlrev_b32_e32 v10, 16, v115
	v_and_b32_e32 v11, 0xffff0000, v115
	v_mul_f32_e32 v164, v8, v164
	v_mul_f32_e32 v165, v9, v165
	v_mul_f32_e32 v166, v10, v166
	v_mul_f32_e32 v167, v11, v167
	v_cvt_pk_bf16_f32 v12, v164, v165
	v_cvt_pk_bf16_f32 v13, v166, v167
	global_store_dwordx2 v2, v[12:13], s[26:27] offset:32
	s_nop 0
	v_add_f32_e32 v168, v168, v7
	v_add_f32_e32 v169, v169, v7
	v_add_f32_e32 v170, v170, v7
	v_add_f32_e32 v171, v171, v7
	v_lshlrev_b32_e32 v8, 16, v116
	v_and_b32_e32 v9, 0xffff0000, v116
	v_lshlrev_b32_e32 v10, 16, v117
	v_and_b32_e32 v11, 0xffff0000, v117
	v_mul_f32_e32 v168, v8, v168
	v_mul_f32_e32 v169, v9, v169
	v_mul_f32_e32 v170, v10, v170
	v_mul_f32_e32 v171, v11, v171
	v_cvt_pk_bf16_f32 v12, v168, v169
	v_cvt_pk_bf16_f32 v13, v170, v171
	global_store_dwordx2 v2, v[12:13], s[26:27] offset:64
	s_nop 0
	v_add_f32_e32 v172, v172, v7
	v_add_f32_e32 v173, v173, v7
	v_add_f32_e32 v174, v174, v7
	v_add_f32_e32 v175, v175, v7
	v_lshlrev_b32_e32 v8, 16, v118
	v_and_b32_e32 v9, 0xffff0000, v118
	v_lshlrev_b32_e32 v10, 16, v119
	v_and_b32_e32 v11, 0xffff0000, v119
	v_mul_f32_e32 v172, v8, v172
	v_mul_f32_e32 v173, v9, v173
	v_mul_f32_e32 v174, v10, v174
	v_mul_f32_e32 v175, v11, v175
	v_cvt_pk_bf16_f32 v12, v172, v173
	v_cvt_pk_bf16_f32 v13, v174, v175
	global_store_dwordx2 v2, v[12:13], s[26:27] offset:96
	s_nop 0
	v_add_f32_e32 v176, v176, v7
	v_add_f32_e32 v177, v177, v7
	v_add_f32_e32 v178, v178, v7
	v_add_f32_e32 v179, v179, v7
	v_lshlrev_b32_e32 v8, 16, v120
	v_and_b32_e32 v9, 0xffff0000, v120
	v_lshlrev_b32_e32 v10, 16, v121
	v_and_b32_e32 v11, 0xffff0000, v121
	v_mul_f32_e32 v176, v8, v176
	v_mul_f32_e32 v177, v9, v177
	v_mul_f32_e32 v178, v10, v178
	v_mul_f32_e32 v179, v11, v179
	v_cvt_pk_bf16_f32 v12, v176, v177
	v_cvt_pk_bf16_f32 v13, v178, v179
	global_store_dwordx2 v2, v[12:13], s[26:27] offset:128
	s_nop 0
	v_add_f32_e32 v180, v180, v7
	v_add_f32_e32 v181, v181, v7
	v_add_f32_e32 v182, v182, v7
	v_add_f32_e32 v183, v183, v7
	v_lshlrev_b32_e32 v8, 16, v122
	v_and_b32_e32 v9, 0xffff0000, v122
	v_lshlrev_b32_e32 v10, 16, v123
	v_and_b32_e32 v11, 0xffff0000, v123
	v_mul_f32_e32 v180, v8, v180
	v_mul_f32_e32 v181, v9, v181
	v_mul_f32_e32 v182, v10, v182
	v_mul_f32_e32 v183, v11, v183
	v_cvt_pk_bf16_f32 v12, v180, v181
	v_cvt_pk_bf16_f32 v13, v182, v183
	global_store_dwordx2 v2, v[12:13], s[26:27] offset:160
	s_nop 0
	v_add_f32_e32 v184, v184, v7
	v_add_f32_e32 v185, v185, v7
	v_add_f32_e32 v186, v186, v7
	v_add_f32_e32 v187, v187, v7
	v_lshlrev_b32_e32 v8, 16, v124
	v_and_b32_e32 v9, 0xffff0000, v124
	v_lshlrev_b32_e32 v10, 16, v125
	v_and_b32_e32 v11, 0xffff0000, v125
	v_mul_f32_e32 v184, v8, v184
	v_mul_f32_e32 v185, v9, v185
	v_mul_f32_e32 v186, v10, v186
	v_mul_f32_e32 v187, v11, v187
	v_cvt_pk_bf16_f32 v12, v184, v185
	v_cvt_pk_bf16_f32 v13, v186, v187
	global_store_dwordx2 v2, v[12:13], s[26:27] offset:192
	s_nop 0
	v_add_f32_e32 v188, v188, v7
	v_add_f32_e32 v189, v189, v7
	v_add_f32_e32 v190, v190, v7
	v_add_f32_e32 v191, v191, v7
	v_lshlrev_b32_e32 v8, 16, v126
	v_and_b32_e32 v9, 0xffff0000, v126
	v_lshlrev_b32_e32 v10, 16, v127
	v_and_b32_e32 v11, 0xffff0000, v127
	v_mul_f32_e32 v188, v8, v188
	v_mul_f32_e32 v189, v9, v189
	v_mul_f32_e32 v190, v10, v190
	v_mul_f32_e32 v191, v11, v191
	v_cvt_pk_bf16_f32 v12, v188, v189
	v_cvt_pk_bf16_f32 v13, v190, v191
	global_store_dwordx2 v2, v[12:13], s[26:27] offset:224
	s_waitcnt vmcnt(16)
	v_lshlrev_b32_e32 v160, 16, v128
	v_and_b32_e32 v161, 0xffff0000, v128
	v_lshlrev_b32_e32 v162, 16, v129
	v_and_b32_e32 v163, 0xffff0000, v129
	v_lshlrev_b32_e32 v164, 16, v130
	v_and_b32_e32 v165, 0xffff0000, v130
	v_lshlrev_b32_e32 v166, 16, v131
	v_and_b32_e32 v167, 0xffff0000, v131
	v_lshlrev_b32_e32 v168, 16, v132
	v_and_b32_e32 v169, 0xffff0000, v132
	v_lshlrev_b32_e32 v170, 16, v133
	v_and_b32_e32 v171, 0xffff0000, v133
	v_lshlrev_b32_e32 v172, 16, v134
	v_and_b32_e32 v173, 0xffff0000, v134
	v_lshlrev_b32_e32 v174, 16, v135
	v_and_b32_e32 v175, 0xffff0000, v135
	v_lshlrev_b32_e32 v176, 16, v136
	v_and_b32_e32 v177, 0xffff0000, v136
	v_lshlrev_b32_e32 v178, 16, v137
	v_and_b32_e32 v179, 0xffff0000, v137
	v_lshlrev_b32_e32 v180, 16, v138
	v_and_b32_e32 v181, 0xffff0000, v138
	v_lshlrev_b32_e32 v182, 16, v139
	v_and_b32_e32 v183, 0xffff0000, v139
	v_lshlrev_b32_e32 v184, 16, v140
	v_and_b32_e32 v185, 0xffff0000, v140
	v_lshlrev_b32_e32 v186, 16, v141
	v_and_b32_e32 v187, 0xffff0000, v141
	v_lshlrev_b32_e32 v188, 16, v142
	v_and_b32_e32 v189, 0xffff0000, v142
	v_lshlrev_b32_e32 v190, 16, v143
	v_and_b32_e32 v191, 0xffff0000, v143
	v_add_f32_e32 v8, v160, v164
	v_add_f32_e32 v9, v161, v165
	v_add_f32_e32 v10, v162, v166
	v_add_f32_e32 v11, v163, v167
	v_add_f32_e32 v8, v8, v168
	v_add_f32_e32 v9, v9, v169
	v_add_f32_e32 v10, v10, v170
	v_add_f32_e32 v11, v11, v171
	v_add_f32_e32 v8, v8, v172
	v_add_f32_e32 v9, v9, v173
	v_add_f32_e32 v10, v10, v174
	v_add_f32_e32 v11, v11, v175
	v_add_f32_e32 v8, v8, v176
; #define LAS __attribute__((address_space(3)))
; __device__ __forceinline__ unsigned f2bf(float f) { unsigned u = __builtin_bit_cast(unsigned, f); return (u + 0x7fffu + ((u >> 16) & 1u)) >> 16; }
; __device__ __forceinline__ void gmlp_unit(LAS unsigned char* lds, bf16_t* Z, const float* ln_g, const float* ln_b, const float* b_s, const u32x2 (&uu)[8], const f32x4 (&wreg)[8], const u32x4 (&raw)[4], int cidx, int g, int tid) {
;     ...
;         s += __shfl_xor(s, 1); s += __shfl_xor(s, 2);
;         const float mean = s * (1.f / 128.f); float q2 = 0.f;
; #pragma unroll
;         for (int c = 0; c < 32; ++c) { x[c] -= mean; q2 += x[c] * x[c]; }
;         q2 += __shfl_xor(q2, 1); q2 += __shfl_xor(q2, 2);
;         const float rstd = __builtin_amdgcn_rsqf(q2 * (1.f / 128.f) + EPS);
;         const float* gp = ln_g + g * 128 + cq; const float* bp = ln_b + g * 128 + cq;
; #pragma unroll
;         for (int c4 = 0; c4 < 8; ++c4) { const f32x4 gg = *(const f32x4*)(gp + 4 * c4), bb = *(const f32x4*)(bp + 4 * c4);
; #pragma unroll
;             for (int e = 0; e < 4; ++e) { const int c = 4 * c4 + e; const float y = x[c] * rstd * gg[e] + bb[e];
;                 *(LAS unsigned short*)(VT + (cq + c) * LSTR + j * 2) = (unsigned short)f2bf(y); } }
	v_add_f32_e32 v9, v9, v177
	v_add_f32_e32 v10, v10, v178
	v_add_f32_e32 v11, v11, v179
	v_add_f32_e32 v8, v8, v180
	v_add_f32_e32 v9, v9, v181
	v_add_f32_e32 v10, v10, v182
	v_add_f32_e32 v11, v11, v183
	v_add_f32_e32 v8, v8, v184
	v_add_f32_e32 v9, v9, v185
	v_add_f32_e32 v10, v10, v186
	v_add_f32_e32 v11, v11, v187
	v_add_f32_e32 v8, v8, v188
	v_add_f32_e32 v9, v9, v189
	v_add_f32_e32 v10, v10, v190
	v_add_f32_e32 v11, v11, v191
	v_add_f32_e32 v8, v8, v9
	v_add_f32_e32 v10, v10, v11
	v_add_f32_e32 v8, v8, v10
	s_nop 1
	v_add_f32_dpp v8, v8, v8 quad_perm:[1,0,3,2] row_mask:0xf bank_mask:0xf
	s_nop 1
	v_add_f32_dpp v8, v8, v8 quad_perm:[2,3,0,1] row_mask:0xf bank_mask:0xf
	v_mul_f32_e32 v8, 0xbc000000, v8
	v_add_f32_e32 v160, v160, v8
	v_add_f32_e32 v161, v161, v8
	v_add_f32_e32 v162, v162, v8
	v_add_f32_e32 v163, v163, v8
	v_add_f32_e32 v164, v164, v8
	v_add_f32_e32 v165, v165, v8
	v_add_f32_e32 v166, v166, v8
	v_add_f32_e32 v167, v167, v8
	v_add_f32_e32 v168, v168, v8
	v_add_f32_e32 v169, v169, v8
	v_add_f32_e32 v170, v170, v8
	v_add_f32_e32 v171, v171, v8
	v_add_f32_e32 v172, v172, v8
	v_add_f32_e32 v173, v173, v8
	v_add_f32_e32 v174, v174, v8
	v_add_f32_e32 v175, v175, v8
	v_add_f32_e32 v176, v176, v8
	v_add_f32_e32 v177, v177, v8
	v_add_f32_e32 v178, v178, v8
	v_add_f32_e32 v179, v179, v8
	v_add_f32_e32 v180, v180, v8
	v_add_f32_e32 v181, v181, v8
	v_add_f32_e32 v182, v182, v8
	v_add_f32_e32 v183, v183, v8
	v_add_f32_e32 v184, v184, v8
	v_add_f32_e32 v185, v185, v8
	v_add_f32_e32 v186, v186, v8
	v_add_f32_e32 v187, v187, v8
	v_add_f32_e32 v188, v188, v8
	v_add_f32_e32 v189, v189, v8
	v_add_f32_e32 v190, v190, v8
	v_add_f32_e32 v191, v191, v8
	v_mul_f32_e32 v8, v160, v160
	v_mul_f32_e32 v9, v161, v161
	v_mul_f32_e32 v10, v162, v162
	v_mul_f32_e32 v11, v163, v163
	v_fmac_f32_e32 v8, v164, v164
	v_fmac_f32_e32 v9, v165, v165
	v_fmac_f32_e32 v10, v166, v166
	v_fmac_f32_e32 v11, v167, v167
	v_fmac_f32_e32 v8, v168, v168
	v_fmac_f32_e32 v9, v169, v169
	v_fmac_f32_e32 v10, v170, v170
	v_fmac_f32_e32 v11, v171, v171
	v_fmac_f32_e32 v8, v172, v172
	v_fmac_f32_e32 v9, v173, v173
	v_fmac_f32_e32 v10, v174, v174
	v_fmac_f32_e32 v11, v175, v175
	v_fmac_f32_e32 v8, v176, v176
	v_fmac_f32_e32 v9, v177, v177
	v_fmac_f32_e32 v10, v178, v178
	v_fmac_f32_e32 v11, v179, v179
	v_fmac_f32_e32 v8, v180, v180
	v_fmac_f32_e32 v9, v181, v181
	v_fmac_f32_e32 v10, v182, v182
	v_fmac_f32_e32 v11, v183, v183
	v_fmac_f32_e32 v8, v184, v184
	v_fmac_f32_e32 v9, v185, v185
	v_fmac_f32_e32 v10, v186, v186
	v_fmac_f32_e32 v11, v187, v187
	v_fmac_f32_e32 v8, v188, v188
	v_fmac_f32_e32 v9, v189, v189
	v_fmac_f32_e32 v10, v190, v190
	v_fmac_f32_e32 v11, v191, v191
	v_add_f32_e32 v8, v8, v9
	v_add_f32_e32 v10, v10, v11
	v_add_f32_e32 v8, v8, v10
	s_nop 1
	v_add_f32_dpp v8, v8, v8 quad_perm:[1,0,3,2] row_mask:0xf bank_mask:0xf
	s_nop 1
	v_add_f32_dpp v8, v8, v8 quad_perm:[2,3,0,1] row_mask:0xf bank_mask:0xf
	v_fmamk_f32 v8, v8, 0x3c000000, v219
	v_rsq_f32_e32 v8, v8
	s_nop 0
	v_mul_f32_e32 v160, v160, v8
	v_fma_f32 v160, v16, v160, v48
	v_bfe_u32 v9, v160, 16, 1
	v_add3_u32 v160, v160, v9, s81
	ds_write_b16_d16_hi v3, v160 offset:34816
	v_mul_f32_e32 v161, v161, v8
	v_fma_f32 v161, v17, v161, v49
	v_bfe_u32 v10, v161, 16, 1
	v_add3_u32 v161, v161, v10, s81
	ds_write_b16_d16_hi v3, v161 offset:35088
	v_mul_f32_e32 v162, v162, v8
	v_fma_f32 v162, v18, v162, v50
	v_bfe_u32 v9, v162, 16, 1
	v_add3_u32 v162, v162, v9, s81
	ds_write_b16_d16_hi v3, v162 offset:35360
	v_mul_f32_e32 v163, v163, v8
	v_fma_f32 v163, v19, v163, v51
	v_bfe_u32 v10, v163, 16, 1
	v_add3_u32 v163, v163, v10, s81
	ds_write_b16_d16_hi v3, v163 offset:35632
	v_mul_f32_e32 v164, v164, v8
	v_fma_f32 v164, v20, v164, v52
	v_bfe_u32 v9, v164, 16, 1
	v_add3_u32 v164, v164, v9, s81
	ds_write_b16_d16_hi v3, v164 offset:35904
	v_mul_f32_e32 v165, v165, v8
	v_fma_f32 v165, v21, v165, v53
	v_bfe_u32 v10, v165, 16, 1
	v_add3_u32 v165, v165, v10, s81
	ds_write_b16_d16_hi v3, v165 offset:36176
	v_mul_f32_e32 v166, v166, v8
	v_fma_f32 v166, v22, v166, v54
	v_bfe_u32 v9, v166, 16, 1
	v_add3_u32 v166, v166, v9, s81
	ds_write_b16_d16_hi v3, v166 offset:36448
	v_mul_f32_e32 v167, v167, v8
	v_fma_f32 v167, v23, v167, v55
	v_bfe_u32 v10, v167, 16, 1
	v_add3_u32 v167, v167, v10, s81
	ds_write_b16_d16_hi v3, v167 offset:36720
	v_mul_f32_e32 v168, v168, v8
	v_fma_f32 v168, v24, v168, v56
	v_bfe_u32 v9, v168, 16, 1
	v_add3_u32 v168, v168, v9, s81
	ds_write_b16_d16_hi v3, v168 offset:36992
	v_mul_f32_e32 v169, v169, v8
	v_fma_f32 v169, v25, v169, v57
	v_bfe_u32 v10, v169, 16, 1
	v_add3_u32 v169, v169, v10, s81
	ds_write_b16_d16_hi v3, v169 offset:37264
	v_mul_f32_e32 v170, v170, v8
	v_fma_f32 v170, v26, v170, v58
	v_bfe_u32 v9, v170, 16, 1
	v_add3_u32 v170, v170, v9, s81
	ds_write_b16_d16_hi v3, v170 offset:37536
	v_mul_f32_e32 v171, v171, v8
	v_fma_f32 v171, v27, v171, v59
	v_bfe_u32 v10, v171, 16, 1
	v_add3_u32 v171, v171, v10, s81
	ds_write_b16_d16_hi v3, v171 offset:37808
	v_mul_f32_e32 v172, v172, v8
	v_fma_f32 v172, v28, v172, v60
	v_bfe_u32 v9, v172, 16, 1
	v_add3_u32 v172, v172, v9, s81
	ds_write_b16_d16_hi v3, v172 offset:38080
	v_mul_f32_e32 v173, v173, v8
	v_fma_f32 v173, v29, v173, v61
	v_bfe_u32 v10, v173, 16, 1
	v_add3_u32 v173, v173, v10, s81
	ds_write_b16_d16_hi v3, v173 offset:38352
	v_mul_f32_e32 v174, v174, v8
	v_fma_f32 v174, v30, v174, v62
	v_bfe_u32 v9, v174, 16, 1
	v_add3_u32 v174, v174, v9, s81
	ds_write_b16_d16_hi v3, v174 offset:38624
	v_mul_f32_e32 v175, v175, v8
	v_fma_f32 v175, v31, v175, v63
	v_bfe_u32 v10, v175, 16, 1
	v_add3_u32 v175, v175, v10, s81
	ds_write_b16_d16_hi v3, v175 offset:38896
; #define LAS __attribute__((address_space(3)))
; __device__ __forceinline__ unsigned f2bf(float f) { unsigned u = __builtin_bit_cast(unsigned, f); return (u + 0x7fffu + ((u >> 16) & 1u)) >> 16; }
; __device__ __forceinline__ void gmlp_unit(LAS unsigned char* lds, bf16_t* Z, const float* ln_g, const float* ln_b, const float* b_s, const u32x2 (&uu)[8], const f32x4 (&wreg)[8], const u32x4 (&raw)[4], int cidx, int g, int tid) {
;     ...
;             for (int e = 0; e < 4; ++e) { const int c = 4 * c4 + e; const float y = x[c] * rstd * gg[e] + bb[e];
;                 *(LAS unsigned short*)(VT + (cq + c) * LSTR + j * 2) = (unsigned short)f2bf(y); } }
;     ...
;     for (int ks = 0; ks < 4; ++ks) {
;         const bf16x8 bw = *(const LAS bf16x8*)(WS + (wv * 16 + fr) * LSTR + (ks * 32 + fq * 8) * 2);
; #pragma unroll
;         for (int ct = 0; ct < 8; ++ct) { const bf16x8 av = *(const LAS bf16x8*)(VT + (ct * 16 + fr) * LSTR + (ks * 32 + fq * 8) * 2);
;             acc[ct] = __builtin_amdgcn_mfma_f32_16x16x32_bf16(av, bw, acc[ct], 0, 0, 0); }
	v_mul_f32_e32 v176, v176, v8
	v_fma_f32 v176, v32, v176, v64
	v_bfe_u32 v9, v176, 16, 1
	v_add3_u32 v176, v176, v9, s81
	ds_write_b16_d16_hi v3, v176 offset:39168
	v_mul_f32_e32 v177, v177, v8
	v_fma_f32 v177, v33, v177, v65
	v_bfe_u32 v10, v177, 16, 1
	v_add3_u32 v177, v177, v10, s81
	ds_write_b16_d16_hi v3, v177 offset:39440
	v_mul_f32_e32 v178, v178, v8
	v_fma_f32 v178, v34, v178, v66
	v_bfe_u32 v9, v178, 16, 1
	v_add3_u32 v178, v178, v9, s81
	ds_write_b16_d16_hi v3, v178 offset:39712
	v_mul_f32_e32 v179, v179, v8
	v_fma_f32 v179, v35, v179, v67
	v_bfe_u32 v10, v179, 16, 1
	v_add3_u32 v179, v179, v10, s81
	ds_write_b16_d16_hi v3, v179 offset:39984
	v_mul_f32_e32 v180, v180, v8
	v_fma_f32 v180, v36, v180, v68
	v_bfe_u32 v9, v180, 16, 1
	v_add3_u32 v180, v180, v9, s81
	ds_write_b16_d16_hi v3, v180 offset:40256
	v_mul_f32_e32 v181, v181, v8
	v_fma_f32 v181, v37, v181, v69
	v_bfe_u32 v10, v181, 16, 1
	v_add3_u32 v181, v181, v10, s81
	ds_write_b16_d16_hi v3, v181 offset:40528
	v_mul_f32_e32 v182, v182, v8
	v_fma_f32 v182, v38, v182, v70
	v_bfe_u32 v9, v182, 16, 1
	v_add3_u32 v182, v182, v9, s81
	ds_write_b16_d16_hi v3, v182 offset:40800
	v_mul_f32_e32 v183, v183, v8
	v_fma_f32 v183, v39, v183, v71
	v_bfe_u32 v10, v183, 16, 1
	v_add3_u32 v183, v183, v10, s81
	ds_write_b16_d16_hi v3, v183 offset:41072
	v_mul_f32_e32 v184, v184, v8
	v_fma_f32 v184, v40, v184, v72
	v_bfe_u32 v9, v184, 16, 1
	v_add3_u32 v184, v184, v9, s81
	ds_write_b16_d16_hi v3, v184 offset:41344
	v_mul_f32_e32 v185, v185, v8
	v_fma_f32 v185, v41, v185, v73
	v_bfe_u32 v10, v185, 16, 1
	v_add3_u32 v185, v185, v10, s81
	ds_write_b16_d16_hi v3, v185 offset:41616
	v_mul_f32_e32 v186, v186, v8
	v_fma_f32 v186, v42, v186, v74
	v_bfe_u32 v9, v186, 16, 1
	v_add3_u32 v186, v186, v9, s81
	ds_write_b16_d16_hi v3, v186 offset:41888
	v_mul_f32_e32 v187, v187, v8
	v_fma_f32 v187, v43, v187, v75
	v_bfe_u32 v10, v187, 16, 1
	v_add3_u32 v187, v187, v10, s81
	ds_write_b16_d16_hi v3, v187 offset:42160
	v_mul_f32_e32 v188, v188, v8
	v_fma_f32 v188, v44, v188, v76
	v_bfe_u32 v9, v188, 16, 1
	v_add3_u32 v188, v188, v9, s81
	ds_write_b16_d16_hi v3, v188 offset:42432
	v_mul_f32_e32 v189, v189, v8
	v_fma_f32 v189, v45, v189, v77
	v_bfe_u32 v10, v189, 16, 1
	v_add3_u32 v189, v189, v10, s81
	ds_write_b16_d16_hi v3, v189 offset:42704
	v_mul_f32_e32 v190, v190, v8
	v_fma_f32 v190, v46, v190, v78
	v_bfe_u32 v9, v190, 16, 1
	v_add3_u32 v190, v190, v9, s81
	ds_write_b16_d16_hi v3, v190 offset:42976
	v_mul_f32_e32 v191, v191, v8
	v_fma_f32 v191, v47, v191, v79
	v_bfe_u32 v10, v191, 16, 1
	v_add3_u32 v191, v191, v10, s81
	ds_write_b16_d16_hi v3, v191 offset:43248
	s_waitcnt lgkmcnt(0)
	s_barrier
	ds_read_b128 v[200:203], v4 offset:34816
	ds_read_b128 v[204:207], v4 offset:39168
	ds_read_b128 v[208:211], v4 offset:43520
	ds_read_b128 v[212:215], v4 offset:47872
	ds_read_b128 v[224:227], v4 offset:52224
	ds_read_b128 v[228:231], v4 offset:56576
	ds_read_b128 v[232:235], v4 offset:60928
	ds_read_b128 v[236:239], v4 offset:65280
	s_waitcnt lgkmcnt(7)
	v_mfma_f32_16x16x32_bf16 v[160:163], v[200:203], v[80:83], 0
	ds_read_b128 v[200:203], v4 offset:34880
	s_waitcnt lgkmcnt(7)
	v_mfma_f32_16x16x32_bf16 v[164:167], v[204:207], v[80:83], 0
	ds_read_b128 v[204:207], v4 offset:39232
	s_waitcnt lgkmcnt(7)
	v_mfma_f32_16x16x32_bf16 v[168:171], v[208:211], v[80:83], 0
	ds_read_b128 v[208:211], v4 offset:43584
	s_waitcnt lgkmcnt(7)
	v_mfma_f32_16x16x32_bf16 v[172:175], v[212:215], v[80:83], 0
	ds_read_b128 v[212:215], v4 offset:47936
	s_waitcnt lgkmcnt(7)
	v_mfma_f32_16x16x32_bf16 v[176:179], v[224:227], v[80:83], 0
	ds_read_b128 v[224:227], v4 offset:52288
	s_waitcnt lgkmcnt(7)
	v_mfma_f32_16x16x32_bf16 v[180:183], v[228:231], v[80:83], 0
	ds_read_b128 v[228:231], v4 offset:56640
	s_waitcnt lgkmcnt(7)
	v_mfma_f32_16x16x32_bf16 v[184:187], v[232:235], v[80:83], 0
	ds_read_b128 v[232:235], v4 offset:60992
	s_waitcnt lgkmcnt(7)
	v_mfma_f32_16x16x32_bf16 v[188:191], v[236:239], v[80:83], 0
	ds_read_b128 v[236:239], v4 offset:65344
	s_waitcnt lgkmcnt(7)
	v_mfma_f32_16x16x32_bf16 v[160:163], v[200:203], v[84:87], v[160:163]
	ds_read_b128 v[200:203], v4 offset:34944
	s_waitcnt lgkmcnt(7)
	v_mfma_f32_16x16x32_bf16 v[164:167], v[204:207], v[84:87], v[164:167]
	ds_read_b128 v[204:207], v4 offset:39296
	s_waitcnt lgkmcnt(7)
	v_mfma_f32_16x16x32_bf16 v[168:171], v[208:211], v[84:87], v[168:171]
	ds_read_b128 v[208:211], v4 offset:43648
	s_waitcnt lgkmcnt(7)
	v_mfma_f32_16x16x32_bf16 v[172:175], v[212:215], v[84:87], v[172:175]
	ds_read_b128 v[212:215], v4 offset:48000
	s_waitcnt lgkmcnt(7)
	v_mfma_f32_16x16x32_bf16 v[176:179], v[224:227], v[84:87], v[176:179]
	ds_read_b128 v[224:227], v4 offset:52352
	s_waitcnt lgkmcnt(7)
	v_mfma_f32_16x16x32_bf16 v[180:183], v[228:231], v[84:87], v[180:183]
	ds_read_b128 v[228:231], v4 offset:56704
	s_waitcnt lgkmcnt(7)
	v_mfma_f32_16x16x32_bf16 v[184:187], v[232:235], v[84:87], v[184:187]
	ds_read_b128 v[232:235], v4 offset:61056
	s_waitcnt lgkmcnt(7)
	v_mfma_f32_16x16x32_bf16 v[188:191], v[236:239], v[84:87], v[188:191]
	ds_read_b128 v[236:239], v4 offset:65408
	s_waitcnt lgkmcnt(7)
	v_mfma_f32_16x16x32_bf16 v[160:163], v[200:203], v[88:91], v[160:163]
	ds_read_b128 v[200:203], v4 offset:35008
	s_waitcnt lgkmcnt(7)
	v_mfma_f32_16x16x32_bf16 v[164:167], v[204:207], v[88:91], v[164:167]
	ds_read_b128 v[204:207], v4 offset:39360
	s_waitcnt lgkmcnt(7)
	v_mfma_f32_16x16x32_bf16 v[168:171], v[208:211], v[88:91], v[168:171]
	ds_read_b128 v[208:211], v4 offset:43712
	s_waitcnt lgkmcnt(7)
; #define LAS __attribute__((address_space(3)))
; __device__ __forceinline__ unsigned pk2(float lo, float hi) { return pg8::cvt_pk_bf16(lo, hi); }
; __device__ __forceinline__ void gmlp_unit(LAS unsigned char* lds, bf16_t* Z, const float* ln_g, const float* ln_b, const float* b_s, const u32x2 (&uu)[8], const f32x4 (&wreg)[8], const u32x4 (&raw)[4], int cidx, int g, int tid) {
;     ...
;     for (int ks = 0; ks < 4; ++ks) {
;         const bf16x8 bw = *(const LAS bf16x8*)(WS + (wv * 16 + fr) * LSTR + (ks * 32 + fq * 8) * 2);
; #pragma unroll
;         for (int ct = 0; ct < 8; ++ct) { const bf16x8 av = *(const LAS bf16x8*)(VT + (ct * 16 + fr) * LSTR + (ks * 32 + fq * 8) * 2);
;             acc[ct] = __builtin_amdgcn_mfma_f32_16x16x32_bf16(av, bw, acc[ct], 0, 0, 0); }
;     }
;     {
;         const int i = wv * 16 + fr; const float bs = b_s[g * 128 + i];
;         bf16_t* up = Z + (size_t)(row0 + i) * INW + g * 128 + 4 * fq;
; #pragma unroll
;         for (int ct = 0; ct < 8; ++ct) {
;             u32x2 w; w.x = pk2(bf_lo(uu[ct].x) * (acc[ct][0] + bs), bf_hi(uu[ct].x) * (acc[ct][1] + bs)); w.y = pk2(bf_lo(uu[ct].y) * (acc[ct][2] + bs), bf_hi(uu[ct].y) * (acc[ct][3] + bs));
;             *(u32x2*)(up + 16 * ct) = w; }
;     }
	v_mfma_f32_16x16x32_bf16 v[172:175], v[212:215], v[88:91], v[172:175]
	ds_read_b128 v[212:215], v4 offset:48064
	s_waitcnt lgkmcnt(7)
	v_mfma_f32_16x16x32_bf16 v[176:179], v[224:227], v[88:91], v[176:179]
	ds_read_b128 v[224:227], v4 offset:52416
	s_waitcnt lgkmcnt(7)
	v_mfma_f32_16x16x32_bf16 v[180:183], v[228:231], v[88:91], v[180:183]
	ds_read_b128 v[228:231], v4 offset:56768
	s_waitcnt lgkmcnt(7)
	v_mfma_f32_16x16x32_bf16 v[184:187], v[232:235], v[88:91], v[184:187]
	ds_read_b128 v[232:235], v4 offset:61120
	s_waitcnt lgkmcnt(7)
	v_mfma_f32_16x16x32_bf16 v[188:191], v[236:239], v[88:91], v[188:191]
	ds_read_b128 v[236:239], v4 offset:65472
	s_waitcnt lgkmcnt(7)
	v_mfma_f32_16x16x32_bf16 v[160:163], v[200:203], v[92:95], v[160:163]
	s_waitcnt lgkmcnt(6)
	v_mfma_f32_16x16x32_bf16 v[164:167], v[204:207], v[92:95], v[164:167]
	s_waitcnt lgkmcnt(5)
	v_mfma_f32_16x16x32_bf16 v[168:171], v[208:211], v[92:95], v[168:171]
	s_waitcnt lgkmcnt(4)
	v_mfma_f32_16x16x32_bf16 v[172:175], v[212:215], v[92:95], v[172:175]
	s_waitcnt lgkmcnt(3)
	v_mfma_f32_16x16x32_bf16 v[176:179], v[224:227], v[92:95], v[176:179]
	s_waitcnt lgkmcnt(2)
	v_mfma_f32_16x16x32_bf16 v[180:183], v[228:231], v[92:95], v[180:183]
	s_waitcnt lgkmcnt(1)
	v_mfma_f32_16x16x32_bf16 v[184:187], v[232:235], v[92:95], v[184:187]
	s_waitcnt lgkmcnt(0)
	v_mfma_f32_16x16x32_bf16 v[188:191], v[236:239], v[92:95], v[188:191]
	s_waitcnt vmcnt(8)
	v_add_f32_e32 v160, v160, v7
	v_add_f32_e32 v161, v161, v7
	v_add_f32_e32 v162, v162, v7
	v_add_f32_e32 v163, v163, v7
	v_lshlrev_b32_e32 v8, 16, v144
	v_and_b32_e32 v9, 0xffff0000, v144
	v_lshlrev_b32_e32 v10, 16, v145
	v_and_b32_e32 v11, 0xffff0000, v145
	v_mul_f32_e32 v160, v8, v160
	v_mul_f32_e32 v161, v9, v161
	v_mul_f32_e32 v162, v10, v162
	v_mul_f32_e32 v163, v11, v163
	v_cvt_pk_bf16_f32 v12, v160, v161
	v_cvt_pk_bf16_f32 v13, v162, v163
	global_store_dwordx2 v2, v[12:13], s[28:29]
	s_nop 0
	v_add_f32_e32 v164, v164, v7
	v_add_f32_e32 v165, v165, v7
	v_add_f32_e32 v166, v166, v7
	v_add_f32_e32 v167, v167, v7
	v_lshlrev_b32_e32 v8, 16, v146
	v_and_b32_e32 v9, 0xffff0000, v146
	v_lshlrev_b32_e32 v10, 16, v147
	v_and_b32_e32 v11, 0xffff0000, v147
	v_mul_f32_e32 v164, v8, v164
	v_mul_f32_e32 v165, v9, v165
	v_mul_f32_e32 v166, v10, v166
	v_mul_f32_e32 v167, v11, v167
	v_cvt_pk_bf16_f32 v12, v164, v165
	v_cvt_pk_bf16_f32 v13, v166, v167
	global_store_dwordx2 v2, v[12:13], s[28:29] offset:32
	s_nop 0
	v_add_f32_e32 v168, v168, v7
	v_add_f32_e32 v169, v169, v7
	v_add_f32_e32 v170, v170, v7
	v_add_f32_e32 v171, v171, v7
	v_lshlrev_b32_e32 v8, 16, v148
	v_and_b32_e32 v9, 0xffff0000, v148
	v_lshlrev_b32_e32 v10, 16, v149
	v_and_b32_e32 v11, 0xffff0000, v149
	v_mul_f32_e32 v168, v8, v168
	v_mul_f32_e32 v169, v9, v169
	v_mul_f32_e32 v170, v10, v170
	v_mul_f32_e32 v171, v11, v171
	v_cvt_pk_bf16_f32 v12, v168, v169
	v_cvt_pk_bf16_f32 v13, v170, v171
	global_store_dwordx2 v2, v[12:13], s[28:29] offset:64
	s_nop 0
	v_add_f32_e32 v172, v172, v7
	v_add_f32_e32 v173, v173, v7
	v_add_f32_e32 v174, v174, v7
	v_add_f32_e32 v175, v175, v7
	v_lshlrev_b32_e32 v8, 16, v150
	v_and_b32_e32 v9, 0xffff0000, v150
	v_lshlrev_b32_e32 v10, 16, v151
	v_and_b32_e32 v11, 0xffff0000, v151
	v_mul_f32_e32 v172, v8, v172
	v_mul_f32_e32 v173, v9, v173
	v_mul_f32_e32 v174, v10, v174
	v_mul_f32_e32 v175, v11, v175
	v_cvt_pk_bf16_f32 v12, v172, v173
	v_cvt_pk_bf16_f32 v13, v174, v175
	global_store_dwordx2 v2, v[12:13], s[28:29] offset:96
	s_nop 0
	v_add_f32_e32 v176, v176, v7
	v_add_f32_e32 v177, v177, v7
	v_add_f32_e32 v178, v178, v7
	v_add_f32_e32 v179, v179, v7
	v_lshlrev_b32_e32 v8, 16, v152
	v_and_b32_e32 v9, 0xffff0000, v152
	v_lshlrev_b32_e32 v10, 16, v153
	v_and_b32_e32 v11, 0xffff0000, v153
	v_mul_f32_e32 v176, v8, v176
	v_mul_f32_e32 v177, v9, v177
	v_mul_f32_e32 v178, v10, v178
	v_mul_f32_e32 v179, v11, v179
	v_cvt_pk_bf16_f32 v12, v176, v177
	v_cvt_pk_bf16_f32 v13, v178, v179
	global_store_dwordx2 v2, v[12:13], s[28:29] offset:128
	s_nop 0
	v_add_f32_e32 v180, v180, v7
	v_add_f32_e32 v181, v181, v7
	v_add_f32_e32 v182, v182, v7
	v_add_f32_e32 v183, v183, v7
	v_lshlrev_b32_e32 v8, 16, v154
	v_and_b32_e32 v9, 0xffff0000, v154
	v_lshlrev_b32_e32 v10, 16, v155
	v_and_b32_e32 v11, 0xffff0000, v155
	v_mul_f32_e32 v180, v8, v180
	v_mul_f32_e32 v181, v9, v181
	v_mul_f32_e32 v182, v10, v182
	v_mul_f32_e32 v183, v11, v183
	v_cvt_pk_bf16_f32 v12, v180, v181
	v_cvt_pk_bf16_f32 v13, v182, v183
	global_store_dwordx2 v2, v[12:13], s[28:29] offset:160
	s_nop 0
	v_add_f32_e32 v184, v184, v7
	v_add_f32_e32 v185, v185, v7
	v_add_f32_e32 v186, v186, v7
	v_add_f32_e32 v187, v187, v7
	v_lshlrev_b32_e32 v8, 16, v156
	v_and_b32_e32 v9, 0xffff0000, v156
	v_lshlrev_b32_e32 v10, 16, v157
	v_and_b32_e32 v11, 0xffff0000, v157
	v_mul_f32_e32 v184, v8, v184
	v_mul_f32_e32 v185, v9, v185
	v_mul_f32_e32 v186, v10, v186
	v_mul_f32_e32 v187, v11, v187
	v_cvt_pk_bf16_f32 v12, v184, v185
	v_cvt_pk_bf16_f32 v13, v186, v187
	global_store_dwordx2 v2, v[12:13], s[28:29] offset:192
	s_nop 0
	v_add_f32_e32 v188, v188, v7
	v_add_f32_e32 v189, v189, v7
	v_add_f32_e32 v190, v190, v7
	v_add_f32_e32 v191, v191, v7
	v_lshlrev_b32_e32 v8, 16, v158
	v_and_b32_e32 v9, 0xffff0000, v158
	v_lshlrev_b32_e32 v10, 16, v159
	v_and_b32_e32 v11, 0xffff0000, v159
	v_mul_f32_e32 v188, v8, v188
	v_mul_f32_e32 v189, v9, v189
	v_mul_f32_e32 v190, v10, v190
	v_mul_f32_e32 v191, v11, v191
	v_cvt_pk_bf16_f32 v12, v188, v189
	v_cvt_pk_bf16_f32 v13, v190, v191
	global_store_dwordx2 v2, v[12:13], s[28:29] offset:224
	s_barrier
